# GEMM tile loops: drop the ALIGN barrier pair at the tile end so the half-interval stagger persists through the epilogue
# speedup vs baseline: 1.0149x; 1.0036x over previous
; #define PG8_STAGE(bufoff, gbase, voff) do { _Pragma("unroll") for (int _i = 0; _i < 2; ++_i) \
;         __builtin_amdgcn_global_load_lds((const unsigned*)((const char*)(gbase) + (voff)[_i]), (LAS unsigned*)(lds + (bufoff) + ldsw + _i * 8192), 16, 0, 0); } while (0)
; #define PG8_LDA(dst, b, h) do { _Pragma("unroll") for (int m = 0; m < 4; ++m) _Pragma("unroll") for (int k = 0; k < 2; ++k) dst[m][k] = *(const LAS bf16x8*)(lds + PG8_SA(b, h) + aoff + m * 2048 + k * 1024); } while (0)
; #define PG8_LDB(dst, b, h) do { _Pragma("unroll") for (int n = 0; n < 2; ++n) _Pragma("unroll") for (int k = 0; k < 2; ++k) dst[n][k] = *(const LAS bf16x8*)(lds + PG8_SB(b, h) + boff + n * 2048 + k * 1024); } while (0)
; #define PG8_MMA(ai, bj, At, Bt) do { __builtin_amdgcn_s_setprio(1); _Pragma("unroll") for (int m = 0; m < 4; ++m) _Pragma("unroll") for (int n = 0; n < 2; ++n) _Pragma("unroll") for (int k = 0; k < 2; ++k) \
;         acc[ai][bj][m][n] = __builtin_amdgcn_mfma_f32_16x16x32_bf16(Bt[n][k], At[m][k], acc[ai][bj][m][n], 0, 0, 0); __builtin_amdgcn_s_setprio(0); } while (0)
; #define PG8_WAIT_V(n) asm volatile("s_waitcnt vmcnt(" #n ")" ::: "memory")
; #define PG8_WAIT_L(n) asm volatile("s_waitcnt lgkmcnt(" #n ")" ::: "memory")
; #define PG8_BAR __builtin_amdgcn_s_barrier()
; #define PG8_SCHED __builtin_amdgcn_sched_barrier(0)
; template <class Epi, bool ALIGN_EPI>
; __device__ __forceinline__ void gemm_phase(LAS unsigned char* lds, const Gemm g, const StaticOrder& S, const Epi& E) {
;     ...
;         for (int t = 0; t < nt; t += 2) {
;             const bool last = (t == nt - 2);
;             const char* a1 = cA + (size_t)(t + 1) * kstep;
;             const char* a2 = last ? nA : cA + (size_t)(t + 2) * kstep; const char* b2 = last ? nB : cB + (size_t)(t + 2) * kstep;
;             const char* a3 = a2 + kstep; const char* b3 = b2 + kstep;
;             PG8_LDB(B0, 0, 0); PG8_LDB(B1, 0, 1); PG8_SCHED; PG8_LDA(At, 0, 0); PG8_STAGE(PG8_SA(1, 1), a1 + hstepA, voffA);
;             PG8_WAIT_V(8); PG8_WAIT_L(0); PG8_BAR; PG8_MMA(0, 0, At, B0); PG8_MMA(0, 1, At, B1); PG8_BAR; PG8_SCHED;
;             PG8_LDA(At, 0, 1); PG8_STAGE(PG8_SB(0, 0), b2, voffB); PG8_STAGE(PG8_SB(0, 1), b2 + hstepB, voffB); PG8_STAGE(PG8_SA(0, 0), a2, voffA);
.LBB0_102:
	s_add_u32 s6, s2, 0xfffc0080
	s_addc_u32 s7, s3, -1
	s_add_i32 s49, 0, 0x10000
	s_cmp_eq_u32 s37, 12
	s_cselect_b32 s9, s4, s7
	s_cselect_b32 s8, s10, s6
	v_add_u32_e32 v152, s49, v148
	s_cselect_b32 s7, s11, s36
	s_cselect_b32 s6, s13, s27
	s_add_i32 s52, 0, 0x14000
	ds_read_b128 v[140:143], v152
	ds_read_b128 v[144:147], v152 offset:1024
	ds_read_b128 v[156:159], v152 offset:2048
	ds_read_b128 v[160:163], v152 offset:3072
	v_add_u32_e32 v152, s52, v148
	ds_read_b128 v[170:173], v152
	ds_read_b128 v[180:183], v152 offset:1024
	ds_read_b128 v[184:187], v152 offset:2048
	ds_read_b128 v[188:191], v152 offset:3072
	v_lshl_add_u64 v[152:153], s[2:3], 0, v[136:137]
	s_add_i32 m0, s41, 0xc000
	ds_read_b128 v[192:195], v150
	ds_read_b128 v[196:199], v150 offset:1024
	ds_read_b128 v[200:203], v150 offset:2048
	ds_read_b128 v[204:207], v150 offset:3072
	ds_read_b128 v[208:211], v150 offset:4096
	ds_read_b128 v[212:215], v150 offset:5120
	ds_read_b128 v[216:219], v150 offset:6144
	ds_read_b128 v[220:223], v150 offset:7168
	global_load_lds_dwordx4 v[152:153], off
	v_lshl_add_u64 v[152:153], s[2:3], 0, v[138:139]
	s_add_i32 m0, s41, 0xe000
	s_nop 0
	global_load_lds_dwordx4 v[152:153], off
	s_waitcnt vmcnt(8)
	s_waitcnt lgkmcnt(0)
	s_barrier
	s_waitcnt lgkmcnt(0)
	v_mfma_f32_16x16x32_bf16 v[122:125], v[140:143], v[192:195], v[122:125]
	v_mfma_f32_16x16x32_bf16 v[126:129], v[156:159], v[192:195], v[126:129]
	v_mfma_f32_16x16x32_bf16 v[110:113], v[140:143], v[200:203], v[110:113]
	v_mfma_f32_16x16x32_bf16 v[106:109], v[156:159], v[200:203], v[106:109]
	v_mfma_f32_16x16x32_bf16 v[94:97], v[140:143], v[208:211], v[94:97]
	v_mfma_f32_16x16x32_bf16 v[90:93], v[156:159], v[208:211], v[90:93]
	v_mfma_f32_16x16x32_bf16 v[78:81], v[140:143], v[216:219], v[78:81]
	v_mfma_f32_16x16x32_bf16 v[74:77], v[156:159], v[216:219], v[74:77]
	v_mfma_f32_16x16x32_bf16 v[122:125], v[144:147], v[196:199], v[122:125]
	v_mfma_f32_16x16x32_bf16 v[126:129], v[160:163], v[196:199], v[126:129]
	v_mfma_f32_16x16x32_bf16 v[110:113], v[144:147], v[204:207], v[110:113]
	v_mfma_f32_16x16x32_bf16 v[106:109], v[160:163], v[204:207], v[106:109]
	v_mfma_f32_16x16x32_bf16 v[94:97], v[144:147], v[212:215], v[94:97]
	v_mfma_f32_16x16x32_bf16 v[90:93], v[160:163], v[212:215], v[90:93]
	v_mfma_f32_16x16x32_bf16 v[78:81], v[144:147], v[220:223], v[78:81]
	v_mfma_f32_16x16x32_bf16 v[74:77], v[160:163], v[220:223], v[74:77]
	v_mfma_f32_16x16x32_bf16 v[118:121], v[170:173], v[192:195], v[118:121]
	v_mfma_f32_16x16x32_bf16 v[114:117], v[184:187], v[192:195], v[114:117]
	v_mfma_f32_16x16x32_bf16 v[102:105], v[170:173], v[200:203], v[102:105]
	v_mfma_f32_16x16x32_bf16 v[98:101], v[184:187], v[200:203], v[98:101]
	v_mfma_f32_16x16x32_bf16 v[86:89], v[170:173], v[208:211], v[86:89]
	v_mfma_f32_16x16x32_bf16 v[82:85], v[184:187], v[208:211], v[82:85]
	v_mfma_f32_16x16x32_bf16 v[70:73], v[170:173], v[216:219], v[70:73]
	v_mfma_f32_16x16x32_bf16 v[66:69], v[184:187], v[216:219], v[66:69]
	v_mfma_f32_16x16x32_bf16 v[118:121], v[180:183], v[196:199], v[118:121]
	v_mfma_f32_16x16x32_bf16 v[114:117], v[188:191], v[196:199], v[114:117]
	v_mfma_f32_16x16x32_bf16 v[102:105], v[180:183], v[204:207], v[102:105]
	v_mfma_f32_16x16x32_bf16 v[98:101], v[188:191], v[204:207], v[98:101]
	v_mfma_f32_16x16x32_bf16 v[86:89], v[180:183], v[212:215], v[86:89]
	v_mfma_f32_16x16x32_bf16 v[82:85], v[188:191], v[212:215], v[82:85]
	v_mfma_f32_16x16x32_bf16 v[70:73], v[180:183], v[220:223], v[70:73]
	v_mfma_f32_16x16x32_bf16 v[66:69], v[188:191], v[220:223], v[66:69]
	s_barrier
	s_add_i32 s49, s49, s40
	v_lshl_add_u64 v[152:153], s[6:7], 0, v[0:1]
	s_mov_b32 m0, s49
	ds_read_b128 v[192:195], v150 offset:16384
	ds_read_b128 v[196:199], v150 offset:17408
	ds_read_b128 v[200:203], v150 offset:18432
	ds_read_b128 v[204:207], v150 offset:19456
	ds_read_b128 v[208:211], v150 offset:20480
	ds_read_b128 v[212:215], v150 offset:21504
	ds_read_b128 v[216:219], v150 offset:22528
	ds_read_b128 v[220:223], v150 offset:23552
	global_load_lds_dwordx4 v[152:153], off
	s_add_i32 m0, s49, 0x2000
	s_add_u32 s50, s6, 0x40000
	v_lshl_add_u64 v[164:165], s[6:7], 0, v[134:135]
	s_addc_u32 s51, s7, 0
	s_add_i32 s49, s52, s40
	global_load_lds_dwordx4 v[164:165], off
	v_lshl_add_u64 v[168:169], s[50:51], 0, v[0:1]
	s_mov_b32 m0, s49
	v_lshl_add_u64 v[174:175], s[8:9], 0, v[132:133]
	global_load_lds_dwordx4 v[168:169], off
	v_lshl_add_u64 v[168:169], s[50:51], 0, v[134:135]
	s_add_i32 m0, s49, 0x2000
	s_nop 0
	global_load_lds_dwordx4 v[168:169], off
	v_lshl_add_u64 v[168:169], s[8:9], 0, v[130:131]
	s_mov_b32 m0, s41
	s_nop 0
	global_load_lds_dwordx4 v[168:169], off
	s_mov_b32 m0, s42
	s_nop 0
	global_load_lds_dwordx4 v[174:175], off
	s_waitcnt vmcnt(8)
	s_waitcnt lgkmcnt(0)
	s_barrier
; #define PG8_STAGE(bufoff, gbase, voff) do { _Pragma("unroll") for (int _i = 0; _i < 2; ++_i) \
;         __builtin_amdgcn_global_load_lds((const unsigned*)((const char*)(gbase) + (voff)[_i]), (LAS unsigned*)(lds + (bufoff) + ldsw + _i * 8192), 16, 0, 0); } while (0)
; #define PG8_LDA(dst, b, h) do { _Pragma("unroll") for (int m = 0; m < 4; ++m) _Pragma("unroll") for (int k = 0; k < 2; ++k) dst[m][k] = *(const LAS bf16x8*)(lds + PG8_SA(b, h) + aoff + m * 2048 + k * 1024); } while (0)
; #define PG8_LDB(dst, b, h) do { _Pragma("unroll") for (int n = 0; n < 2; ++n) _Pragma("unroll") for (int k = 0; k < 2; ++k) dst[n][k] = *(const LAS bf16x8*)(lds + PG8_SB(b, h) + boff + n * 2048 + k * 1024); } while (0)
; #define PG8_MMA(ai, bj, At, Bt) do { __builtin_amdgcn_s_setprio(1); _Pragma("unroll") for (int m = 0; m < 4; ++m) _Pragma("unroll") for (int n = 0; n < 2; ++n) _Pragma("unroll") for (int k = 0; k < 2; ++k) \
;         acc[ai][bj][m][n] = __builtin_amdgcn_mfma_f32_16x16x32_bf16(Bt[n][k], At[m][k], acc[ai][bj][m][n], 0, 0, 0); __builtin_amdgcn_s_setprio(0); } while (0)
; #define PG8_WAIT_V(n) asm volatile("s_waitcnt vmcnt(" #n ")" ::: "memory")
; #define PG8_WAIT_L(n) asm volatile("s_waitcnt lgkmcnt(" #n ")" ::: "memory")
; #define PG8_BAR __builtin_amdgcn_s_barrier()
; #define PG8_SCHED __builtin_amdgcn_sched_barrier(0)
; template <class Epi, bool ALIGN_EPI>
; __device__ __forceinline__ void gemm_phase(LAS unsigned char* lds, const Gemm g, const StaticOrder& S, const Epi& E) {
;     ...
;             PG8_WAIT_V(8); PG8_WAIT_L(0); PG8_BAR; PG8_MMA(1, 0, At, B0); PG8_MMA(1, 1, At, B1); PG8_BAR; PG8_SCHED;
;             PG8_LDB(B0, 1, 0); PG8_LDB(B1, 1, 1); PG8_SCHED; PG8_LDA(At, 1, 0); PG8_STAGE(PG8_SA(0, 1), a2 + hstepA, voffA);
;             PG8_WAIT_V(8); PG8_WAIT_L(0); PG8_BAR; PG8_MMA(0, 0, At, B0); PG8_MMA(0, 1, At, B1); PG8_BAR; PG8_SCHED;
	s_waitcnt lgkmcnt(0)
	v_mfma_f32_16x16x32_bf16 v[62:65], v[140:143], v[192:195], v[62:65]
	v_mfma_f32_16x16x32_bf16 v[58:61], v[156:159], v[192:195], v[58:61]
	v_mfma_f32_16x16x32_bf16 v[46:49], v[140:143], v[200:203], v[46:49]
	v_mfma_f32_16x16x32_bf16 v[42:45], v[156:159], v[200:203], v[42:45]
	v_mfma_f32_16x16x32_bf16 v[30:33], v[140:143], v[208:211], v[30:33]
	v_mfma_f32_16x16x32_bf16 v[26:29], v[156:159], v[208:211], v[26:29]
	v_mfma_f32_16x16x32_bf16 v[14:17], v[140:143], v[216:219], v[14:17]
	v_mfma_f32_16x16x32_bf16 v[10:13], v[156:159], v[216:219], v[10:13]
	v_mfma_f32_16x16x32_bf16 v[62:65], v[144:147], v[196:199], v[62:65]
	v_mfma_f32_16x16x32_bf16 v[58:61], v[160:163], v[196:199], v[58:61]
	v_mfma_f32_16x16x32_bf16 v[46:49], v[144:147], v[204:207], v[46:49]
	v_mfma_f32_16x16x32_bf16 v[42:45], v[160:163], v[204:207], v[42:45]
	v_mfma_f32_16x16x32_bf16 v[30:33], v[144:147], v[212:215], v[30:33]
	v_mfma_f32_16x16x32_bf16 v[26:29], v[160:163], v[212:215], v[26:29]
	v_mfma_f32_16x16x32_bf16 v[14:17], v[144:147], v[220:223], v[14:17]
	v_mfma_f32_16x16x32_bf16 v[10:13], v[160:163], v[220:223], v[10:13]
	v_mfma_f32_16x16x32_bf16 v[54:57], v[170:173], v[192:195], v[54:57]
	v_mfma_f32_16x16x32_bf16 v[50:53], v[184:187], v[192:195], v[50:53]
	v_mfma_f32_16x16x32_bf16 v[38:41], v[170:173], v[200:203], v[38:41]
	v_mfma_f32_16x16x32_bf16 v[34:37], v[184:187], v[200:203], v[34:37]
	v_mfma_f32_16x16x32_bf16 v[22:25], v[170:173], v[208:211], v[22:25]
	v_mfma_f32_16x16x32_bf16 v[18:21], v[184:187], v[208:211], v[18:21]
	v_mfma_f32_16x16x32_bf16 v[6:9], v[170:173], v[216:219], v[6:9]
	v_mfma_f32_16x16x32_bf16 v[2:5], v[184:187], v[216:219], v[2:5]
	v_mfma_f32_16x16x32_bf16 v[54:57], v[180:183], v[196:199], v[54:57]
	v_mfma_f32_16x16x32_bf16 v[50:53], v[188:191], v[196:199], v[50:53]
	v_mfma_f32_16x16x32_bf16 v[38:41], v[180:183], v[204:207], v[38:41]
	v_mfma_f32_16x16x32_bf16 v[34:37], v[188:191], v[204:207], v[34:37]
	v_mfma_f32_16x16x32_bf16 v[22:25], v[180:183], v[212:215], v[22:25]
	v_mfma_f32_16x16x32_bf16 v[18:21], v[188:191], v[212:215], v[18:21]
	v_mfma_f32_16x16x32_bf16 v[6:9], v[180:183], v[220:223], v[6:9]
	v_mfma_f32_16x16x32_bf16 v[2:5], v[188:191], v[220:223], v[2:5]
	s_barrier
	s_add_i32 s49, 0, 0x18000
	s_add_i32 s50, 0, 0x1c000
	v_add_u32_e32 v160, s49, v148
	v_add_u32_e32 v188, s50, v148
	ds_read_b128 v[140:143], v160
	ds_read_b128 v[144:147], v160 offset:1024
	ds_read_b128 v[156:159], v160 offset:2048
	ds_read_b128 v[160:163], v160 offset:3072
	ds_read_b128 v[170:173], v188
	ds_read_b128 v[180:183], v188 offset:1024
	ds_read_b128 v[184:187], v188 offset:2048
	ds_read_b128 v[188:191], v188 offset:3072
	s_add_u32 s8, s8, 0x40000
	s_addc_u32 s9, s9, 0
	s_mov_b32 m0, s43
	v_lshl_add_u64 v[224:225], s[8:9], 0, v[130:131]
	ds_read_b128 v[192:195], v150 offset:32768
	ds_read_b128 v[196:199], v150 offset:33792
	ds_read_b128 v[200:203], v150 offset:34816
	ds_read_b128 v[204:207], v150 offset:35840
	ds_read_b128 v[208:211], v150 offset:36864
	ds_read_b128 v[212:215], v150 offset:37888
	ds_read_b128 v[216:219], v150 offset:38912
	ds_read_b128 v[220:223], v150 offset:39936
	global_load_lds_dwordx4 v[224:225], off
	v_lshl_add_u64 v[224:225], s[8:9], 0, v[132:133]
	s_mov_b32 m0, s44
	s_nop 0
	global_load_lds_dwordx4 v[224:225], off
	s_waitcnt vmcnt(8)
	s_waitcnt lgkmcnt(0)
	s_barrier
	s_waitcnt lgkmcnt(0)
	v_mfma_f32_16x16x32_bf16 v[122:125], v[140:143], v[192:195], v[122:125]
	v_mfma_f32_16x16x32_bf16 v[126:129], v[156:159], v[192:195], v[126:129]
	v_mfma_f32_16x16x32_bf16 v[110:113], v[140:143], v[200:203], v[110:113]
	v_mfma_f32_16x16x32_bf16 v[106:109], v[156:159], v[200:203], v[106:109]
	v_mfma_f32_16x16x32_bf16 v[94:97], v[140:143], v[208:211], v[94:97]
	v_mfma_f32_16x16x32_bf16 v[90:93], v[156:159], v[208:211], v[90:93]
	v_mfma_f32_16x16x32_bf16 v[78:81], v[140:143], v[216:219], v[78:81]
	v_mfma_f32_16x16x32_bf16 v[74:77], v[156:159], v[216:219], v[74:77]
	v_mfma_f32_16x16x32_bf16 v[122:125], v[144:147], v[196:199], v[122:125]
	v_mfma_f32_16x16x32_bf16 v[126:129], v[160:163], v[196:199], v[126:129]
	v_mfma_f32_16x16x32_bf16 v[110:113], v[144:147], v[204:207], v[110:113]
	v_mfma_f32_16x16x32_bf16 v[106:109], v[160:163], v[204:207], v[106:109]
	v_mfma_f32_16x16x32_bf16 v[94:97], v[144:147], v[212:215], v[94:97]
	v_mfma_f32_16x16x32_bf16 v[90:93], v[160:163], v[212:215], v[90:93]
	v_mfma_f32_16x16x32_bf16 v[78:81], v[144:147], v[220:223], v[78:81]
	v_mfma_f32_16x16x32_bf16 v[74:77], v[160:163], v[220:223], v[74:77]
	v_mfma_f32_16x16x32_bf16 v[118:121], v[170:173], v[192:195], v[118:121]
	v_mfma_f32_16x16x32_bf16 v[114:117], v[184:187], v[192:195], v[114:117]
	v_mfma_f32_16x16x32_bf16 v[102:105], v[170:173], v[200:203], v[102:105]
	v_mfma_f32_16x16x32_bf16 v[98:101], v[184:187], v[200:203], v[98:101]
	v_mfma_f32_16x16x32_bf16 v[86:89], v[170:173], v[208:211], v[86:89]
	v_mfma_f32_16x16x32_bf16 v[82:85], v[184:187], v[208:211], v[82:85]
	v_mfma_f32_16x16x32_bf16 v[70:73], v[170:173], v[216:219], v[70:73]
	v_mfma_f32_16x16x32_bf16 v[66:69], v[184:187], v[216:219], v[66:69]
	v_mfma_f32_16x16x32_bf16 v[118:121], v[180:183], v[196:199], v[118:121]
	v_mfma_f32_16x16x32_bf16 v[114:117], v[188:191], v[196:199], v[114:117]
	v_mfma_f32_16x16x32_bf16 v[102:105], v[180:183], v[204:207], v[102:105]
	v_mfma_f32_16x16x32_bf16 v[98:101], v[188:191], v[204:207], v[98:101]
	v_mfma_f32_16x16x32_bf16 v[86:89], v[180:183], v[212:215], v[86:89]
	v_mfma_f32_16x16x32_bf16 v[82:85], v[188:191], v[212:215], v[82:85]
	v_mfma_f32_16x16x32_bf16 v[70:73], v[180:183], v[220:223], v[70:73]
	v_mfma_f32_16x16x32_bf16 v[66:69], v[188:191], v[220:223], v[66:69]
	s_barrier
; #define PG8_STAGE(bufoff, gbase, voff) do { _Pragma("unroll") for (int _i = 0; _i < 2; ++_i) \
;         __builtin_amdgcn_global_load_lds((const unsigned*)((const char*)(gbase) + (voff)[_i]), (LAS unsigned*)(lds + (bufoff) + ldsw + _i * 8192), 16, 0, 0); } while (0)
; #define PG8_LDA(dst, b, h) do { _Pragma("unroll") for (int m = 0; m < 4; ++m) _Pragma("unroll") for (int k = 0; k < 2; ++k) dst[m][k] = *(const LAS bf16x8*)(lds + PG8_SA(b, h) + aoff + m * 2048 + k * 1024); } while (0)
; #define PG8_MMA(ai, bj, At, Bt) do { __builtin_amdgcn_s_setprio(1); _Pragma("unroll") for (int m = 0; m < 4; ++m) _Pragma("unroll") for (int n = 0; n < 2; ++n) _Pragma("unroll") for (int k = 0; k < 2; ++k) \
;         acc[ai][bj][m][n] = __builtin_amdgcn_mfma_f32_16x16x32_bf16(Bt[n][k], At[m][k], acc[ai][bj][m][n], 0, 0, 0); __builtin_amdgcn_s_setprio(0); } while (0)
; #define PG8_WAIT_V(n) asm volatile("s_waitcnt vmcnt(" #n ")" ::: "memory")
; #define PG8_WAIT_L(n) asm volatile("s_waitcnt lgkmcnt(" #n ")" ::: "memory")
; #define PG8_BAR __builtin_amdgcn_s_barrier()
; #define PG8_SCHED __builtin_amdgcn_sched_barrier(0)
; template <class Epi, bool ALIGN_EPI>
; __device__ __forceinline__ void gemm_phase(LAS unsigned char* lds, const Gemm g, const StaticOrder& S, const Epi& E) {
;     ...
;             PG8_LDA(At, 1, 1); PG8_STAGE(PG8_SB(1, 0), b3, voffB); PG8_STAGE(PG8_SB(1, 1), b3 + hstepB, voffB); PG8_STAGE(PG8_SA(1, 0), a3, voffA);
;             PG8_WAIT_V(8); PG8_WAIT_L(0); PG8_BAR; PG8_MMA(1, 0, At, B0); PG8_MMA(1, 1, At, B1); PG8_BAR; PG8_SCHED;
;         }
;         if constexpr (ALIGN_EPI) { if (wr == 0) PG8_BAR; }
	s_add_i32 s8, s49, s40
	v_lshl_add_u64 v[152:153], v[152:153], 0, s[94:95]
	s_mov_b32 m0, s8
	ds_read_b128 v[192:195], v150 offset:49152
	ds_read_b128 v[196:199], v150 offset:50176
	ds_read_b128 v[200:203], v150 offset:51200
	ds_read_b128 v[204:207], v150 offset:52224
	ds_read_b128 v[208:211], v150 offset:53248
	ds_read_b128 v[212:215], v150 offset:54272
	ds_read_b128 v[216:219], v150 offset:55296
	ds_read_b128 v[220:223], v150 offset:56320
	global_load_lds_dwordx4 v[152:153], off
	s_add_i32 m0, s8, 0x2000
	s_add_u32 s6, s6, 0x40080
	v_lshl_add_u64 v[152:153], v[164:165], 0, s[94:95]
	s_addc_u32 s7, s7, 0
	s_add_i32 s8, s50, s40
	global_load_lds_dwordx4 v[152:153], off
	v_lshl_add_u64 v[152:153], s[6:7], 0, v[0:1]
	s_mov_b32 m0, s8
	s_nop 0
	global_load_lds_dwordx4 v[152:153], off
	v_lshl_add_u64 v[152:153], s[6:7], 0, v[134:135]
	s_add_i32 m0, s8, 0x2000
	s_nop 0
	global_load_lds_dwordx4 v[152:153], off
	v_lshl_add_u64 v[152:153], v[168:169], 0, s[94:95]
	s_mov_b32 m0, s46
	s_nop 0
	global_load_lds_dwordx4 v[152:153], off
	v_lshl_add_u64 v[152:153], v[174:175], 0, s[94:95]
	s_mov_b32 m0, s47
	s_nop 0
	global_load_lds_dwordx4 v[152:153], off
	s_waitcnt vmcnt(8)
	s_waitcnt lgkmcnt(0)
	s_barrier
	s_waitcnt lgkmcnt(0)
	v_mfma_f32_16x16x32_bf16 v[62:65], v[140:143], v[192:195], v[62:65]
	v_mfma_f32_16x16x32_bf16 v[58:61], v[156:159], v[192:195], v[58:61]
	v_mfma_f32_16x16x32_bf16 v[46:49], v[140:143], v[200:203], v[46:49]
	v_mfma_f32_16x16x32_bf16 v[42:45], v[156:159], v[200:203], v[42:45]
	v_mfma_f32_16x16x32_bf16 v[30:33], v[140:143], v[208:211], v[30:33]
	v_mfma_f32_16x16x32_bf16 v[26:29], v[156:159], v[208:211], v[26:29]
	v_mfma_f32_16x16x32_bf16 v[14:17], v[140:143], v[216:219], v[14:17]
	v_mfma_f32_16x16x32_bf16 v[10:13], v[156:159], v[216:219], v[10:13]
	v_mfma_f32_16x16x32_bf16 v[62:65], v[144:147], v[196:199], v[62:65]
	v_mfma_f32_16x16x32_bf16 v[58:61], v[160:163], v[196:199], v[58:61]
	v_mfma_f32_16x16x32_bf16 v[46:49], v[144:147], v[204:207], v[46:49]
	v_mfma_f32_16x16x32_bf16 v[42:45], v[160:163], v[204:207], v[42:45]
	v_mfma_f32_16x16x32_bf16 v[30:33], v[144:147], v[212:215], v[30:33]
	v_mfma_f32_16x16x32_bf16 v[26:29], v[160:163], v[212:215], v[26:29]
	v_mfma_f32_16x16x32_bf16 v[14:17], v[144:147], v[220:223], v[14:17]
	v_mfma_f32_16x16x32_bf16 v[10:13], v[160:163], v[220:223], v[10:13]
	v_mfma_f32_16x16x32_bf16 v[54:57], v[170:173], v[192:195], v[54:57]
	v_mfma_f32_16x16x32_bf16 v[50:53], v[184:187], v[192:195], v[50:53]
	v_mfma_f32_16x16x32_bf16 v[38:41], v[170:173], v[200:203], v[38:41]
	v_mfma_f32_16x16x32_bf16 v[34:37], v[184:187], v[200:203], v[34:37]
	v_mfma_f32_16x16x32_bf16 v[22:25], v[170:173], v[208:211], v[22:25]
	v_mfma_f32_16x16x32_bf16 v[18:21], v[184:187], v[208:211], v[18:21]
	v_mfma_f32_16x16x32_bf16 v[6:9], v[170:173], v[216:219], v[6:9]
	v_mfma_f32_16x16x32_bf16 v[2:5], v[184:187], v[216:219], v[2:5]
	v_mfma_f32_16x16x32_bf16 v[54:57], v[180:183], v[196:199], v[54:57]
	v_mfma_f32_16x16x32_bf16 v[50:53], v[188:191], v[196:199], v[50:53]
	v_mfma_f32_16x16x32_bf16 v[38:41], v[180:183], v[204:207], v[38:41]
	v_mfma_f32_16x16x32_bf16 v[34:37], v[188:191], v[204:207], v[34:37]
	v_mfma_f32_16x16x32_bf16 v[22:25], v[180:183], v[212:215], v[22:25]
	v_mfma_f32_16x16x32_bf16 v[18:21], v[188:191], v[212:215], v[18:21]
	v_mfma_f32_16x16x32_bf16 v[6:9], v[180:183], v[220:223], v[6:9]
	v_mfma_f32_16x16x32_bf16 v[2:5], v[188:191], v[220:223], v[2:5]
	s_cmp_lg_u32 s37, 12
	s_cbranch_scc1 .Ltail_bar_10
	s_cmp_eq_u64 s[20:21], 0
	s_cbranch_scc1 .Ltail_skip_10
.Ltail_bar_10:
	s_barrier
.Ltail_skip_10:
	s_add_i32 s37, s37, 2
	s_add_u32 s2, s2, 0x100
	s_addc_u32 s3, s3, 0
	s_add_u32 s27, s27, 0x100
	s_addc_u32 s36, s36, 0
	s_cmp_gt_u32 s37, 13
	s_cbranch_scc0 .LBB0_102

; #define PG8_STAGE(bufoff, gbase, voff) do { _Pragma("unroll") for (int _i = 0; _i < 2; ++_i) \
;         __builtin_amdgcn_global_load_lds((const unsigned*)((const char*)(gbase) + (voff)[_i]), (LAS unsigned*)(lds + (bufoff) + ldsw + _i * 8192), 16, 0, 0); } while (0)
; #define PG8_LDA(dst, b, h) do { _Pragma("unroll") for (int m = 0; m < 4; ++m) _Pragma("unroll") for (int k = 0; k < 2; ++k) dst[m][k] = *(const LAS bf16x8*)(lds + PG8_SA(b, h) + aoff + m * 2048 + k * 1024); } while (0)
; #define PG8_LDB(dst, b, h) do { _Pragma("unroll") for (int n = 0; n < 2; ++n) _Pragma("unroll") for (int k = 0; k < 2; ++k) dst[n][k] = *(const LAS bf16x8*)(lds + PG8_SB(b, h) + boff + n * 2048 + k * 1024); } while (0)
; #define PG8_MMA(ai, bj, At, Bt) do { __builtin_amdgcn_s_setprio(1); _Pragma("unroll") for (int m = 0; m < 4; ++m) _Pragma("unroll") for (int n = 0; n < 2; ++n) _Pragma("unroll") for (int k = 0; k < 2; ++k) \
;         acc[ai][bj][m][n] = __builtin_amdgcn_mfma_f32_16x16x32_bf16(Bt[n][k], At[m][k], acc[ai][bj][m][n], 0, 0, 0); __builtin_amdgcn_s_setprio(0); } while (0)
; #define PG8_WAIT_V(n) asm volatile("s_waitcnt vmcnt(" #n ")" ::: "memory")
; #define PG8_WAIT_L(n) asm volatile("s_waitcnt lgkmcnt(" #n ")" ::: "memory")
; #define PG8_BAR __builtin_amdgcn_s_barrier()
; #define PG8_SCHED __builtin_amdgcn_sched_barrier(0)
; template <class Epi, bool ALIGN_EPI>
; __device__ __forceinline__ void gemm_phase(LAS unsigned char* lds, const Gemm g, const StaticOrder& S, const Epi& E) {
;     ...
;         for (int t = 0; t < nt; t += 2) {
;             const bool last = (t == nt - 2);
;             const char* a1 = cA + (size_t)(t + 1) * kstep;
;             const char* a2 = last ? nA : cA + (size_t)(t + 2) * kstep; const char* b2 = last ? nB : cB + (size_t)(t + 2) * kstep;
;             const char* a3 = a2 + kstep; const char* b3 = b2 + kstep;
;             PG8_LDB(B0, 0, 0); PG8_LDB(B1, 0, 1); PG8_SCHED; PG8_LDA(At, 0, 0); PG8_STAGE(PG8_SA(1, 1), a1 + hstepA, voffA);
;             PG8_WAIT_V(8); PG8_WAIT_L(0); PG8_BAR; PG8_MMA(0, 0, At, B0); PG8_MMA(0, 1, At, B1); PG8_BAR; PG8_SCHED;
;             PG8_LDA(At, 0, 1); PG8_STAGE(PG8_SB(0, 0), b2, voffB); PG8_STAGE(PG8_SB(0, 1), b2 + hstepB, voffB); PG8_STAGE(PG8_SA(0, 0), a2, voffA);
.LBB0_216:
	s_add_u32 s12, s10, 0x100
	s_addc_u32 s13, s11, 0
	s_add_i32 s44, 0, 0x10000
	s_cmp_eq_u32 s43, 40
	s_cselect_b32 s25, s19, s13
	s_cselect_b32 s24, s18, s12
	v_add_u32_e32 v144, s44, v146
	s_cselect_b32 s23, s21, s42
	s_cselect_b32 s22, s20, s41
	s_add_i32 s45, 0, 0x14000
	ds_read_b128 v[140:143], v144
	ds_read_b128 v[148:151], v144 offset:1024
	ds_read_b128 v[156:159], v144 offset:2048
	ds_read_b128 v[180:183], v144 offset:3072
	v_add_u32_e32 v144, s45, v146
	ds_read_b128 v[184:187], v144
	ds_read_b128 v[188:191], v144 offset:1024
	ds_read_b128 v[192:195], v144 offset:2048
	ds_read_b128 v[196:199], v144 offset:3072
	v_lshl_add_u64 v[144:145], s[10:11], 0, v[136:137]
	s_add_i32 m0, s29, 0xc000
	ds_read_b128 v[200:203], v147
	ds_read_b128 v[204:207], v147 offset:1024
	ds_read_b128 v[208:211], v147 offset:2048
	ds_read_b128 v[212:215], v147 offset:3072
	ds_read_b128 v[216:219], v147 offset:4096
	ds_read_b128 v[220:223], v147 offset:5120
	ds_read_b128 v[224:227], v147 offset:6144
	ds_read_b128 v[228:231], v147 offset:7168
	global_load_lds_dwordx4 v[144:145], off
	v_lshl_add_u64 v[144:145], s[10:11], 0, v[138:139]
	s_add_i32 m0, s29, 0xe000
	s_nop 0
	global_load_lds_dwordx4 v[144:145], off
	s_waitcnt vmcnt(8)
	s_waitcnt lgkmcnt(0)
	s_barrier
	s_waitcnt lgkmcnt(0)
	v_mfma_f32_16x16x32_bf16 v[126:129], v[140:143], v[200:203], v[126:129]
	v_mfma_f32_16x16x32_bf16 v[122:125], v[156:159], v[200:203], v[122:125]
	v_mfma_f32_16x16x32_bf16 v[110:113], v[140:143], v[208:211], v[110:113]
	v_mfma_f32_16x16x32_bf16 v[106:109], v[156:159], v[208:211], v[106:109]
	v_mfma_f32_16x16x32_bf16 v[94:97], v[140:143], v[216:219], v[94:97]
	v_mfma_f32_16x16x32_bf16 v[90:93], v[156:159], v[216:219], v[90:93]
	v_mfma_f32_16x16x32_bf16 v[78:81], v[140:143], v[224:227], v[78:81]
	v_mfma_f32_16x16x32_bf16 v[74:77], v[156:159], v[224:227], v[74:77]
	v_mfma_f32_16x16x32_bf16 v[126:129], v[148:151], v[204:207], v[126:129]
	v_mfma_f32_16x16x32_bf16 v[122:125], v[180:183], v[204:207], v[122:125]
	v_mfma_f32_16x16x32_bf16 v[110:113], v[148:151], v[212:215], v[110:113]
	v_mfma_f32_16x16x32_bf16 v[106:109], v[180:183], v[212:215], v[106:109]
	v_mfma_f32_16x16x32_bf16 v[94:97], v[148:151], v[220:223], v[94:97]
	v_mfma_f32_16x16x32_bf16 v[90:93], v[180:183], v[220:223], v[90:93]
	v_mfma_f32_16x16x32_bf16 v[78:81], v[148:151], v[228:231], v[78:81]
	v_mfma_f32_16x16x32_bf16 v[74:77], v[180:183], v[228:231], v[74:77]
	v_mfma_f32_16x16x32_bf16 v[118:121], v[184:187], v[200:203], v[118:121]
	v_mfma_f32_16x16x32_bf16 v[114:117], v[192:195], v[200:203], v[114:117]
	v_mfma_f32_16x16x32_bf16 v[102:105], v[184:187], v[208:211], v[102:105]
	v_mfma_f32_16x16x32_bf16 v[98:101], v[192:195], v[208:211], v[98:101]
	v_mfma_f32_16x16x32_bf16 v[86:89], v[184:187], v[216:219], v[86:89]
	v_mfma_f32_16x16x32_bf16 v[82:85], v[192:195], v[216:219], v[82:85]
	v_mfma_f32_16x16x32_bf16 v[70:73], v[184:187], v[224:227], v[70:73]
	v_mfma_f32_16x16x32_bf16 v[66:69], v[192:195], v[224:227], v[66:69]
	v_mfma_f32_16x16x32_bf16 v[118:121], v[188:191], v[204:207], v[118:121]
	v_mfma_f32_16x16x32_bf16 v[114:117], v[196:199], v[204:207], v[114:117]
	v_mfma_f32_16x16x32_bf16 v[102:105], v[188:191], v[212:215], v[102:105]
	v_mfma_f32_16x16x32_bf16 v[98:101], v[196:199], v[212:215], v[98:101]
	v_mfma_f32_16x16x32_bf16 v[86:89], v[188:191], v[220:223], v[86:89]
	v_mfma_f32_16x16x32_bf16 v[82:85], v[196:199], v[220:223], v[82:85]
	v_mfma_f32_16x16x32_bf16 v[70:73], v[188:191], v[228:231], v[70:73]
	v_mfma_f32_16x16x32_bf16 v[66:69], v[196:199], v[228:231], v[66:69]
	s_barrier
	s_add_i32 s10, s44, s28
	v_lshl_add_u64 v[144:145], s[22:23], 0, v[0:1]
	s_mov_b32 m0, s10
	ds_read_b128 v[200:203], v147 offset:16384
	ds_read_b128 v[204:207], v147 offset:17408
	ds_read_b128 v[208:211], v147 offset:18432
	ds_read_b128 v[212:215], v147 offset:19456
	ds_read_b128 v[216:219], v147 offset:20480
	ds_read_b128 v[220:223], v147 offset:21504
	ds_read_b128 v[224:227], v147 offset:22528
	ds_read_b128 v[228:231], v147 offset:23552
	global_load_lds_dwordx4 v[144:145], off
	s_add_i32 m0, s10, 0x2000
	s_add_u32 s10, s22, 0xb0000
	v_lshl_add_u64 v[152:153], s[22:23], 0, v[134:135]
	s_addc_u32 s11, s23, 0
	s_add_i32 s44, s45, s28
	global_load_lds_dwordx4 v[152:153], off
	v_lshl_add_u64 v[160:161], s[10:11], 0, v[0:1]
	s_mov_b32 m0, s44
	v_lshl_add_u64 v[162:163], s[24:25], 0, v[132:133]
	global_load_lds_dwordx4 v[160:161], off
	v_lshl_add_u64 v[160:161], s[10:11], 0, v[134:135]
	s_add_i32 m0, s44, 0x2000
	s_nop 0
	global_load_lds_dwordx4 v[160:161], off
	v_lshl_add_u64 v[160:161], s[24:25], 0, v[130:131]
	s_mov_b32 m0, s29
	s_nop 0
	global_load_lds_dwordx4 v[160:161], off
	s_mov_b32 m0, s30
	s_nop 0
	global_load_lds_dwordx4 v[162:163], off
	s_waitcnt vmcnt(8)
	s_waitcnt lgkmcnt(0)
	s_barrier
; #define PG8_STAGE(bufoff, gbase, voff) do { _Pragma("unroll") for (int _i = 0; _i < 2; ++_i) \
;         __builtin_amdgcn_global_load_lds((const unsigned*)((const char*)(gbase) + (voff)[_i]), (LAS unsigned*)(lds + (bufoff) + ldsw + _i * 8192), 16, 0, 0); } while (0)
; #define PG8_LDA(dst, b, h) do { _Pragma("unroll") for (int m = 0; m < 4; ++m) _Pragma("unroll") for (int k = 0; k < 2; ++k) dst[m][k] = *(const LAS bf16x8*)(lds + PG8_SA(b, h) + aoff + m * 2048 + k * 1024); } while (0)
; #define PG8_LDB(dst, b, h) do { _Pragma("unroll") for (int n = 0; n < 2; ++n) _Pragma("unroll") for (int k = 0; k < 2; ++k) dst[n][k] = *(const LAS bf16x8*)(lds + PG8_SB(b, h) + boff + n * 2048 + k * 1024); } while (0)
; #define PG8_MMA(ai, bj, At, Bt) do { __builtin_amdgcn_s_setprio(1); _Pragma("unroll") for (int m = 0; m < 4; ++m) _Pragma("unroll") for (int n = 0; n < 2; ++n) _Pragma("unroll") for (int k = 0; k < 2; ++k) \
;         acc[ai][bj][m][n] = __builtin_amdgcn_mfma_f32_16x16x32_bf16(Bt[n][k], At[m][k], acc[ai][bj][m][n], 0, 0, 0); __builtin_amdgcn_s_setprio(0); } while (0)
; #define PG8_WAIT_V(n) asm volatile("s_waitcnt vmcnt(" #n ")" ::: "memory")
; #define PG8_WAIT_L(n) asm volatile("s_waitcnt lgkmcnt(" #n ")" ::: "memory")
; #define PG8_BAR __builtin_amdgcn_s_barrier()
; #define PG8_SCHED __builtin_amdgcn_sched_barrier(0)
; template <class Epi, bool ALIGN_EPI>
; __device__ __forceinline__ void gemm_phase(LAS unsigned char* lds, const Gemm g, const StaticOrder& S, const Epi& E) {
;     ...
;             PG8_WAIT_V(8); PG8_WAIT_L(0); PG8_BAR; PG8_MMA(1, 0, At, B0); PG8_MMA(1, 1, At, B1); PG8_BAR; PG8_SCHED;
;             PG8_LDB(B0, 1, 0); PG8_LDB(B1, 1, 1); PG8_SCHED; PG8_LDA(At, 1, 0); PG8_STAGE(PG8_SA(0, 1), a2 + hstepA, voffA);
;             PG8_WAIT_V(8); PG8_WAIT_L(0); PG8_BAR; PG8_MMA(0, 0, At, B0); PG8_MMA(0, 1, At, B1); PG8_BAR; PG8_SCHED;
	s_waitcnt lgkmcnt(0)
	v_mfma_f32_16x16x32_bf16 v[62:65], v[140:143], v[200:203], v[62:65]
	v_mfma_f32_16x16x32_bf16 v[58:61], v[156:159], v[200:203], v[58:61]
	v_mfma_f32_16x16x32_bf16 v[46:49], v[140:143], v[208:211], v[46:49]
	v_mfma_f32_16x16x32_bf16 v[42:45], v[156:159], v[208:211], v[42:45]
	v_mfma_f32_16x16x32_bf16 v[30:33], v[140:143], v[216:219], v[30:33]
	v_mfma_f32_16x16x32_bf16 v[26:29], v[156:159], v[216:219], v[26:29]
	v_mfma_f32_16x16x32_bf16 v[14:17], v[140:143], v[224:227], v[14:17]
	v_mfma_f32_16x16x32_bf16 v[10:13], v[156:159], v[224:227], v[10:13]
	v_mfma_f32_16x16x32_bf16 v[62:65], v[148:151], v[204:207], v[62:65]
	v_mfma_f32_16x16x32_bf16 v[58:61], v[180:183], v[204:207], v[58:61]
	v_mfma_f32_16x16x32_bf16 v[46:49], v[148:151], v[212:215], v[46:49]
	v_mfma_f32_16x16x32_bf16 v[42:45], v[180:183], v[212:215], v[42:45]
	v_mfma_f32_16x16x32_bf16 v[30:33], v[148:151], v[220:223], v[30:33]
	v_mfma_f32_16x16x32_bf16 v[26:29], v[180:183], v[220:223], v[26:29]
	v_mfma_f32_16x16x32_bf16 v[14:17], v[148:151], v[228:231], v[14:17]
	v_mfma_f32_16x16x32_bf16 v[10:13], v[180:183], v[228:231], v[10:13]
	v_mfma_f32_16x16x32_bf16 v[54:57], v[184:187], v[200:203], v[54:57]
	v_mfma_f32_16x16x32_bf16 v[50:53], v[192:195], v[200:203], v[50:53]
	v_mfma_f32_16x16x32_bf16 v[38:41], v[184:187], v[208:211], v[38:41]
	v_mfma_f32_16x16x32_bf16 v[34:37], v[192:195], v[208:211], v[34:37]
	v_mfma_f32_16x16x32_bf16 v[22:25], v[184:187], v[216:219], v[22:25]
	v_mfma_f32_16x16x32_bf16 v[18:21], v[192:195], v[216:219], v[18:21]
	v_mfma_f32_16x16x32_bf16 v[6:9], v[184:187], v[224:227], v[6:9]
	v_mfma_f32_16x16x32_bf16 v[2:5], v[192:195], v[224:227], v[2:5]
	v_mfma_f32_16x16x32_bf16 v[54:57], v[188:191], v[204:207], v[54:57]
	v_mfma_f32_16x16x32_bf16 v[50:53], v[196:199], v[204:207], v[50:53]
	v_mfma_f32_16x16x32_bf16 v[38:41], v[188:191], v[212:215], v[38:41]
	v_mfma_f32_16x16x32_bf16 v[34:37], v[196:199], v[212:215], v[34:37]
	v_mfma_f32_16x16x32_bf16 v[22:25], v[188:191], v[220:223], v[22:25]
	v_mfma_f32_16x16x32_bf16 v[18:21], v[196:199], v[220:223], v[18:21]
	v_mfma_f32_16x16x32_bf16 v[6:9], v[188:191], v[228:231], v[6:9]
	v_mfma_f32_16x16x32_bf16 v[2:5], v[196:199], v[228:231], v[2:5]
	s_barrier
	s_add_i32 s44, 0, 0x18000
	v_add_u32_e32 v164, s44, v146
	s_add_i32 s45, 0, 0x1c000
	ds_read_b128 v[140:143], v164
	ds_read_b128 v[148:151], v164 offset:1024
	ds_read_b128 v[156:159], v164 offset:2048
	ds_read_b128 v[180:183], v164 offset:3072
	v_add_u32_e32 v164, s45, v146
	ds_read_b128 v[184:187], v164
	ds_read_b128 v[188:191], v164 offset:1024
	ds_read_b128 v[192:195], v164 offset:2048
	ds_read_b128 v[196:199], v164 offset:3072
	s_add_u32 s10, s24, 0xb0000
	s_addc_u32 s11, s25, 0
	s_mov_b32 m0, s31
	v_lshl_add_u64 v[170:171], s[10:11], 0, v[130:131]
	ds_read_b128 v[200:203], v147 offset:32768
	ds_read_b128 v[204:207], v147 offset:33792
	ds_read_b128 v[208:211], v147 offset:34816
	ds_read_b128 v[212:215], v147 offset:35840
	ds_read_b128 v[216:219], v147 offset:36864
	ds_read_b128 v[220:223], v147 offset:37888
	ds_read_b128 v[224:227], v147 offset:38912
	ds_read_b128 v[228:231], v147 offset:39936
	global_load_lds_dwordx4 v[170:171], off
	v_lshl_add_u64 v[170:171], s[10:11], 0, v[132:133]
	s_mov_b32 m0, s34
	s_nop 0
	global_load_lds_dwordx4 v[170:171], off
	s_waitcnt vmcnt(8)
	s_waitcnt lgkmcnt(0)
	s_barrier
	s_waitcnt lgkmcnt(0)
	v_mfma_f32_16x16x32_bf16 v[126:129], v[140:143], v[200:203], v[126:129]
	v_mfma_f32_16x16x32_bf16 v[122:125], v[156:159], v[200:203], v[122:125]
	v_mfma_f32_16x16x32_bf16 v[110:113], v[140:143], v[208:211], v[110:113]
	v_mfma_f32_16x16x32_bf16 v[106:109], v[156:159], v[208:211], v[106:109]
	v_mfma_f32_16x16x32_bf16 v[94:97], v[140:143], v[216:219], v[94:97]
	v_mfma_f32_16x16x32_bf16 v[90:93], v[156:159], v[216:219], v[90:93]
	v_mfma_f32_16x16x32_bf16 v[78:81], v[140:143], v[224:227], v[78:81]
	v_mfma_f32_16x16x32_bf16 v[74:77], v[156:159], v[224:227], v[74:77]
	v_mfma_f32_16x16x32_bf16 v[126:129], v[148:151], v[204:207], v[126:129]
	v_mfma_f32_16x16x32_bf16 v[122:125], v[180:183], v[204:207], v[122:125]
	v_mfma_f32_16x16x32_bf16 v[110:113], v[148:151], v[212:215], v[110:113]
	v_mfma_f32_16x16x32_bf16 v[106:109], v[180:183], v[212:215], v[106:109]
	v_mfma_f32_16x16x32_bf16 v[94:97], v[148:151], v[220:223], v[94:97]
	v_mfma_f32_16x16x32_bf16 v[90:93], v[180:183], v[220:223], v[90:93]
	v_mfma_f32_16x16x32_bf16 v[78:81], v[148:151], v[228:231], v[78:81]
	v_mfma_f32_16x16x32_bf16 v[74:77], v[180:183], v[228:231], v[74:77]
	v_mfma_f32_16x16x32_bf16 v[118:121], v[184:187], v[200:203], v[118:121]
	v_mfma_f32_16x16x32_bf16 v[114:117], v[192:195], v[200:203], v[114:117]
	v_mfma_f32_16x16x32_bf16 v[102:105], v[184:187], v[208:211], v[102:105]
	v_mfma_f32_16x16x32_bf16 v[98:101], v[192:195], v[208:211], v[98:101]
	v_mfma_f32_16x16x32_bf16 v[86:89], v[184:187], v[216:219], v[86:89]
	v_mfma_f32_16x16x32_bf16 v[82:85], v[192:195], v[216:219], v[82:85]
	v_mfma_f32_16x16x32_bf16 v[70:73], v[184:187], v[224:227], v[70:73]
	v_mfma_f32_16x16x32_bf16 v[66:69], v[192:195], v[224:227], v[66:69]
	v_mfma_f32_16x16x32_bf16 v[118:121], v[188:191], v[204:207], v[118:121]
	v_mfma_f32_16x16x32_bf16 v[114:117], v[196:199], v[204:207], v[114:117]
	v_mfma_f32_16x16x32_bf16 v[102:105], v[188:191], v[212:215], v[102:105]
	v_mfma_f32_16x16x32_bf16 v[98:101], v[196:199], v[212:215], v[98:101]
	v_mfma_f32_16x16x32_bf16 v[86:89], v[188:191], v[220:223], v[86:89]
	v_mfma_f32_16x16x32_bf16 v[82:85], v[196:199], v[220:223], v[82:85]
	v_mfma_f32_16x16x32_bf16 v[70:73], v[188:191], v[228:231], v[70:73]
	v_mfma_f32_16x16x32_bf16 v[66:69], v[196:199], v[228:231], v[66:69]
	s_barrier
; #define PG8_STAGE(bufoff, gbase, voff) do { _Pragma("unroll") for (int _i = 0; _i < 2; ++_i) \
;         __builtin_amdgcn_global_load_lds((const unsigned*)((const char*)(gbase) + (voff)[_i]), (LAS unsigned*)(lds + (bufoff) + ldsw + _i * 8192), 16, 0, 0); } while (0)
; #define PG8_LDA(dst, b, h) do { _Pragma("unroll") for (int m = 0; m < 4; ++m) _Pragma("unroll") for (int k = 0; k < 2; ++k) dst[m][k] = *(const LAS bf16x8*)(lds + PG8_SA(b, h) + aoff + m * 2048 + k * 1024); } while (0)
; #define PG8_MMA(ai, bj, At, Bt) do { __builtin_amdgcn_s_setprio(1); _Pragma("unroll") for (int m = 0; m < 4; ++m) _Pragma("unroll") for (int n = 0; n < 2; ++n) _Pragma("unroll") for (int k = 0; k < 2; ++k) \
;         acc[ai][bj][m][n] = __builtin_amdgcn_mfma_f32_16x16x32_bf16(Bt[n][k], At[m][k], acc[ai][bj][m][n], 0, 0, 0); __builtin_amdgcn_s_setprio(0); } while (0)
; #define PG8_WAIT_V(n) asm volatile("s_waitcnt vmcnt(" #n ")" ::: "memory")
; #define PG8_WAIT_L(n) asm volatile("s_waitcnt lgkmcnt(" #n ")" ::: "memory")
; #define PG8_BAR __builtin_amdgcn_s_barrier()
; #define PG8_SCHED __builtin_amdgcn_sched_barrier(0)
; template <class Epi, bool ALIGN_EPI>
; __device__ __forceinline__ void gemm_phase(LAS unsigned char* lds, const Gemm g, const StaticOrder& S, const Epi& E) {
;     ...
;             PG8_LDA(At, 1, 1); PG8_STAGE(PG8_SB(1, 0), b3, voffB); PG8_STAGE(PG8_SB(1, 1), b3 + hstepB, voffB); PG8_STAGE(PG8_SA(1, 0), a3, voffA);
;             PG8_WAIT_V(8); PG8_WAIT_L(0); PG8_BAR; PG8_MMA(1, 0, At, B0); PG8_MMA(1, 1, At, B1); PG8_BAR; PG8_SCHED;
	s_add_i32 s10, s44, s28
	v_lshl_add_u64 v[144:145], v[144:145], 0, s[94:95]
	s_mov_b32 m0, s10
	ds_read_b128 v[200:203], v147 offset:49152
	ds_read_b128 v[204:207], v147 offset:50176
	ds_read_b128 v[208:211], v147 offset:51200
	ds_read_b128 v[212:215], v147 offset:52224
	ds_read_b128 v[216:219], v147 offset:53248
	ds_read_b128 v[220:223], v147 offset:54272
	ds_read_b128 v[224:227], v147 offset:55296
	ds_read_b128 v[228:231], v147 offset:56320
	global_load_lds_dwordx4 v[144:145], off
	s_add_i32 m0, s10, 0x2000
	s_add_u32 s10, s22, 0xb0080
	v_lshl_add_u64 v[144:145], v[152:153], 0, s[94:95]
	s_addc_u32 s11, s23, 0
	s_add_i32 s22, s45, s28
	global_load_lds_dwordx4 v[144:145], off
	v_lshl_add_u64 v[144:145], s[10:11], 0, v[0:1]
	s_mov_b32 m0, s22
	s_nop 0
	global_load_lds_dwordx4 v[144:145], off
	v_lshl_add_u64 v[144:145], s[10:11], 0, v[134:135]
	s_add_i32 m0, s22, 0x2000
	s_nop 0
	global_load_lds_dwordx4 v[144:145], off
	v_lshl_add_u64 v[144:145], v[160:161], 0, s[94:95]
	s_mov_b32 m0, s35
	s_nop 0
	global_load_lds_dwordx4 v[144:145], off
	v_lshl_add_u64 v[144:145], v[162:163], 0, s[94:95]
	s_mov_b32 m0, s36
	s_nop 0
	global_load_lds_dwordx4 v[144:145], off
	s_waitcnt vmcnt(8)
	s_waitcnt lgkmcnt(0)
	s_barrier
	s_waitcnt lgkmcnt(0)
	v_mfma_f32_16x16x32_bf16 v[62:65], v[140:143], v[200:203], v[62:65]
	v_mfma_f32_16x16x32_bf16 v[58:61], v[156:159], v[200:203], v[58:61]
	v_mfma_f32_16x16x32_bf16 v[46:49], v[140:143], v[208:211], v[46:49]
	v_mfma_f32_16x16x32_bf16 v[42:45], v[156:159], v[208:211], v[42:45]
	v_mfma_f32_16x16x32_bf16 v[30:33], v[140:143], v[216:219], v[30:33]
	v_mfma_f32_16x16x32_bf16 v[26:29], v[156:159], v[216:219], v[26:29]
	v_mfma_f32_16x16x32_bf16 v[14:17], v[140:143], v[224:227], v[14:17]
	v_mfma_f32_16x16x32_bf16 v[10:13], v[156:159], v[224:227], v[10:13]
	v_mfma_f32_16x16x32_bf16 v[62:65], v[148:151], v[204:207], v[62:65]
	v_mfma_f32_16x16x32_bf16 v[58:61], v[180:183], v[204:207], v[58:61]
	v_mfma_f32_16x16x32_bf16 v[46:49], v[148:151], v[212:215], v[46:49]
	v_mfma_f32_16x16x32_bf16 v[42:45], v[180:183], v[212:215], v[42:45]
	v_mfma_f32_16x16x32_bf16 v[30:33], v[148:151], v[220:223], v[30:33]
	v_mfma_f32_16x16x32_bf16 v[26:29], v[180:183], v[220:223], v[26:29]
	v_mfma_f32_16x16x32_bf16 v[14:17], v[148:151], v[228:231], v[14:17]
	v_mfma_f32_16x16x32_bf16 v[10:13], v[180:183], v[228:231], v[10:13]
	v_mfma_f32_16x16x32_bf16 v[54:57], v[184:187], v[200:203], v[54:57]
	v_mfma_f32_16x16x32_bf16 v[50:53], v[192:195], v[200:203], v[50:53]
	v_mfma_f32_16x16x32_bf16 v[38:41], v[184:187], v[208:211], v[38:41]
	v_mfma_f32_16x16x32_bf16 v[34:37], v[192:195], v[208:211], v[34:37]
	v_mfma_f32_16x16x32_bf16 v[22:25], v[184:187], v[216:219], v[22:25]
	v_mfma_f32_16x16x32_bf16 v[18:21], v[192:195], v[216:219], v[18:21]
	v_mfma_f32_16x16x32_bf16 v[6:9], v[184:187], v[224:227], v[6:9]
	v_mfma_f32_16x16x32_bf16 v[2:5], v[192:195], v[224:227], v[2:5]
	v_mfma_f32_16x16x32_bf16 v[54:57], v[188:191], v[204:207], v[54:57]
	v_mfma_f32_16x16x32_bf16 v[50:53], v[196:199], v[204:207], v[50:53]
	v_mfma_f32_16x16x32_bf16 v[38:41], v[188:191], v[212:215], v[38:41]
	v_mfma_f32_16x16x32_bf16 v[34:37], v[196:199], v[212:215], v[34:37]
	v_mfma_f32_16x16x32_bf16 v[22:25], v[188:191], v[220:223], v[22:25]
	v_mfma_f32_16x16x32_bf16 v[18:21], v[196:199], v[220:223], v[18:21]
	v_mfma_f32_16x16x32_bf16 v[6:9], v[188:191], v[228:231], v[6:9]
	v_mfma_f32_16x16x32_bf16 v[2:5], v[196:199], v[228:231], v[2:5]
	s_cmp_lg_u32 s43, 40
	s_cbranch_scc1 .Ltail_bar_9
	s_cmp_eq_u64 s[2:3], 0
	s_cbranch_scc1 .Ltail_skip_9

; #define PG8_BAR __builtin_amdgcn_s_barrier()
; template <class Epi, bool ALIGN_EPI>
; __device__ __forceinline__ void gemm_phase(LAS unsigned char* lds, const Gemm g, const StaticOrder& S, const Epi& E) {
;     ...
;         }
;         if constexpr (ALIGN_EPI) { if (wr == 0) PG8_BAR; }
.Ltail_skip_9:
	s_add_i32 s43, s43, 2
	s_add_u32 s41, s41, 0x100
	s_addc_u32 s42, s42, 0
	s_cmp_gt_u32 s43, 41
	s_mov_b64 s[10:11], s[12:13]
	s_cbranch_scc0 .LBB0_216

; #define PG8_STAGE(bufoff, gbase, voff) do { _Pragma("unroll") for (int _i = 0; _i < 2; ++_i) \
;         __builtin_amdgcn_global_load_lds((const unsigned*)((const char*)(gbase) + (voff)[_i]), (LAS unsigned*)(lds + (bufoff) + ldsw + _i * 8192), 16, 0, 0); } while (0)
; #define PG8_LDA(dst, b, h) do { _Pragma("unroll") for (int m = 0; m < 4; ++m) _Pragma("unroll") for (int k = 0; k < 2; ++k) dst[m][k] = *(const LAS bf16x8*)(lds + PG8_SA(b, h) + aoff + m * 2048 + k * 1024); } while (0)
; #define PG8_LDB(dst, b, h) do { _Pragma("unroll") for (int n = 0; n < 2; ++n) _Pragma("unroll") for (int k = 0; k < 2; ++k) dst[n][k] = *(const LAS bf16x8*)(lds + PG8_SB(b, h) + boff + n * 2048 + k * 1024); } while (0)
; #define PG8_MMA(ai, bj, At, Bt) do { __builtin_amdgcn_s_setprio(1); _Pragma("unroll") for (int m = 0; m < 4; ++m) _Pragma("unroll") for (int n = 0; n < 2; ++n) _Pragma("unroll") for (int k = 0; k < 2; ++k) \
;         acc[ai][bj][m][n] = __builtin_amdgcn_mfma_f32_16x16x32_bf16(Bt[n][k], At[m][k], acc[ai][bj][m][n], 0, 0, 0); __builtin_amdgcn_s_setprio(0); } while (0)
; #define PG8_WAIT_V(n) asm volatile("s_waitcnt vmcnt(" #n ")" ::: "memory")
; #define PG8_WAIT_L(n) asm volatile("s_waitcnt lgkmcnt(" #n ")" ::: "memory")
; #define PG8_BAR __builtin_amdgcn_s_barrier()
; #define PG8_SCHED __builtin_amdgcn_sched_barrier(0)
; template <class Epi, bool ALIGN_EPI>
; __device__ __forceinline__ void gemm_phase(LAS unsigned char* lds, const Gemm g, const StaticOrder& S, const Epi& E) {
;     ...
;         for (int t = 0; t < nt; t += 2) {
;             const bool last = (t == nt - 2);
;             const char* a1 = cA + (size_t)(t + 1) * kstep;
;             const char* a2 = last ? nA : cA + (size_t)(t + 2) * kstep; const char* b2 = last ? nB : cB + (size_t)(t + 2) * kstep;
;             const char* a3 = a2 + kstep; const char* b3 = b2 + kstep;
;             PG8_LDB(B0, 0, 0); PG8_LDB(B1, 0, 1); PG8_SCHED; PG8_LDA(At, 0, 0); PG8_STAGE(PG8_SA(1, 1), a1 + hstepA, voffA);
;             PG8_WAIT_V(8); PG8_WAIT_L(0); PG8_BAR; PG8_MMA(0, 0, At, B0); PG8_MMA(0, 1, At, B1); PG8_BAR; PG8_SCHED;
;             PG8_LDA(At, 0, 1); PG8_STAGE(PG8_SB(0, 0), b2, voffB); PG8_STAGE(PG8_SB(0, 1), b2 + hstepB, voffB); PG8_STAGE(PG8_SA(0, 0), a2, voffA);
.LBB0_304:
	s_add_u32 s18, s6, 0xfffc0080
	s_addc_u32 s19, s7, -1
	s_add_i32 s41, 0, 0x10000
	s_cmp_eq_u32 s40, 12
	s_cselect_b32 s21, s1, s19
	s_cselect_b32 s20, s36, s18
	v_add_u32_e32 v152, s41, v144
	s_cselect_b32 s19, s11, s39
	s_cselect_b32 s18, s37, s38
	s_add_i32 s44, 0, 0x14000
	ds_read_b128 v[140:143], v152
	ds_read_b128 v[148:151], v152 offset:1024
	ds_read_b128 v[156:159], v152 offset:2048
	ds_read_b128 v[180:183], v152 offset:3072
	v_add_u32_e32 v152, s44, v144
	ds_read_b128 v[184:187], v152
	ds_read_b128 v[188:191], v152 offset:1024
	ds_read_b128 v[192:195], v152 offset:2048
	ds_read_b128 v[196:199], v152 offset:3072
	v_lshl_add_u64 v[152:153], s[6:7], 0, v[136:137]
	s_add_i32 m0, s25, 0xc000
	ds_read_b128 v[200:203], v146
	ds_read_b128 v[204:207], v146 offset:1024
	ds_read_b128 v[208:211], v146 offset:2048
	ds_read_b128 v[212:215], v146 offset:3072
	ds_read_b128 v[216:219], v146 offset:4096
	ds_read_b128 v[220:223], v146 offset:5120
	ds_read_b128 v[224:227], v146 offset:6144
	ds_read_b128 v[228:231], v146 offset:7168
	global_load_lds_dwordx4 v[152:153], off
	v_lshl_add_u64 v[152:153], s[6:7], 0, v[138:139]
	s_add_i32 m0, s25, 0xe000
	s_nop 0
	global_load_lds_dwordx4 v[152:153], off
	s_waitcnt vmcnt(8)
	s_waitcnt lgkmcnt(0)
	s_barrier
	s_waitcnt lgkmcnt(0)
	v_mfma_f32_16x16x32_bf16 v[126:129], v[140:143], v[200:203], v[126:129]
	v_mfma_f32_16x16x32_bf16 v[118:121], v[156:159], v[200:203], v[118:121]
	v_mfma_f32_16x16x32_bf16 v[110:113], v[140:143], v[208:211], v[110:113]
	v_mfma_f32_16x16x32_bf16 v[102:105], v[156:159], v[208:211], v[102:105]
	v_mfma_f32_16x16x32_bf16 v[94:97], v[140:143], v[216:219], v[94:97]
	v_mfma_f32_16x16x32_bf16 v[86:89], v[156:159], v[216:219], v[86:89]
	v_mfma_f32_16x16x32_bf16 v[78:81], v[140:143], v[224:227], v[78:81]
	v_mfma_f32_16x16x32_bf16 v[70:73], v[156:159], v[224:227], v[70:73]
	v_mfma_f32_16x16x32_bf16 v[126:129], v[148:151], v[204:207], v[126:129]
	v_mfma_f32_16x16x32_bf16 v[118:121], v[180:183], v[204:207], v[118:121]
	v_mfma_f32_16x16x32_bf16 v[110:113], v[148:151], v[212:215], v[110:113]
	v_mfma_f32_16x16x32_bf16 v[102:105], v[180:183], v[212:215], v[102:105]
	v_mfma_f32_16x16x32_bf16 v[94:97], v[148:151], v[220:223], v[94:97]
	v_mfma_f32_16x16x32_bf16 v[86:89], v[180:183], v[220:223], v[86:89]
	v_mfma_f32_16x16x32_bf16 v[78:81], v[148:151], v[228:231], v[78:81]
	v_mfma_f32_16x16x32_bf16 v[70:73], v[180:183], v[228:231], v[70:73]
	v_mfma_f32_16x16x32_bf16 v[122:125], v[184:187], v[200:203], v[122:125]
	v_mfma_f32_16x16x32_bf16 v[114:117], v[192:195], v[200:203], v[114:117]
	v_mfma_f32_16x16x32_bf16 v[106:109], v[184:187], v[208:211], v[106:109]
	v_mfma_f32_16x16x32_bf16 v[98:101], v[192:195], v[208:211], v[98:101]
	v_mfma_f32_16x16x32_bf16 v[90:93], v[184:187], v[216:219], v[90:93]
	v_mfma_f32_16x16x32_bf16 v[82:85], v[192:195], v[216:219], v[82:85]
	v_mfma_f32_16x16x32_bf16 v[74:77], v[184:187], v[224:227], v[74:77]
	v_mfma_f32_16x16x32_bf16 v[66:69], v[192:195], v[224:227], v[66:69]
	v_mfma_f32_16x16x32_bf16 v[122:125], v[188:191], v[204:207], v[122:125]
	v_mfma_f32_16x16x32_bf16 v[114:117], v[196:199], v[204:207], v[114:117]
	v_mfma_f32_16x16x32_bf16 v[106:109], v[188:191], v[212:215], v[106:109]
	v_mfma_f32_16x16x32_bf16 v[98:101], v[196:199], v[212:215], v[98:101]
	v_mfma_f32_16x16x32_bf16 v[90:93], v[188:191], v[220:223], v[90:93]
	v_mfma_f32_16x16x32_bf16 v[82:85], v[196:199], v[220:223], v[82:85]
	v_mfma_f32_16x16x32_bf16 v[74:77], v[188:191], v[228:231], v[74:77]
	v_mfma_f32_16x16x32_bf16 v[66:69], v[196:199], v[228:231], v[66:69]
	s_barrier
	s_add_i32 s41, s41, s24
	v_lshl_add_u64 v[152:153], s[18:19], 0, v[0:1]
	s_mov_b32 m0, s41
	ds_read_b128 v[200:203], v146 offset:16384
	ds_read_b128 v[204:207], v146 offset:17408
	ds_read_b128 v[208:211], v146 offset:18432
	ds_read_b128 v[212:215], v146 offset:19456
	ds_read_b128 v[216:219], v146 offset:20480
	ds_read_b128 v[220:223], v146 offset:21504
	ds_read_b128 v[224:227], v146 offset:22528
	ds_read_b128 v[228:231], v146 offset:23552
	global_load_lds_dwordx4 v[152:153], off
	s_add_i32 m0, s41, 0x2000
	s_add_u32 s42, s18, 0x40000
	v_lshl_add_u64 v[160:161], s[18:19], 0, v[130:131]
	s_addc_u32 s43, s19, 0
	s_add_i32 s41, s44, s24
	global_load_lds_dwordx4 v[160:161], off
	v_lshl_add_u64 v[162:163], s[42:43], 0, v[0:1]
	s_mov_b32 m0, s41
	v_lshl_add_u64 v[170:171], s[20:21], 0, v[132:133]
	global_load_lds_dwordx4 v[162:163], off
	v_lshl_add_u64 v[162:163], s[42:43], 0, v[130:131]
	s_add_i32 m0, s41, 0x2000
	s_nop 0
	global_load_lds_dwordx4 v[162:163], off
	v_lshl_add_u64 v[162:163], s[20:21], 0, v[134:135]
	s_mov_b32 m0, s25
	s_nop 0
	global_load_lds_dwordx4 v[162:163], off
	s_mov_b32 m0, s26
	s_nop 0
	global_load_lds_dwordx4 v[170:171], off
	s_waitcnt vmcnt(8)
	s_waitcnt lgkmcnt(0)
	s_barrier
; #define PG8_STAGE(bufoff, gbase, voff) do { _Pragma("unroll") for (int _i = 0; _i < 2; ++_i) \
;         __builtin_amdgcn_global_load_lds((const unsigned*)((const char*)(gbase) + (voff)[_i]), (LAS unsigned*)(lds + (bufoff) + ldsw + _i * 8192), 16, 0, 0); } while (0)
; #define PG8_LDA(dst, b, h) do { _Pragma("unroll") for (int m = 0; m < 4; ++m) _Pragma("unroll") for (int k = 0; k < 2; ++k) dst[m][k] = *(const LAS bf16x8*)(lds + PG8_SA(b, h) + aoff + m * 2048 + k * 1024); } while (0)
; #define PG8_LDB(dst, b, h) do { _Pragma("unroll") for (int n = 0; n < 2; ++n) _Pragma("unroll") for (int k = 0; k < 2; ++k) dst[n][k] = *(const LAS bf16x8*)(lds + PG8_SB(b, h) + boff + n * 2048 + k * 1024); } while (0)
; #define PG8_MMA(ai, bj, At, Bt) do { __builtin_amdgcn_s_setprio(1); _Pragma("unroll") for (int m = 0; m < 4; ++m) _Pragma("unroll") for (int n = 0; n < 2; ++n) _Pragma("unroll") for (int k = 0; k < 2; ++k) \
;         acc[ai][bj][m][n] = __builtin_amdgcn_mfma_f32_16x16x32_bf16(Bt[n][k], At[m][k], acc[ai][bj][m][n], 0, 0, 0); __builtin_amdgcn_s_setprio(0); } while (0)
; #define PG8_WAIT_V(n) asm volatile("s_waitcnt vmcnt(" #n ")" ::: "memory")
; #define PG8_WAIT_L(n) asm volatile("s_waitcnt lgkmcnt(" #n ")" ::: "memory")
; #define PG8_BAR __builtin_amdgcn_s_barrier()
; #define PG8_SCHED __builtin_amdgcn_sched_barrier(0)
; template <class Epi, bool ALIGN_EPI>
; __device__ __forceinline__ void gemm_phase(LAS unsigned char* lds, const Gemm g, const StaticOrder& S, const Epi& E) {
;     ...
;             PG8_WAIT_V(8); PG8_WAIT_L(0); PG8_BAR; PG8_MMA(1, 0, At, B0); PG8_MMA(1, 1, At, B1); PG8_BAR; PG8_SCHED;
;             PG8_LDB(B0, 1, 0); PG8_LDB(B1, 1, 1); PG8_SCHED; PG8_LDA(At, 1, 0); PG8_STAGE(PG8_SA(0, 1), a2 + hstepA, voffA);
;             PG8_WAIT_V(8); PG8_WAIT_L(0); PG8_BAR; PG8_MMA(0, 0, At, B0); PG8_MMA(0, 1, At, B1); PG8_BAR; PG8_SCHED;
	s_waitcnt lgkmcnt(0)
	v_mfma_f32_16x16x32_bf16 v[62:65], v[140:143], v[200:203], v[62:65]
	v_mfma_f32_16x16x32_bf16 v[54:57], v[156:159], v[200:203], v[54:57]
	v_mfma_f32_16x16x32_bf16 v[46:49], v[140:143], v[208:211], v[46:49]
	v_mfma_f32_16x16x32_bf16 v[38:41], v[156:159], v[208:211], v[38:41]
	v_mfma_f32_16x16x32_bf16 v[30:33], v[140:143], v[216:219], v[30:33]
	v_mfma_f32_16x16x32_bf16 v[22:25], v[156:159], v[216:219], v[22:25]
	v_mfma_f32_16x16x32_bf16 v[14:17], v[140:143], v[224:227], v[14:17]
	v_mfma_f32_16x16x32_bf16 v[6:9], v[156:159], v[224:227], v[6:9]
	v_mfma_f32_16x16x32_bf16 v[62:65], v[148:151], v[204:207], v[62:65]
	v_mfma_f32_16x16x32_bf16 v[54:57], v[180:183], v[204:207], v[54:57]
	v_mfma_f32_16x16x32_bf16 v[46:49], v[148:151], v[212:215], v[46:49]
	v_mfma_f32_16x16x32_bf16 v[38:41], v[180:183], v[212:215], v[38:41]
	v_mfma_f32_16x16x32_bf16 v[30:33], v[148:151], v[220:223], v[30:33]
	v_mfma_f32_16x16x32_bf16 v[22:25], v[180:183], v[220:223], v[22:25]
	v_mfma_f32_16x16x32_bf16 v[14:17], v[148:151], v[228:231], v[14:17]
	v_mfma_f32_16x16x32_bf16 v[6:9], v[180:183], v[228:231], v[6:9]
	v_mfma_f32_16x16x32_bf16 v[58:61], v[184:187], v[200:203], v[58:61]
	v_mfma_f32_16x16x32_bf16 v[50:53], v[192:195], v[200:203], v[50:53]
	v_mfma_f32_16x16x32_bf16 v[42:45], v[184:187], v[208:211], v[42:45]
	v_mfma_f32_16x16x32_bf16 v[34:37], v[192:195], v[208:211], v[34:37]
	v_mfma_f32_16x16x32_bf16 v[26:29], v[184:187], v[216:219], v[26:29]
	v_mfma_f32_16x16x32_bf16 v[18:21], v[192:195], v[216:219], v[18:21]
	v_mfma_f32_16x16x32_bf16 v[10:13], v[184:187], v[224:227], v[10:13]
	v_mfma_f32_16x16x32_bf16 v[2:5], v[192:195], v[224:227], v[2:5]
	v_mfma_f32_16x16x32_bf16 v[58:61], v[188:191], v[204:207], v[58:61]
	v_mfma_f32_16x16x32_bf16 v[50:53], v[196:199], v[204:207], v[50:53]
	v_mfma_f32_16x16x32_bf16 v[42:45], v[188:191], v[212:215], v[42:45]
	v_mfma_f32_16x16x32_bf16 v[34:37], v[196:199], v[212:215], v[34:37]
	v_mfma_f32_16x16x32_bf16 v[26:29], v[188:191], v[220:223], v[26:29]
	v_mfma_f32_16x16x32_bf16 v[18:21], v[196:199], v[220:223], v[18:21]
	v_mfma_f32_16x16x32_bf16 v[10:13], v[188:191], v[228:231], v[10:13]
	v_mfma_f32_16x16x32_bf16 v[2:5], v[196:199], v[228:231], v[2:5]
	s_barrier
	s_add_i32 s41, 0, 0x18000
	v_add_u32_e32 v164, s41, v144
	s_add_i32 s42, 0, 0x1c000
	ds_read_b128 v[140:143], v164
	ds_read_b128 v[148:151], v164 offset:1024
	ds_read_b128 v[156:159], v164 offset:2048
	ds_read_b128 v[180:183], v164 offset:3072
	v_add_u32_e32 v164, s42, v144
	ds_read_b128 v[184:187], v164
	ds_read_b128 v[188:191], v164 offset:1024
	ds_read_b128 v[192:195], v164 offset:2048
	ds_read_b128 v[196:199], v164 offset:3072
	s_add_u32 s20, s20, 0x40000
	s_addc_u32 s21, s21, 0
	s_mov_b32 m0, s27
	v_lshl_add_u64 v[172:173], s[20:21], 0, v[134:135]
	ds_read_b128 v[200:203], v146 offset:32768
	ds_read_b128 v[204:207], v146 offset:33792
	ds_read_b128 v[208:211], v146 offset:34816
	ds_read_b128 v[212:215], v146 offset:35840
	ds_read_b128 v[216:219], v146 offset:36864
	ds_read_b128 v[220:223], v146 offset:37888
	ds_read_b128 v[224:227], v146 offset:38912
	ds_read_b128 v[228:231], v146 offset:39936
	global_load_lds_dwordx4 v[172:173], off
	v_lshl_add_u64 v[172:173], s[20:21], 0, v[132:133]
	s_mov_b32 m0, s28
	s_nop 0
	global_load_lds_dwordx4 v[172:173], off
	s_waitcnt vmcnt(8)
	s_waitcnt lgkmcnt(0)
	s_barrier
	s_waitcnt lgkmcnt(0)
	v_mfma_f32_16x16x32_bf16 v[126:129], v[140:143], v[200:203], v[126:129]
	v_mfma_f32_16x16x32_bf16 v[118:121], v[156:159], v[200:203], v[118:121]
	v_mfma_f32_16x16x32_bf16 v[110:113], v[140:143], v[208:211], v[110:113]
	v_mfma_f32_16x16x32_bf16 v[102:105], v[156:159], v[208:211], v[102:105]
	v_mfma_f32_16x16x32_bf16 v[94:97], v[140:143], v[216:219], v[94:97]
	v_mfma_f32_16x16x32_bf16 v[86:89], v[156:159], v[216:219], v[86:89]
	v_mfma_f32_16x16x32_bf16 v[78:81], v[140:143], v[224:227], v[78:81]
	v_mfma_f32_16x16x32_bf16 v[70:73], v[156:159], v[224:227], v[70:73]
	v_mfma_f32_16x16x32_bf16 v[126:129], v[148:151], v[204:207], v[126:129]
	v_mfma_f32_16x16x32_bf16 v[118:121], v[180:183], v[204:207], v[118:121]
	v_mfma_f32_16x16x32_bf16 v[110:113], v[148:151], v[212:215], v[110:113]
	v_mfma_f32_16x16x32_bf16 v[102:105], v[180:183], v[212:215], v[102:105]
	v_mfma_f32_16x16x32_bf16 v[94:97], v[148:151], v[220:223], v[94:97]
	v_mfma_f32_16x16x32_bf16 v[86:89], v[180:183], v[220:223], v[86:89]
	v_mfma_f32_16x16x32_bf16 v[78:81], v[148:151], v[228:231], v[78:81]
	v_mfma_f32_16x16x32_bf16 v[70:73], v[180:183], v[228:231], v[70:73]
	v_mfma_f32_16x16x32_bf16 v[122:125], v[184:187], v[200:203], v[122:125]
	v_mfma_f32_16x16x32_bf16 v[114:117], v[192:195], v[200:203], v[114:117]
	v_mfma_f32_16x16x32_bf16 v[106:109], v[184:187], v[208:211], v[106:109]
	v_mfma_f32_16x16x32_bf16 v[98:101], v[192:195], v[208:211], v[98:101]
	v_mfma_f32_16x16x32_bf16 v[90:93], v[184:187], v[216:219], v[90:93]
	v_mfma_f32_16x16x32_bf16 v[82:85], v[192:195], v[216:219], v[82:85]
	v_mfma_f32_16x16x32_bf16 v[74:77], v[184:187], v[224:227], v[74:77]
	v_mfma_f32_16x16x32_bf16 v[66:69], v[192:195], v[224:227], v[66:69]
	v_mfma_f32_16x16x32_bf16 v[122:125], v[188:191], v[204:207], v[122:125]
	v_mfma_f32_16x16x32_bf16 v[114:117], v[196:199], v[204:207], v[114:117]
	v_mfma_f32_16x16x32_bf16 v[106:109], v[188:191], v[212:215], v[106:109]
	v_mfma_f32_16x16x32_bf16 v[98:101], v[196:199], v[212:215], v[98:101]
	v_mfma_f32_16x16x32_bf16 v[90:93], v[188:191], v[220:223], v[90:93]
	v_mfma_f32_16x16x32_bf16 v[82:85], v[196:199], v[220:223], v[82:85]
	v_mfma_f32_16x16x32_bf16 v[74:77], v[188:191], v[228:231], v[74:77]
	v_mfma_f32_16x16x32_bf16 v[66:69], v[196:199], v[228:231], v[66:69]
	s_barrier
; #define PG8_STAGE(bufoff, gbase, voff) do { _Pragma("unroll") for (int _i = 0; _i < 2; ++_i) \
;         __builtin_amdgcn_global_load_lds((const unsigned*)((const char*)(gbase) + (voff)[_i]), (LAS unsigned*)(lds + (bufoff) + ldsw + _i * 8192), 16, 0, 0); } while (0)
; #define PG8_LDA(dst, b, h) do { _Pragma("unroll") for (int m = 0; m < 4; ++m) _Pragma("unroll") for (int k = 0; k < 2; ++k) dst[m][k] = *(const LAS bf16x8*)(lds + PG8_SA(b, h) + aoff + m * 2048 + k * 1024); } while (0)
; #define PG8_MMA(ai, bj, At, Bt) do { __builtin_amdgcn_s_setprio(1); _Pragma("unroll") for (int m = 0; m < 4; ++m) _Pragma("unroll") for (int n = 0; n < 2; ++n) _Pragma("unroll") for (int k = 0; k < 2; ++k) \
;         acc[ai][bj][m][n] = __builtin_amdgcn_mfma_f32_16x16x32_bf16(Bt[n][k], At[m][k], acc[ai][bj][m][n], 0, 0, 0); __builtin_amdgcn_s_setprio(0); } while (0)
; #define PG8_WAIT_V(n) asm volatile("s_waitcnt vmcnt(" #n ")" ::: "memory")
; #define PG8_WAIT_L(n) asm volatile("s_waitcnt lgkmcnt(" #n ")" ::: "memory")
; #define PG8_BAR __builtin_amdgcn_s_barrier()
; #define PG8_SCHED __builtin_amdgcn_sched_barrier(0)
; template <class Epi, bool ALIGN_EPI>
; __device__ __forceinline__ void gemm_phase(LAS unsigned char* lds, const Gemm g, const StaticOrder& S, const Epi& E) {
;     ...
;             PG8_LDA(At, 1, 1); PG8_STAGE(PG8_SB(1, 0), b3, voffB); PG8_STAGE(PG8_SB(1, 1), b3 + hstepB, voffB); PG8_STAGE(PG8_SA(1, 0), a3, voffA);
;             PG8_WAIT_V(8); PG8_WAIT_L(0); PG8_BAR; PG8_MMA(1, 0, At, B0); PG8_MMA(1, 1, At, B1); PG8_BAR; PG8_SCHED;
	s_add_i32 s20, s41, s24
	v_lshl_add_u64 v[152:153], v[152:153], 0, s[94:95]
	s_mov_b32 m0, s20
	ds_read_b128 v[200:203], v146 offset:49152
	ds_read_b128 v[204:207], v146 offset:50176
	ds_read_b128 v[208:211], v146 offset:51200
	ds_read_b128 v[212:215], v146 offset:52224
	ds_read_b128 v[216:219], v146 offset:53248
	ds_read_b128 v[220:223], v146 offset:54272
	ds_read_b128 v[224:227], v146 offset:55296
	ds_read_b128 v[228:231], v146 offset:56320
	global_load_lds_dwordx4 v[152:153], off
	s_add_i32 m0, s20, 0x2000
	s_add_u32 s18, s18, 0x40080
	v_lshl_add_u64 v[152:153], v[160:161], 0, s[94:95]
	s_addc_u32 s19, s19, 0
	s_add_i32 s20, s42, s24
	global_load_lds_dwordx4 v[152:153], off
	v_lshl_add_u64 v[152:153], s[18:19], 0, v[0:1]
	s_mov_b32 m0, s20
	s_nop 0
	global_load_lds_dwordx4 v[152:153], off
	v_lshl_add_u64 v[152:153], s[18:19], 0, v[130:131]
	s_add_i32 m0, s20, 0x2000
	s_nop 0
	global_load_lds_dwordx4 v[152:153], off
	v_lshl_add_u64 v[152:153], v[162:163], 0, s[94:95]
	s_mov_b32 m0, s4
	s_nop 0
	global_load_lds_dwordx4 v[152:153], off
	v_lshl_add_u64 v[152:153], v[170:171], 0, s[94:95]
	s_mov_b32 m0, s29
	s_nop 0
	global_load_lds_dwordx4 v[152:153], off
	s_waitcnt vmcnt(8)
	s_waitcnt lgkmcnt(0)
	s_barrier
	s_waitcnt lgkmcnt(0)
	v_mfma_f32_16x16x32_bf16 v[62:65], v[140:143], v[200:203], v[62:65]
	v_mfma_f32_16x16x32_bf16 v[54:57], v[156:159], v[200:203], v[54:57]
	v_mfma_f32_16x16x32_bf16 v[46:49], v[140:143], v[208:211], v[46:49]
	v_mfma_f32_16x16x32_bf16 v[38:41], v[156:159], v[208:211], v[38:41]
	v_mfma_f32_16x16x32_bf16 v[30:33], v[140:143], v[216:219], v[30:33]
	v_mfma_f32_16x16x32_bf16 v[22:25], v[156:159], v[216:219], v[22:25]
	v_mfma_f32_16x16x32_bf16 v[14:17], v[140:143], v[224:227], v[14:17]
	v_mfma_f32_16x16x32_bf16 v[6:9], v[156:159], v[224:227], v[6:9]
	v_mfma_f32_16x16x32_bf16 v[62:65], v[148:151], v[204:207], v[62:65]
	v_mfma_f32_16x16x32_bf16 v[54:57], v[180:183], v[204:207], v[54:57]
	v_mfma_f32_16x16x32_bf16 v[46:49], v[148:151], v[212:215], v[46:49]
	v_mfma_f32_16x16x32_bf16 v[38:41], v[180:183], v[212:215], v[38:41]
	v_mfma_f32_16x16x32_bf16 v[30:33], v[148:151], v[220:223], v[30:33]
	v_mfma_f32_16x16x32_bf16 v[22:25], v[180:183], v[220:223], v[22:25]
	v_mfma_f32_16x16x32_bf16 v[14:17], v[148:151], v[228:231], v[14:17]
	v_mfma_f32_16x16x32_bf16 v[6:9], v[180:183], v[228:231], v[6:9]
	v_mfma_f32_16x16x32_bf16 v[58:61], v[184:187], v[200:203], v[58:61]
	v_mfma_f32_16x16x32_bf16 v[50:53], v[192:195], v[200:203], v[50:53]
	v_mfma_f32_16x16x32_bf16 v[42:45], v[184:187], v[208:211], v[42:45]
	v_mfma_f32_16x16x32_bf16 v[34:37], v[192:195], v[208:211], v[34:37]
	v_mfma_f32_16x16x32_bf16 v[26:29], v[184:187], v[216:219], v[26:29]
	v_mfma_f32_16x16x32_bf16 v[18:21], v[192:195], v[216:219], v[18:21]
	v_mfma_f32_16x16x32_bf16 v[10:13], v[184:187], v[224:227], v[10:13]
	v_mfma_f32_16x16x32_bf16 v[2:5], v[192:195], v[224:227], v[2:5]
	v_mfma_f32_16x16x32_bf16 v[58:61], v[188:191], v[204:207], v[58:61]
	v_mfma_f32_16x16x32_bf16 v[50:53], v[196:199], v[204:207], v[50:53]
	v_mfma_f32_16x16x32_bf16 v[42:45], v[188:191], v[212:215], v[42:45]
	v_mfma_f32_16x16x32_bf16 v[34:37], v[196:199], v[212:215], v[34:37]
	v_mfma_f32_16x16x32_bf16 v[26:29], v[188:191], v[220:223], v[26:29]
	v_mfma_f32_16x16x32_bf16 v[18:21], v[196:199], v[220:223], v[18:21]
	v_mfma_f32_16x16x32_bf16 v[10:13], v[188:191], v[228:231], v[10:13]
	v_mfma_f32_16x16x32_bf16 v[2:5], v[196:199], v[228:231], v[2:5]
	s_cmp_lg_u32 s40, 12
	s_cbranch_scc1 .Ltail_bar_8
	s_cmp_eq_u64 s[8:9], 0
	s_cbranch_scc1 .Ltail_skip_8

; #define PG8_BAR __builtin_amdgcn_s_barrier()
; template <class Epi, bool ALIGN_EPI>
; __device__ __forceinline__ void gemm_phase(LAS unsigned char* lds, const Gemm g, const StaticOrder& S, const Epi& E) {
;     ...
;         }
;         if constexpr (ALIGN_EPI) { if (wr == 0) PG8_BAR; }
.Ltail_skip_8:
	s_add_i32 s40, s40, 2
	s_add_u32 s6, s6, 0x100
	s_addc_u32 s7, s7, 0
	s_add_u32 s38, s38, 0x100
	s_addc_u32 s39, s39, 0
	s_cmp_gt_u32 s40, 13
	s_cbranch_scc0 .LBB0_304

; #define PG8_STAGE(bufoff, gbase, voff) do { _Pragma("unroll") for (int _i = 0; _i < 2; ++_i) \
;         __builtin_amdgcn_global_load_lds((const unsigned*)((const char*)(gbase) + (voff)[_i]), (LAS unsigned*)(lds + (bufoff) + ldsw + _i * 8192), 16, 0, 0); } while (0)
; #define PG8_LDA(dst, b, h) do { _Pragma("unroll") for (int m = 0; m < 4; ++m) _Pragma("unroll") for (int k = 0; k < 2; ++k) dst[m][k] = *(const LAS bf16x8*)(lds + PG8_SA(b, h) + aoff + m * 2048 + k * 1024); } while (0)
; #define PG8_LDB(dst, b, h) do { _Pragma("unroll") for (int n = 0; n < 2; ++n) _Pragma("unroll") for (int k = 0; k < 2; ++k) dst[n][k] = *(const LAS bf16x8*)(lds + PG8_SB(b, h) + boff + n * 2048 + k * 1024); } while (0)
; #define PG8_MMA(ai, bj, At, Bt) do { __builtin_amdgcn_s_setprio(1); _Pragma("unroll") for (int m = 0; m < 4; ++m) _Pragma("unroll") for (int n = 0; n < 2; ++n) _Pragma("unroll") for (int k = 0; k < 2; ++k) \
;         acc[ai][bj][m][n] = __builtin_amdgcn_mfma_f32_16x16x32_bf16(Bt[n][k], At[m][k], acc[ai][bj][m][n], 0, 0, 0); __builtin_amdgcn_s_setprio(0); } while (0)
; #define PG8_WAIT_V(n) asm volatile("s_waitcnt vmcnt(" #n ")" ::: "memory")
; #define PG8_WAIT_L(n) asm volatile("s_waitcnt lgkmcnt(" #n ")" ::: "memory")
; #define PG8_BAR __builtin_amdgcn_s_barrier()
; #define PG8_SCHED __builtin_amdgcn_sched_barrier(0)
; template <class Epi, bool ALIGN_EPI>
; __device__ __forceinline__ void gemm_phase(LAS unsigned char* lds, const Gemm g, const StaticOrder& S, const Epi& E) {
;     ...
;         for (int t = 0; t < nt; t += 2) {
;             const bool last = (t == nt - 2);
;             const char* a1 = cA + (size_t)(t + 1) * kstep;
;             const char* a2 = last ? nA : cA + (size_t)(t + 2) * kstep; const char* b2 = last ? nB : cB + (size_t)(t + 2) * kstep;
;             const char* a3 = a2 + kstep; const char* b3 = b2 + kstep;
;             PG8_LDB(B0, 0, 0); PG8_LDB(B1, 0, 1); PG8_SCHED; PG8_LDA(At, 0, 0); PG8_STAGE(PG8_SA(1, 1), a1 + hstepA, voffA);
;             PG8_WAIT_V(8); PG8_WAIT_L(0); PG8_BAR; PG8_MMA(0, 0, At, B0); PG8_MMA(0, 1, At, B1); PG8_BAR; PG8_SCHED;
;             PG8_LDA(At, 0, 1); PG8_STAGE(PG8_SB(0, 0), b2, voffB); PG8_STAGE(PG8_SB(0, 1), b2 + hstepB, voffB); PG8_STAGE(PG8_SA(0, 0), a2, voffA);
.LBB0_338:
	s_add_u32 s10, s8, 0x100
	s_addc_u32 s11, s9, 0
	s_add_i32 s42, 0, 0x10000
	s_cmp_eq_u32 s41, 12
	s_cselect_b32 s25, s17, s11
	s_cselect_b32 s24, s16, s10
	v_add_u32_e32 v144, s42, v146
	s_cselect_b32 s23, s15, s40
	s_cselect_b32 s22, s21, s39
	s_add_i32 s43, 0, 0x14000
	ds_read_b128 v[140:143], v144
	ds_read_b128 v[148:151], v144 offset:1024
	ds_read_b128 v[156:159], v144 offset:2048
	ds_read_b128 v[180:183], v144 offset:3072
	v_add_u32_e32 v144, s43, v146
	ds_read_b128 v[184:187], v144
	ds_read_b128 v[188:191], v144 offset:1024
	ds_read_b128 v[192:195], v144 offset:2048
	ds_read_b128 v[196:199], v144 offset:3072
	v_lshl_add_u64 v[144:145], s[8:9], 0, v[136:137]
	s_add_i32 m0, s29, 0xc000
	ds_read_b128 v[200:203], v147
	ds_read_b128 v[204:207], v147 offset:1024
	ds_read_b128 v[208:211], v147 offset:2048
	ds_read_b128 v[212:215], v147 offset:3072
	ds_read_b128 v[216:219], v147 offset:4096
	ds_read_b128 v[220:223], v147 offset:5120
	ds_read_b128 v[224:227], v147 offset:6144
	ds_read_b128 v[228:231], v147 offset:7168
	global_load_lds_dwordx4 v[144:145], off
	v_lshl_add_u64 v[144:145], s[8:9], 0, v[138:139]
	s_add_i32 m0, s29, 0xe000
	s_nop 0
	global_load_lds_dwordx4 v[144:145], off
	s_waitcnt vmcnt(8)
	s_waitcnt lgkmcnt(0)
	s_barrier
	s_waitcnt lgkmcnt(0)
	v_mfma_f32_16x16x32_bf16 v[126:129], v[140:143], v[200:203], v[126:129]
	v_mfma_f32_16x16x32_bf16 v[122:125], v[156:159], v[200:203], v[122:125]
	v_mfma_f32_16x16x32_bf16 v[110:113], v[140:143], v[208:211], v[110:113]
	v_mfma_f32_16x16x32_bf16 v[106:109], v[156:159], v[208:211], v[106:109]
	v_mfma_f32_16x16x32_bf16 v[94:97], v[140:143], v[216:219], v[94:97]
	v_mfma_f32_16x16x32_bf16 v[90:93], v[156:159], v[216:219], v[90:93]
	v_mfma_f32_16x16x32_bf16 v[78:81], v[140:143], v[224:227], v[78:81]
	v_mfma_f32_16x16x32_bf16 v[74:77], v[156:159], v[224:227], v[74:77]
	v_mfma_f32_16x16x32_bf16 v[126:129], v[148:151], v[204:207], v[126:129]
	v_mfma_f32_16x16x32_bf16 v[122:125], v[180:183], v[204:207], v[122:125]
	v_mfma_f32_16x16x32_bf16 v[110:113], v[148:151], v[212:215], v[110:113]
	v_mfma_f32_16x16x32_bf16 v[106:109], v[180:183], v[212:215], v[106:109]
	v_mfma_f32_16x16x32_bf16 v[94:97], v[148:151], v[220:223], v[94:97]
	v_mfma_f32_16x16x32_bf16 v[90:93], v[180:183], v[220:223], v[90:93]
	v_mfma_f32_16x16x32_bf16 v[78:81], v[148:151], v[228:231], v[78:81]
	v_mfma_f32_16x16x32_bf16 v[74:77], v[180:183], v[228:231], v[74:77]
	v_mfma_f32_16x16x32_bf16 v[118:121], v[184:187], v[200:203], v[118:121]
	v_mfma_f32_16x16x32_bf16 v[114:117], v[192:195], v[200:203], v[114:117]
	v_mfma_f32_16x16x32_bf16 v[102:105], v[184:187], v[208:211], v[102:105]
	v_mfma_f32_16x16x32_bf16 v[98:101], v[192:195], v[208:211], v[98:101]
	v_mfma_f32_16x16x32_bf16 v[86:89], v[184:187], v[216:219], v[86:89]
	v_mfma_f32_16x16x32_bf16 v[82:85], v[192:195], v[216:219], v[82:85]
	v_mfma_f32_16x16x32_bf16 v[70:73], v[184:187], v[224:227], v[70:73]
	v_mfma_f32_16x16x32_bf16 v[66:69], v[192:195], v[224:227], v[66:69]
	v_mfma_f32_16x16x32_bf16 v[118:121], v[188:191], v[204:207], v[118:121]
	v_mfma_f32_16x16x32_bf16 v[114:117], v[196:199], v[204:207], v[114:117]
	v_mfma_f32_16x16x32_bf16 v[102:105], v[188:191], v[212:215], v[102:105]
	v_mfma_f32_16x16x32_bf16 v[98:101], v[196:199], v[212:215], v[98:101]
	v_mfma_f32_16x16x32_bf16 v[86:89], v[188:191], v[220:223], v[86:89]
	v_mfma_f32_16x16x32_bf16 v[82:85], v[196:199], v[220:223], v[82:85]
	v_mfma_f32_16x16x32_bf16 v[70:73], v[188:191], v[228:231], v[70:73]
	v_mfma_f32_16x16x32_bf16 v[66:69], v[196:199], v[228:231], v[66:69]
	s_barrier
	s_add_i32 s8, s42, s28
	v_lshl_add_u64 v[144:145], s[22:23], 0, v[0:1]
	s_mov_b32 m0, s8
	ds_read_b128 v[200:203], v147 offset:16384
	ds_read_b128 v[204:207], v147 offset:17408
	ds_read_b128 v[208:211], v147 offset:18432
	ds_read_b128 v[212:215], v147 offset:19456
	ds_read_b128 v[216:219], v147 offset:20480
	ds_read_b128 v[220:223], v147 offset:21504
	ds_read_b128 v[224:227], v147 offset:22528
	ds_read_b128 v[228:231], v147 offset:23552
	global_load_lds_dwordx4 v[144:145], off
	s_add_i32 m0, s8, 0x2000
	s_add_u32 s8, s22, 0x40000
	v_lshl_add_u64 v[152:153], s[22:23], 0, v[134:135]
	s_addc_u32 s9, s23, 0
	s_add_i32 s42, s43, s28
	global_load_lds_dwordx4 v[152:153], off
	v_lshl_add_u64 v[160:161], s[8:9], 0, v[0:1]
	s_mov_b32 m0, s42
	v_lshl_add_u64 v[162:163], s[24:25], 0, v[132:133]
	global_load_lds_dwordx4 v[160:161], off
	v_lshl_add_u64 v[160:161], s[8:9], 0, v[134:135]
	s_add_i32 m0, s42, 0x2000
	s_nop 0
	global_load_lds_dwordx4 v[160:161], off
	v_lshl_add_u64 v[160:161], s[24:25], 0, v[130:131]
	s_mov_b32 m0, s29
	s_nop 0
	global_load_lds_dwordx4 v[160:161], off
	s_mov_b32 m0, s30
	s_nop 0
	global_load_lds_dwordx4 v[162:163], off
	s_waitcnt vmcnt(8)
	s_waitcnt lgkmcnt(0)
	s_barrier
; #define PG8_STAGE(bufoff, gbase, voff) do { _Pragma("unroll") for (int _i = 0; _i < 2; ++_i) \
;         __builtin_amdgcn_global_load_lds((const unsigned*)((const char*)(gbase) + (voff)[_i]), (LAS unsigned*)(lds + (bufoff) + ldsw + _i * 8192), 16, 0, 0); } while (0)
; #define PG8_LDA(dst, b, h) do { _Pragma("unroll") for (int m = 0; m < 4; ++m) _Pragma("unroll") for (int k = 0; k < 2; ++k) dst[m][k] = *(const LAS bf16x8*)(lds + PG8_SA(b, h) + aoff + m * 2048 + k * 1024); } while (0)
; #define PG8_LDB(dst, b, h) do { _Pragma("unroll") for (int n = 0; n < 2; ++n) _Pragma("unroll") for (int k = 0; k < 2; ++k) dst[n][k] = *(const LAS bf16x8*)(lds + PG8_SB(b, h) + boff + n * 2048 + k * 1024); } while (0)
; #define PG8_MMA(ai, bj, At, Bt) do { __builtin_amdgcn_s_setprio(1); _Pragma("unroll") for (int m = 0; m < 4; ++m) _Pragma("unroll") for (int n = 0; n < 2; ++n) _Pragma("unroll") for (int k = 0; k < 2; ++k) \
;         acc[ai][bj][m][n] = __builtin_amdgcn_mfma_f32_16x16x32_bf16(Bt[n][k], At[m][k], acc[ai][bj][m][n], 0, 0, 0); __builtin_amdgcn_s_setprio(0); } while (0)
; #define PG8_WAIT_V(n) asm volatile("s_waitcnt vmcnt(" #n ")" ::: "memory")
; #define PG8_WAIT_L(n) asm volatile("s_waitcnt lgkmcnt(" #n ")" ::: "memory")
; #define PG8_BAR __builtin_amdgcn_s_barrier()
; #define PG8_SCHED __builtin_amdgcn_sched_barrier(0)
; template <class Epi, bool ALIGN_EPI>
; __device__ __forceinline__ void gemm_phase(LAS unsigned char* lds, const Gemm g, const StaticOrder& S, const Epi& E) {
;     ...
;             PG8_WAIT_V(8); PG8_WAIT_L(0); PG8_BAR; PG8_MMA(1, 0, At, B0); PG8_MMA(1, 1, At, B1); PG8_BAR; PG8_SCHED;
;             PG8_LDB(B0, 1, 0); PG8_LDB(B1, 1, 1); PG8_SCHED; PG8_LDA(At, 1, 0); PG8_STAGE(PG8_SA(0, 1), a2 + hstepA, voffA);
;             PG8_WAIT_V(8); PG8_WAIT_L(0); PG8_BAR; PG8_MMA(0, 0, At, B0); PG8_MMA(0, 1, At, B1); PG8_BAR; PG8_SCHED;
	s_waitcnt lgkmcnt(0)
	v_mfma_f32_16x16x32_bf16 v[62:65], v[140:143], v[200:203], v[62:65]
	v_mfma_f32_16x16x32_bf16 v[58:61], v[156:159], v[200:203], v[58:61]
	v_mfma_f32_16x16x32_bf16 v[46:49], v[140:143], v[208:211], v[46:49]
	v_mfma_f32_16x16x32_bf16 v[42:45], v[156:159], v[208:211], v[42:45]
	v_mfma_f32_16x16x32_bf16 v[30:33], v[140:143], v[216:219], v[30:33]
	v_mfma_f32_16x16x32_bf16 v[26:29], v[156:159], v[216:219], v[26:29]
	v_mfma_f32_16x16x32_bf16 v[14:17], v[140:143], v[224:227], v[14:17]
	v_mfma_f32_16x16x32_bf16 v[10:13], v[156:159], v[224:227], v[10:13]
	v_mfma_f32_16x16x32_bf16 v[62:65], v[148:151], v[204:207], v[62:65]
	v_mfma_f32_16x16x32_bf16 v[58:61], v[180:183], v[204:207], v[58:61]
	v_mfma_f32_16x16x32_bf16 v[46:49], v[148:151], v[212:215], v[46:49]
	v_mfma_f32_16x16x32_bf16 v[42:45], v[180:183], v[212:215], v[42:45]
	v_mfma_f32_16x16x32_bf16 v[30:33], v[148:151], v[220:223], v[30:33]
	v_mfma_f32_16x16x32_bf16 v[26:29], v[180:183], v[220:223], v[26:29]
	v_mfma_f32_16x16x32_bf16 v[14:17], v[148:151], v[228:231], v[14:17]
	v_mfma_f32_16x16x32_bf16 v[10:13], v[180:183], v[228:231], v[10:13]
	v_mfma_f32_16x16x32_bf16 v[54:57], v[184:187], v[200:203], v[54:57]
	v_mfma_f32_16x16x32_bf16 v[50:53], v[192:195], v[200:203], v[50:53]
	v_mfma_f32_16x16x32_bf16 v[38:41], v[184:187], v[208:211], v[38:41]
	v_mfma_f32_16x16x32_bf16 v[34:37], v[192:195], v[208:211], v[34:37]
	v_mfma_f32_16x16x32_bf16 v[22:25], v[184:187], v[216:219], v[22:25]
	v_mfma_f32_16x16x32_bf16 v[18:21], v[192:195], v[216:219], v[18:21]
	v_mfma_f32_16x16x32_bf16 v[6:9], v[184:187], v[224:227], v[6:9]
	v_mfma_f32_16x16x32_bf16 v[2:5], v[192:195], v[224:227], v[2:5]
	v_mfma_f32_16x16x32_bf16 v[54:57], v[188:191], v[204:207], v[54:57]
	v_mfma_f32_16x16x32_bf16 v[50:53], v[196:199], v[204:207], v[50:53]
	v_mfma_f32_16x16x32_bf16 v[38:41], v[188:191], v[212:215], v[38:41]
	v_mfma_f32_16x16x32_bf16 v[34:37], v[196:199], v[212:215], v[34:37]
	v_mfma_f32_16x16x32_bf16 v[22:25], v[188:191], v[220:223], v[22:25]
	v_mfma_f32_16x16x32_bf16 v[18:21], v[196:199], v[220:223], v[18:21]
	v_mfma_f32_16x16x32_bf16 v[6:9], v[188:191], v[228:231], v[6:9]
	v_mfma_f32_16x16x32_bf16 v[2:5], v[196:199], v[228:231], v[2:5]
	s_barrier
	s_add_i32 s42, 0, 0x18000
	v_add_u32_e32 v164, s42, v146
	s_add_i32 s43, 0, 0x1c000
	ds_read_b128 v[140:143], v164
	ds_read_b128 v[148:151], v164 offset:1024
	ds_read_b128 v[156:159], v164 offset:2048
	ds_read_b128 v[180:183], v164 offset:3072
	v_add_u32_e32 v164, s43, v146
	ds_read_b128 v[184:187], v164
	ds_read_b128 v[188:191], v164 offset:1024
	ds_read_b128 v[192:195], v164 offset:2048
	ds_read_b128 v[196:199], v164 offset:3072
	s_add_u32 s8, s24, 0x160000
	s_addc_u32 s9, s25, 0
	s_mov_b32 m0, s31
	v_lshl_add_u64 v[170:171], s[8:9], 0, v[130:131]
	ds_read_b128 v[200:203], v147 offset:32768
	ds_read_b128 v[204:207], v147 offset:33792
	ds_read_b128 v[208:211], v147 offset:34816
	ds_read_b128 v[212:215], v147 offset:35840
	ds_read_b128 v[216:219], v147 offset:36864
	ds_read_b128 v[220:223], v147 offset:37888
	ds_read_b128 v[224:227], v147 offset:38912
	ds_read_b128 v[228:231], v147 offset:39936
	global_load_lds_dwordx4 v[170:171], off
	v_lshl_add_u64 v[170:171], s[8:9], 0, v[132:133]
	s_mov_b32 m0, s34
	s_nop 0
	global_load_lds_dwordx4 v[170:171], off
	s_waitcnt vmcnt(8)
	s_waitcnt lgkmcnt(0)
	s_barrier
	s_waitcnt lgkmcnt(0)
	v_mfma_f32_16x16x32_bf16 v[126:129], v[140:143], v[200:203], v[126:129]
	v_mfma_f32_16x16x32_bf16 v[122:125], v[156:159], v[200:203], v[122:125]
	v_mfma_f32_16x16x32_bf16 v[110:113], v[140:143], v[208:211], v[110:113]
	v_mfma_f32_16x16x32_bf16 v[106:109], v[156:159], v[208:211], v[106:109]
	v_mfma_f32_16x16x32_bf16 v[94:97], v[140:143], v[216:219], v[94:97]
	v_mfma_f32_16x16x32_bf16 v[90:93], v[156:159], v[216:219], v[90:93]
	v_mfma_f32_16x16x32_bf16 v[78:81], v[140:143], v[224:227], v[78:81]
	v_mfma_f32_16x16x32_bf16 v[74:77], v[156:159], v[224:227], v[74:77]
	v_mfma_f32_16x16x32_bf16 v[126:129], v[148:151], v[204:207], v[126:129]
	v_mfma_f32_16x16x32_bf16 v[122:125], v[180:183], v[204:207], v[122:125]
	v_mfma_f32_16x16x32_bf16 v[110:113], v[148:151], v[212:215], v[110:113]
	v_mfma_f32_16x16x32_bf16 v[106:109], v[180:183], v[212:215], v[106:109]
	v_mfma_f32_16x16x32_bf16 v[94:97], v[148:151], v[220:223], v[94:97]
	v_mfma_f32_16x16x32_bf16 v[90:93], v[180:183], v[220:223], v[90:93]
	v_mfma_f32_16x16x32_bf16 v[78:81], v[148:151], v[228:231], v[78:81]
	v_mfma_f32_16x16x32_bf16 v[74:77], v[180:183], v[228:231], v[74:77]
	v_mfma_f32_16x16x32_bf16 v[118:121], v[184:187], v[200:203], v[118:121]
	v_mfma_f32_16x16x32_bf16 v[114:117], v[192:195], v[200:203], v[114:117]
	v_mfma_f32_16x16x32_bf16 v[102:105], v[184:187], v[208:211], v[102:105]
	v_mfma_f32_16x16x32_bf16 v[98:101], v[192:195], v[208:211], v[98:101]
	v_mfma_f32_16x16x32_bf16 v[86:89], v[184:187], v[216:219], v[86:89]
	v_mfma_f32_16x16x32_bf16 v[82:85], v[192:195], v[216:219], v[82:85]
	v_mfma_f32_16x16x32_bf16 v[70:73], v[184:187], v[224:227], v[70:73]
	v_mfma_f32_16x16x32_bf16 v[66:69], v[192:195], v[224:227], v[66:69]
	v_mfma_f32_16x16x32_bf16 v[118:121], v[188:191], v[204:207], v[118:121]
	v_mfma_f32_16x16x32_bf16 v[114:117], v[196:199], v[204:207], v[114:117]
	v_mfma_f32_16x16x32_bf16 v[102:105], v[188:191], v[212:215], v[102:105]
	v_mfma_f32_16x16x32_bf16 v[98:101], v[196:199], v[212:215], v[98:101]
	v_mfma_f32_16x16x32_bf16 v[86:89], v[188:191], v[220:223], v[86:89]
	v_mfma_f32_16x16x32_bf16 v[82:85], v[196:199], v[220:223], v[82:85]
	v_mfma_f32_16x16x32_bf16 v[70:73], v[188:191], v[228:231], v[70:73]
	v_mfma_f32_16x16x32_bf16 v[66:69], v[196:199], v[228:231], v[66:69]
	s_barrier
; #define PG8_STAGE(bufoff, gbase, voff) do { _Pragma("unroll") for (int _i = 0; _i < 2; ++_i) \
;         __builtin_amdgcn_global_load_lds((const unsigned*)((const char*)(gbase) + (voff)[_i]), (LAS unsigned*)(lds + (bufoff) + ldsw + _i * 8192), 16, 0, 0); } while (0)
; #define PG8_LDA(dst, b, h) do { _Pragma("unroll") for (int m = 0; m < 4; ++m) _Pragma("unroll") for (int k = 0; k < 2; ++k) dst[m][k] = *(const LAS bf16x8*)(lds + PG8_SA(b, h) + aoff + m * 2048 + k * 1024); } while (0)
; #define PG8_MMA(ai, bj, At, Bt) do { __builtin_amdgcn_s_setprio(1); _Pragma("unroll") for (int m = 0; m < 4; ++m) _Pragma("unroll") for (int n = 0; n < 2; ++n) _Pragma("unroll") for (int k = 0; k < 2; ++k) \
;         acc[ai][bj][m][n] = __builtin_amdgcn_mfma_f32_16x16x32_bf16(Bt[n][k], At[m][k], acc[ai][bj][m][n], 0, 0, 0); __builtin_amdgcn_s_setprio(0); } while (0)
; #define PG8_WAIT_V(n) asm volatile("s_waitcnt vmcnt(" #n ")" ::: "memory")
; #define PG8_WAIT_L(n) asm volatile("s_waitcnt lgkmcnt(" #n ")" ::: "memory")
; #define PG8_BAR __builtin_amdgcn_s_barrier()
; #define PG8_SCHED __builtin_amdgcn_sched_barrier(0)
; template <class Epi, bool ALIGN_EPI>
; __device__ __forceinline__ void gemm_phase(LAS unsigned char* lds, const Gemm g, const StaticOrder& S, const Epi& E) {
;     ...
;             PG8_LDA(At, 1, 1); PG8_STAGE(PG8_SB(1, 0), b3, voffB); PG8_STAGE(PG8_SB(1, 1), b3 + hstepB, voffB); PG8_STAGE(PG8_SA(1, 0), a3, voffA);
;             PG8_WAIT_V(8); PG8_WAIT_L(0); PG8_BAR; PG8_MMA(1, 0, At, B0); PG8_MMA(1, 1, At, B1); PG8_BAR; PG8_SCHED;
	s_add_i32 s8, s42, s28
	v_lshl_add_u64 v[144:145], v[144:145], 0, s[94:95]
	s_mov_b32 m0, s8
	ds_read_b128 v[200:203], v147 offset:49152
	ds_read_b128 v[204:207], v147 offset:50176
	ds_read_b128 v[208:211], v147 offset:51200
	ds_read_b128 v[212:215], v147 offset:52224
	ds_read_b128 v[216:219], v147 offset:53248
	ds_read_b128 v[220:223], v147 offset:54272
	ds_read_b128 v[224:227], v147 offset:55296
	ds_read_b128 v[228:231], v147 offset:56320
	global_load_lds_dwordx4 v[144:145], off
	s_add_i32 m0, s8, 0x2000
	s_add_u32 s8, s22, 0x40080
	v_lshl_add_u64 v[144:145], v[152:153], 0, s[94:95]
	s_addc_u32 s9, s23, 0
	s_add_i32 s22, s43, s28
	global_load_lds_dwordx4 v[144:145], off
	v_lshl_add_u64 v[144:145], s[8:9], 0, v[0:1]
	s_mov_b32 m0, s22
	s_nop 0
	global_load_lds_dwordx4 v[144:145], off
	v_lshl_add_u64 v[144:145], s[8:9], 0, v[134:135]
	s_add_i32 m0, s22, 0x2000
	s_nop 0
	global_load_lds_dwordx4 v[144:145], off
	v_lshl_add_u64 v[144:145], v[160:161], 0, s[94:95]
	s_mov_b32 m0, s35
	s_nop 0
	global_load_lds_dwordx4 v[144:145], off
	v_lshl_add_u64 v[144:145], v[162:163], 0, s[94:95]
	s_mov_b32 m0, s36
	s_nop 0
	global_load_lds_dwordx4 v[144:145], off
	s_waitcnt vmcnt(8)
	s_waitcnt lgkmcnt(0)
	s_barrier
	s_waitcnt lgkmcnt(0)
	v_mfma_f32_16x16x32_bf16 v[62:65], v[140:143], v[200:203], v[62:65]
	v_mfma_f32_16x16x32_bf16 v[58:61], v[156:159], v[200:203], v[58:61]
	v_mfma_f32_16x16x32_bf16 v[46:49], v[140:143], v[208:211], v[46:49]
	v_mfma_f32_16x16x32_bf16 v[42:45], v[156:159], v[208:211], v[42:45]
	v_mfma_f32_16x16x32_bf16 v[30:33], v[140:143], v[216:219], v[30:33]
	v_mfma_f32_16x16x32_bf16 v[26:29], v[156:159], v[216:219], v[26:29]
	v_mfma_f32_16x16x32_bf16 v[14:17], v[140:143], v[224:227], v[14:17]
	v_mfma_f32_16x16x32_bf16 v[10:13], v[156:159], v[224:227], v[10:13]
	v_mfma_f32_16x16x32_bf16 v[62:65], v[148:151], v[204:207], v[62:65]
	v_mfma_f32_16x16x32_bf16 v[58:61], v[180:183], v[204:207], v[58:61]
	v_mfma_f32_16x16x32_bf16 v[46:49], v[148:151], v[212:215], v[46:49]
	v_mfma_f32_16x16x32_bf16 v[42:45], v[180:183], v[212:215], v[42:45]
	v_mfma_f32_16x16x32_bf16 v[30:33], v[148:151], v[220:223], v[30:33]
	v_mfma_f32_16x16x32_bf16 v[26:29], v[180:183], v[220:223], v[26:29]
	v_mfma_f32_16x16x32_bf16 v[14:17], v[148:151], v[228:231], v[14:17]
	v_mfma_f32_16x16x32_bf16 v[10:13], v[180:183], v[228:231], v[10:13]
	v_mfma_f32_16x16x32_bf16 v[54:57], v[184:187], v[200:203], v[54:57]
	v_mfma_f32_16x16x32_bf16 v[50:53], v[192:195], v[200:203], v[50:53]
	v_mfma_f32_16x16x32_bf16 v[38:41], v[184:187], v[208:211], v[38:41]
	v_mfma_f32_16x16x32_bf16 v[34:37], v[192:195], v[208:211], v[34:37]
	v_mfma_f32_16x16x32_bf16 v[22:25], v[184:187], v[216:219], v[22:25]
	v_mfma_f32_16x16x32_bf16 v[18:21], v[192:195], v[216:219], v[18:21]
	v_mfma_f32_16x16x32_bf16 v[6:9], v[184:187], v[224:227], v[6:9]
	v_mfma_f32_16x16x32_bf16 v[2:5], v[192:195], v[224:227], v[2:5]
	v_mfma_f32_16x16x32_bf16 v[54:57], v[188:191], v[204:207], v[54:57]
	v_mfma_f32_16x16x32_bf16 v[50:53], v[196:199], v[204:207], v[50:53]
	v_mfma_f32_16x16x32_bf16 v[38:41], v[188:191], v[212:215], v[38:41]
	v_mfma_f32_16x16x32_bf16 v[34:37], v[196:199], v[212:215], v[34:37]
	v_mfma_f32_16x16x32_bf16 v[22:25], v[188:191], v[220:223], v[22:25]
	v_mfma_f32_16x16x32_bf16 v[18:21], v[196:199], v[220:223], v[18:21]
	v_mfma_f32_16x16x32_bf16 v[6:9], v[188:191], v[228:231], v[6:9]
	v_mfma_f32_16x16x32_bf16 v[2:5], v[196:199], v[228:231], v[2:5]
	s_cmp_lg_u32 s41, 12
	s_cbranch_scc1 .Ltail_bar_7
	s_cmp_eq_u64 s[2:3], 0
	s_cbranch_scc1 .Ltail_skip_7

; #define PG8_BAR __builtin_amdgcn_s_barrier()
; template <class Epi, bool ALIGN_EPI>
; __device__ __forceinline__ void gemm_phase(LAS unsigned char* lds, const Gemm g, const StaticOrder& S, const Epi& E) {
;     ...
;         }
;         if constexpr (ALIGN_EPI) { if (wr == 0) PG8_BAR; }
.Ltail_skip_7:
	s_add_i32 s41, s41, 2
	s_add_u32 s39, s39, 0x100
	s_addc_u32 s40, s40, 0
	s_cmp_gt_u32 s41, 13
	s_mov_b64 s[8:9], s[10:11]
	s_cbranch_scc0 .LBB0_338

; #define PG8_STAGE(bufoff, gbase, voff) do { _Pragma("unroll") for (int _i = 0; _i < 2; ++_i) \
;         __builtin_amdgcn_global_load_lds((const unsigned*)((const char*)(gbase) + (voff)[_i]), (LAS unsigned*)(lds + (bufoff) + ldsw + _i * 8192), 16, 0, 0); } while (0)
; #define PG8_LDA(dst, b, h) do { _Pragma("unroll") for (int m = 0; m < 4; ++m) _Pragma("unroll") for (int k = 0; k < 2; ++k) dst[m][k] = *(const LAS bf16x8*)(lds + PG8_SA(b, h) + aoff + m * 2048 + k * 1024); } while (0)
; #define PG8_LDB(dst, b, h) do { _Pragma("unroll") for (int n = 0; n < 2; ++n) _Pragma("unroll") for (int k = 0; k < 2; ++k) dst[n][k] = *(const LAS bf16x8*)(lds + PG8_SB(b, h) + boff + n * 2048 + k * 1024); } while (0)
; #define PG8_MMA(ai, bj, At, Bt) do { __builtin_amdgcn_s_setprio(1); _Pragma("unroll") for (int m = 0; m < 4; ++m) _Pragma("unroll") for (int n = 0; n < 2; ++n) _Pragma("unroll") for (int k = 0; k < 2; ++k) \
;         acc[ai][bj][m][n] = __builtin_amdgcn_mfma_f32_16x16x32_bf16(Bt[n][k], At[m][k], acc[ai][bj][m][n], 0, 0, 0); __builtin_amdgcn_s_setprio(0); } while (0)
; #define PG8_WAIT_V(n) asm volatile("s_waitcnt vmcnt(" #n ")" ::: "memory")
; #define PG8_WAIT_L(n) asm volatile("s_waitcnt lgkmcnt(" #n ")" ::: "memory")
; #define PG8_BAR __builtin_amdgcn_s_barrier()
; #define PG8_SCHED __builtin_amdgcn_sched_barrier(0)
; template <class Epi, bool ALIGN_EPI>
; __device__ __forceinline__ void gemm_phase(LAS unsigned char* lds, const Gemm g, const StaticOrder& S, const Epi& E) {
;     ...
;         for (int t = 0; t < nt; t += 2) {
;             const bool last = (t == nt - 2);
;             const char* a1 = cA + (size_t)(t + 1) * kstep;
;             const char* a2 = last ? nA : cA + (size_t)(t + 2) * kstep; const char* b2 = last ? nB : cB + (size_t)(t + 2) * kstep;
;             const char* a3 = a2 + kstep; const char* b3 = b2 + kstep;
;             PG8_LDB(B0, 0, 0); PG8_LDB(B1, 0, 1); PG8_SCHED; PG8_LDA(At, 0, 0); PG8_STAGE(PG8_SA(1, 1), a1 + hstepA, voffA);
;             PG8_WAIT_V(8); PG8_WAIT_L(0); PG8_BAR; PG8_MMA(0, 0, At, B0); PG8_MMA(0, 1, At, B1); PG8_BAR; PG8_SCHED;
;             PG8_LDA(At, 0, 1); PG8_STAGE(PG8_SB(0, 0), b2, voffB); PG8_STAGE(PG8_SB(0, 1), b2 + hstepB, voffB); PG8_STAGE(PG8_SA(0, 0), a2, voffA);
.LBB0_414:
	s_add_u32 s2, s0, 0x100
	s_addc_u32 s3, s1, 0
	s_add_i32 s44, 0, 0x10000
	s_cmp_eq_u32 s43, 12
	s_cselect_b32 s23, s17, s3
	s_cselect_b32 s22, s16, s2
	v_add_u32_e32 v144, s44, v146
	s_cselect_b32 s21, s15, s42
	s_cselect_b32 s20, s40, s41
	s_add_i32 s45, 0, 0x14000
	ds_read_b128 v[140:143], v144
	ds_read_b128 v[148:151], v144 offset:1024
	ds_read_b128 v[156:159], v144 offset:2048
	ds_read_b128 v[180:183], v144 offset:3072
	v_add_u32_e32 v144, s45, v146
	ds_read_b128 v[184:187], v144
	ds_read_b128 v[188:191], v144 offset:1024
	ds_read_b128 v[192:195], v144 offset:2048
	ds_read_b128 v[196:199], v144 offset:3072
	v_lshl_add_u64 v[144:145], s[0:1], 0, v[136:137]
	s_add_i32 m0, s29, 0xc000
	ds_read_b128 v[200:203], v147
	ds_read_b128 v[204:207], v147 offset:1024
	ds_read_b128 v[208:211], v147 offset:2048
	ds_read_b128 v[212:215], v147 offset:3072
	ds_read_b128 v[216:219], v147 offset:4096
	ds_read_b128 v[220:223], v147 offset:5120
	ds_read_b128 v[224:227], v147 offset:6144
	ds_read_b128 v[228:231], v147 offset:7168
	global_load_lds_dwordx4 v[144:145], off
	v_lshl_add_u64 v[144:145], s[0:1], 0, v[138:139]
	s_add_i32 m0, s29, 0xe000
	s_nop 0
	global_load_lds_dwordx4 v[144:145], off
	s_waitcnt vmcnt(8)
	s_waitcnt lgkmcnt(0)
	s_barrier
	s_waitcnt lgkmcnt(0)
	v_mfma_f32_16x16x32_bf16 v[126:129], v[140:143], v[200:203], v[126:129]
	v_mfma_f32_16x16x32_bf16 v[122:125], v[156:159], v[200:203], v[122:125]
	v_mfma_f32_16x16x32_bf16 v[110:113], v[140:143], v[208:211], v[110:113]
	v_mfma_f32_16x16x32_bf16 v[106:109], v[156:159], v[208:211], v[106:109]
	v_mfma_f32_16x16x32_bf16 v[94:97], v[140:143], v[216:219], v[94:97]
	v_mfma_f32_16x16x32_bf16 v[90:93], v[156:159], v[216:219], v[90:93]
	v_mfma_f32_16x16x32_bf16 v[78:81], v[140:143], v[224:227], v[78:81]
	v_mfma_f32_16x16x32_bf16 v[74:77], v[156:159], v[224:227], v[74:77]
	v_mfma_f32_16x16x32_bf16 v[126:129], v[148:151], v[204:207], v[126:129]
	v_mfma_f32_16x16x32_bf16 v[122:125], v[180:183], v[204:207], v[122:125]
	v_mfma_f32_16x16x32_bf16 v[110:113], v[148:151], v[212:215], v[110:113]
	v_mfma_f32_16x16x32_bf16 v[106:109], v[180:183], v[212:215], v[106:109]
	v_mfma_f32_16x16x32_bf16 v[94:97], v[148:151], v[220:223], v[94:97]
	v_mfma_f32_16x16x32_bf16 v[90:93], v[180:183], v[220:223], v[90:93]
	v_mfma_f32_16x16x32_bf16 v[78:81], v[148:151], v[228:231], v[78:81]
	v_mfma_f32_16x16x32_bf16 v[74:77], v[180:183], v[228:231], v[74:77]
	v_mfma_f32_16x16x32_bf16 v[118:121], v[184:187], v[200:203], v[118:121]
	v_mfma_f32_16x16x32_bf16 v[114:117], v[192:195], v[200:203], v[114:117]
	v_mfma_f32_16x16x32_bf16 v[102:105], v[184:187], v[208:211], v[102:105]
	v_mfma_f32_16x16x32_bf16 v[98:101], v[192:195], v[208:211], v[98:101]
	v_mfma_f32_16x16x32_bf16 v[86:89], v[184:187], v[216:219], v[86:89]
	v_mfma_f32_16x16x32_bf16 v[82:85], v[192:195], v[216:219], v[82:85]
	v_mfma_f32_16x16x32_bf16 v[70:73], v[184:187], v[224:227], v[70:73]
	v_mfma_f32_16x16x32_bf16 v[66:69], v[192:195], v[224:227], v[66:69]
	v_mfma_f32_16x16x32_bf16 v[118:121], v[188:191], v[204:207], v[118:121]
	v_mfma_f32_16x16x32_bf16 v[114:117], v[196:199], v[204:207], v[114:117]
	v_mfma_f32_16x16x32_bf16 v[102:105], v[188:191], v[212:215], v[102:105]
	v_mfma_f32_16x16x32_bf16 v[98:101], v[196:199], v[212:215], v[98:101]
	v_mfma_f32_16x16x32_bf16 v[86:89], v[188:191], v[220:223], v[86:89]
	v_mfma_f32_16x16x32_bf16 v[82:85], v[196:199], v[220:223], v[82:85]
	v_mfma_f32_16x16x32_bf16 v[70:73], v[188:191], v[228:231], v[70:73]
	v_mfma_f32_16x16x32_bf16 v[66:69], v[196:199], v[228:231], v[66:69]
	s_barrier
	s_add_i32 s0, s44, s28
	v_lshl_add_u64 v[144:145], s[20:21], 0, v[0:1]
	s_mov_b32 m0, s0
	ds_read_b128 v[200:203], v147 offset:16384
	ds_read_b128 v[204:207], v147 offset:17408
	ds_read_b128 v[208:211], v147 offset:18432
	ds_read_b128 v[212:215], v147 offset:19456
	ds_read_b128 v[216:219], v147 offset:20480
	ds_read_b128 v[220:223], v147 offset:21504
	ds_read_b128 v[224:227], v147 offset:22528
	ds_read_b128 v[228:231], v147 offset:23552
	global_load_lds_dwordx4 v[144:145], off
	s_add_i32 m0, s0, 0x2000
	s_add_u32 s0, s20, 0x40000
	v_lshl_add_u64 v[152:153], s[20:21], 0, v[134:135]
	s_addc_u32 s1, s21, 0
	s_add_i32 s44, s45, s28
	global_load_lds_dwordx4 v[152:153], off
	v_lshl_add_u64 v[160:161], s[0:1], 0, v[0:1]
	s_mov_b32 m0, s44
	v_lshl_add_u64 v[162:163], s[22:23], 0, v[132:133]
	global_load_lds_dwordx4 v[160:161], off
	v_lshl_add_u64 v[160:161], s[0:1], 0, v[134:135]
	s_add_i32 m0, s44, 0x2000
	s_nop 0
	global_load_lds_dwordx4 v[160:161], off
	v_lshl_add_u64 v[160:161], s[22:23], 0, v[130:131]
	s_mov_b32 m0, s29
	s_nop 0
	global_load_lds_dwordx4 v[160:161], off
	s_mov_b32 m0, s30
	s_nop 0
	global_load_lds_dwordx4 v[162:163], off
	s_waitcnt vmcnt(8)
	s_waitcnt lgkmcnt(0)
	s_barrier
; #define PG8_STAGE(bufoff, gbase, voff) do { _Pragma("unroll") for (int _i = 0; _i < 2; ++_i) \
;         __builtin_amdgcn_global_load_lds((const unsigned*)((const char*)(gbase) + (voff)[_i]), (LAS unsigned*)(lds + (bufoff) + ldsw + _i * 8192), 16, 0, 0); } while (0)
; #define PG8_LDA(dst, b, h) do { _Pragma("unroll") for (int m = 0; m < 4; ++m) _Pragma("unroll") for (int k = 0; k < 2; ++k) dst[m][k] = *(const LAS bf16x8*)(lds + PG8_SA(b, h) + aoff + m * 2048 + k * 1024); } while (0)
; #define PG8_LDB(dst, b, h) do { _Pragma("unroll") for (int n = 0; n < 2; ++n) _Pragma("unroll") for (int k = 0; k < 2; ++k) dst[n][k] = *(const LAS bf16x8*)(lds + PG8_SB(b, h) + boff + n * 2048 + k * 1024); } while (0)
; #define PG8_MMA(ai, bj, At, Bt) do { __builtin_amdgcn_s_setprio(1); _Pragma("unroll") for (int m = 0; m < 4; ++m) _Pragma("unroll") for (int n = 0; n < 2; ++n) _Pragma("unroll") for (int k = 0; k < 2; ++k) \
;         acc[ai][bj][m][n] = __builtin_amdgcn_mfma_f32_16x16x32_bf16(Bt[n][k], At[m][k], acc[ai][bj][m][n], 0, 0, 0); __builtin_amdgcn_s_setprio(0); } while (0)
; #define PG8_WAIT_V(n) asm volatile("s_waitcnt vmcnt(" #n ")" ::: "memory")
; #define PG8_WAIT_L(n) asm volatile("s_waitcnt lgkmcnt(" #n ")" ::: "memory")
; #define PG8_BAR __builtin_amdgcn_s_barrier()
; #define PG8_SCHED __builtin_amdgcn_sched_barrier(0)
; template <class Epi, bool ALIGN_EPI>
; __device__ __forceinline__ void gemm_phase(LAS unsigned char* lds, const Gemm g, const StaticOrder& S, const Epi& E) {
;     ...
;             PG8_WAIT_V(8); PG8_WAIT_L(0); PG8_BAR; PG8_MMA(1, 0, At, B0); PG8_MMA(1, 1, At, B1); PG8_BAR; PG8_SCHED;
;             PG8_LDB(B0, 1, 0); PG8_LDB(B1, 1, 1); PG8_SCHED; PG8_LDA(At, 1, 0); PG8_STAGE(PG8_SA(0, 1), a2 + hstepA, voffA);
;             PG8_WAIT_V(8); PG8_WAIT_L(0); PG8_BAR; PG8_MMA(0, 0, At, B0); PG8_MMA(0, 1, At, B1); PG8_BAR; PG8_SCHED;
	s_waitcnt lgkmcnt(0)
	v_mfma_f32_16x16x32_bf16 v[62:65], v[140:143], v[200:203], v[62:65]
	v_mfma_f32_16x16x32_bf16 v[58:61], v[156:159], v[200:203], v[58:61]
	v_mfma_f32_16x16x32_bf16 v[46:49], v[140:143], v[208:211], v[46:49]
	v_mfma_f32_16x16x32_bf16 v[42:45], v[156:159], v[208:211], v[42:45]
	v_mfma_f32_16x16x32_bf16 v[30:33], v[140:143], v[216:219], v[30:33]
	v_mfma_f32_16x16x32_bf16 v[26:29], v[156:159], v[216:219], v[26:29]
	v_mfma_f32_16x16x32_bf16 v[14:17], v[140:143], v[224:227], v[14:17]
	v_mfma_f32_16x16x32_bf16 v[10:13], v[156:159], v[224:227], v[10:13]
	v_mfma_f32_16x16x32_bf16 v[62:65], v[148:151], v[204:207], v[62:65]
	v_mfma_f32_16x16x32_bf16 v[58:61], v[180:183], v[204:207], v[58:61]
	v_mfma_f32_16x16x32_bf16 v[46:49], v[148:151], v[212:215], v[46:49]
	v_mfma_f32_16x16x32_bf16 v[42:45], v[180:183], v[212:215], v[42:45]
	v_mfma_f32_16x16x32_bf16 v[30:33], v[148:151], v[220:223], v[30:33]
	v_mfma_f32_16x16x32_bf16 v[26:29], v[180:183], v[220:223], v[26:29]
	v_mfma_f32_16x16x32_bf16 v[14:17], v[148:151], v[228:231], v[14:17]
	v_mfma_f32_16x16x32_bf16 v[10:13], v[180:183], v[228:231], v[10:13]
	v_mfma_f32_16x16x32_bf16 v[54:57], v[184:187], v[200:203], v[54:57]
	v_mfma_f32_16x16x32_bf16 v[50:53], v[192:195], v[200:203], v[50:53]
	v_mfma_f32_16x16x32_bf16 v[38:41], v[184:187], v[208:211], v[38:41]
	v_mfma_f32_16x16x32_bf16 v[34:37], v[192:195], v[208:211], v[34:37]
	v_mfma_f32_16x16x32_bf16 v[22:25], v[184:187], v[216:219], v[22:25]
	v_mfma_f32_16x16x32_bf16 v[18:21], v[192:195], v[216:219], v[18:21]
	v_mfma_f32_16x16x32_bf16 v[6:9], v[184:187], v[224:227], v[6:9]
	v_mfma_f32_16x16x32_bf16 v[2:5], v[192:195], v[224:227], v[2:5]
	v_mfma_f32_16x16x32_bf16 v[54:57], v[188:191], v[204:207], v[54:57]
	v_mfma_f32_16x16x32_bf16 v[50:53], v[196:199], v[204:207], v[50:53]
	v_mfma_f32_16x16x32_bf16 v[38:41], v[188:191], v[212:215], v[38:41]
	v_mfma_f32_16x16x32_bf16 v[34:37], v[196:199], v[212:215], v[34:37]
	v_mfma_f32_16x16x32_bf16 v[22:25], v[188:191], v[220:223], v[22:25]
	v_mfma_f32_16x16x32_bf16 v[18:21], v[196:199], v[220:223], v[18:21]
	v_mfma_f32_16x16x32_bf16 v[6:9], v[188:191], v[228:231], v[6:9]
	v_mfma_f32_16x16x32_bf16 v[2:5], v[196:199], v[228:231], v[2:5]
	s_barrier
	s_add_i32 s44, 0, 0x18000
	v_add_u32_e32 v164, s44, v146
	s_add_i32 s45, 0, 0x1c000
	ds_read_b128 v[140:143], v164
	ds_read_b128 v[148:151], v164 offset:1024
	ds_read_b128 v[156:159], v164 offset:2048
	ds_read_b128 v[180:183], v164 offset:3072
	v_add_u32_e32 v164, s45, v146
	ds_read_b128 v[184:187], v164
	ds_read_b128 v[188:191], v164 offset:1024
	ds_read_b128 v[192:195], v164 offset:2048
	ds_read_b128 v[196:199], v164 offset:3072
	s_add_u32 s0, s22, 0x160000
	s_addc_u32 s1, s23, 0
	s_mov_b32 m0, s31
	v_lshl_add_u64 v[170:171], s[0:1], 0, v[130:131]
	ds_read_b128 v[200:203], v147 offset:32768
	ds_read_b128 v[204:207], v147 offset:33792
	ds_read_b128 v[208:211], v147 offset:34816
	ds_read_b128 v[212:215], v147 offset:35840
	ds_read_b128 v[216:219], v147 offset:36864
	ds_read_b128 v[220:223], v147 offset:37888
	ds_read_b128 v[224:227], v147 offset:38912
	ds_read_b128 v[228:231], v147 offset:39936
	global_load_lds_dwordx4 v[170:171], off
	v_lshl_add_u64 v[170:171], s[0:1], 0, v[132:133]
	s_mov_b32 m0, s34
	s_nop 0
	global_load_lds_dwordx4 v[170:171], off
	s_waitcnt vmcnt(8)
	s_waitcnt lgkmcnt(0)
	s_barrier
	s_waitcnt lgkmcnt(0)
	v_mfma_f32_16x16x32_bf16 v[126:129], v[140:143], v[200:203], v[126:129]
	v_mfma_f32_16x16x32_bf16 v[122:125], v[156:159], v[200:203], v[122:125]
	v_mfma_f32_16x16x32_bf16 v[110:113], v[140:143], v[208:211], v[110:113]
	v_mfma_f32_16x16x32_bf16 v[106:109], v[156:159], v[208:211], v[106:109]
	v_mfma_f32_16x16x32_bf16 v[94:97], v[140:143], v[216:219], v[94:97]
	v_mfma_f32_16x16x32_bf16 v[90:93], v[156:159], v[216:219], v[90:93]
	v_mfma_f32_16x16x32_bf16 v[78:81], v[140:143], v[224:227], v[78:81]
	v_mfma_f32_16x16x32_bf16 v[74:77], v[156:159], v[224:227], v[74:77]
	v_mfma_f32_16x16x32_bf16 v[126:129], v[148:151], v[204:207], v[126:129]
	v_mfma_f32_16x16x32_bf16 v[122:125], v[180:183], v[204:207], v[122:125]
	v_mfma_f32_16x16x32_bf16 v[110:113], v[148:151], v[212:215], v[110:113]
	v_mfma_f32_16x16x32_bf16 v[106:109], v[180:183], v[212:215], v[106:109]
	v_mfma_f32_16x16x32_bf16 v[94:97], v[148:151], v[220:223], v[94:97]
	v_mfma_f32_16x16x32_bf16 v[90:93], v[180:183], v[220:223], v[90:93]
	v_mfma_f32_16x16x32_bf16 v[78:81], v[148:151], v[228:231], v[78:81]
	v_mfma_f32_16x16x32_bf16 v[74:77], v[180:183], v[228:231], v[74:77]
	v_mfma_f32_16x16x32_bf16 v[118:121], v[184:187], v[200:203], v[118:121]
	v_mfma_f32_16x16x32_bf16 v[114:117], v[192:195], v[200:203], v[114:117]
	v_mfma_f32_16x16x32_bf16 v[102:105], v[184:187], v[208:211], v[102:105]
	v_mfma_f32_16x16x32_bf16 v[98:101], v[192:195], v[208:211], v[98:101]
	v_mfma_f32_16x16x32_bf16 v[86:89], v[184:187], v[216:219], v[86:89]
	v_mfma_f32_16x16x32_bf16 v[82:85], v[192:195], v[216:219], v[82:85]
	v_mfma_f32_16x16x32_bf16 v[70:73], v[184:187], v[224:227], v[70:73]
	v_mfma_f32_16x16x32_bf16 v[66:69], v[192:195], v[224:227], v[66:69]
	v_mfma_f32_16x16x32_bf16 v[118:121], v[188:191], v[204:207], v[118:121]
	v_mfma_f32_16x16x32_bf16 v[114:117], v[196:199], v[204:207], v[114:117]
	v_mfma_f32_16x16x32_bf16 v[102:105], v[188:191], v[212:215], v[102:105]
	v_mfma_f32_16x16x32_bf16 v[98:101], v[196:199], v[212:215], v[98:101]
	v_mfma_f32_16x16x32_bf16 v[86:89], v[188:191], v[220:223], v[86:89]
	v_mfma_f32_16x16x32_bf16 v[82:85], v[196:199], v[220:223], v[82:85]
	v_mfma_f32_16x16x32_bf16 v[70:73], v[188:191], v[228:231], v[70:73]
	v_mfma_f32_16x16x32_bf16 v[66:69], v[196:199], v[228:231], v[66:69]
	s_barrier
; #define PG8_STAGE(bufoff, gbase, voff) do { _Pragma("unroll") for (int _i = 0; _i < 2; ++_i) \
;         __builtin_amdgcn_global_load_lds((const unsigned*)((const char*)(gbase) + (voff)[_i]), (LAS unsigned*)(lds + (bufoff) + ldsw + _i * 8192), 16, 0, 0); } while (0)
; #define PG8_LDA(dst, b, h) do { _Pragma("unroll") for (int m = 0; m < 4; ++m) _Pragma("unroll") for (int k = 0; k < 2; ++k) dst[m][k] = *(const LAS bf16x8*)(lds + PG8_SA(b, h) + aoff + m * 2048 + k * 1024); } while (0)
; #define PG8_MMA(ai, bj, At, Bt) do { __builtin_amdgcn_s_setprio(1); _Pragma("unroll") for (int m = 0; m < 4; ++m) _Pragma("unroll") for (int n = 0; n < 2; ++n) _Pragma("unroll") for (int k = 0; k < 2; ++k) \
;         acc[ai][bj][m][n] = __builtin_amdgcn_mfma_f32_16x16x32_bf16(Bt[n][k], At[m][k], acc[ai][bj][m][n], 0, 0, 0); __builtin_amdgcn_s_setprio(0); } while (0)
; #define PG8_WAIT_V(n) asm volatile("s_waitcnt vmcnt(" #n ")" ::: "memory")
; #define PG8_WAIT_L(n) asm volatile("s_waitcnt lgkmcnt(" #n ")" ::: "memory")
; #define PG8_BAR __builtin_amdgcn_s_barrier()
; #define PG8_SCHED __builtin_amdgcn_sched_barrier(0)
; template <class Epi, bool ALIGN_EPI>
; __device__ __forceinline__ void gemm_phase(LAS unsigned char* lds, const Gemm g, const StaticOrder& S, const Epi& E) {
;     ...
;             PG8_LDA(At, 1, 1); PG8_STAGE(PG8_SB(1, 0), b3, voffB); PG8_STAGE(PG8_SB(1, 1), b3 + hstepB, voffB); PG8_STAGE(PG8_SA(1, 0), a3, voffA);
;             PG8_WAIT_V(8); PG8_WAIT_L(0); PG8_BAR; PG8_MMA(1, 0, At, B0); PG8_MMA(1, 1, At, B1); PG8_BAR; PG8_SCHED;
	s_add_i32 s0, s44, s28
	v_lshl_add_u64 v[144:145], v[144:145], 0, s[94:95]
	s_mov_b32 m0, s0
	ds_read_b128 v[200:203], v147 offset:49152
	ds_read_b128 v[204:207], v147 offset:50176
	ds_read_b128 v[208:211], v147 offset:51200
	ds_read_b128 v[212:215], v147 offset:52224
	ds_read_b128 v[216:219], v147 offset:53248
	ds_read_b128 v[220:223], v147 offset:54272
	ds_read_b128 v[224:227], v147 offset:55296
	ds_read_b128 v[228:231], v147 offset:56320
	global_load_lds_dwordx4 v[144:145], off
	s_add_i32 m0, s0, 0x2000
	s_add_u32 s0, s20, 0x40080
	v_lshl_add_u64 v[144:145], v[152:153], 0, s[94:95]
	s_addc_u32 s1, s21, 0
	s_add_i32 s20, s45, s28
	global_load_lds_dwordx4 v[144:145], off
	v_lshl_add_u64 v[144:145], s[0:1], 0, v[0:1]
	s_mov_b32 m0, s20
	s_nop 0
	global_load_lds_dwordx4 v[144:145], off
	v_lshl_add_u64 v[144:145], s[0:1], 0, v[134:135]
	s_add_i32 m0, s20, 0x2000
	s_nop 0
	global_load_lds_dwordx4 v[144:145], off
	v_lshl_add_u64 v[144:145], v[160:161], 0, s[94:95]
	s_mov_b32 m0, s4
	s_nop 0
	global_load_lds_dwordx4 v[144:145], off
	v_lshl_add_u64 v[144:145], v[162:163], 0, s[94:95]
	s_mov_b32 m0, s35
	s_nop 0
	global_load_lds_dwordx4 v[144:145], off
	s_waitcnt vmcnt(8)
	s_waitcnt lgkmcnt(0)
	s_barrier
	s_waitcnt lgkmcnt(0)
	v_mfma_f32_16x16x32_bf16 v[62:65], v[140:143], v[200:203], v[62:65]
	v_mfma_f32_16x16x32_bf16 v[58:61], v[156:159], v[200:203], v[58:61]
	v_mfma_f32_16x16x32_bf16 v[46:49], v[140:143], v[208:211], v[46:49]
	v_mfma_f32_16x16x32_bf16 v[42:45], v[156:159], v[208:211], v[42:45]
	v_mfma_f32_16x16x32_bf16 v[30:33], v[140:143], v[216:219], v[30:33]
	v_mfma_f32_16x16x32_bf16 v[26:29], v[156:159], v[216:219], v[26:29]
	v_mfma_f32_16x16x32_bf16 v[14:17], v[140:143], v[224:227], v[14:17]
	v_mfma_f32_16x16x32_bf16 v[10:13], v[156:159], v[224:227], v[10:13]
	v_mfma_f32_16x16x32_bf16 v[62:65], v[148:151], v[204:207], v[62:65]
	v_mfma_f32_16x16x32_bf16 v[58:61], v[180:183], v[204:207], v[58:61]
	v_mfma_f32_16x16x32_bf16 v[46:49], v[148:151], v[212:215], v[46:49]
	v_mfma_f32_16x16x32_bf16 v[42:45], v[180:183], v[212:215], v[42:45]
	v_mfma_f32_16x16x32_bf16 v[30:33], v[148:151], v[220:223], v[30:33]
	v_mfma_f32_16x16x32_bf16 v[26:29], v[180:183], v[220:223], v[26:29]
	v_mfma_f32_16x16x32_bf16 v[14:17], v[148:151], v[228:231], v[14:17]
	v_mfma_f32_16x16x32_bf16 v[10:13], v[180:183], v[228:231], v[10:13]
	v_mfma_f32_16x16x32_bf16 v[54:57], v[184:187], v[200:203], v[54:57]
	v_mfma_f32_16x16x32_bf16 v[50:53], v[192:195], v[200:203], v[50:53]
	v_mfma_f32_16x16x32_bf16 v[38:41], v[184:187], v[208:211], v[38:41]
	v_mfma_f32_16x16x32_bf16 v[34:37], v[192:195], v[208:211], v[34:37]
	v_mfma_f32_16x16x32_bf16 v[22:25], v[184:187], v[216:219], v[22:25]
	v_mfma_f32_16x16x32_bf16 v[18:21], v[192:195], v[216:219], v[18:21]
	v_mfma_f32_16x16x32_bf16 v[6:9], v[184:187], v[224:227], v[6:9]
	v_mfma_f32_16x16x32_bf16 v[2:5], v[192:195], v[224:227], v[2:5]
	v_mfma_f32_16x16x32_bf16 v[54:57], v[188:191], v[204:207], v[54:57]
	v_mfma_f32_16x16x32_bf16 v[50:53], v[196:199], v[204:207], v[50:53]
	v_mfma_f32_16x16x32_bf16 v[38:41], v[188:191], v[212:215], v[38:41]
	v_mfma_f32_16x16x32_bf16 v[34:37], v[196:199], v[212:215], v[34:37]
	v_mfma_f32_16x16x32_bf16 v[22:25], v[188:191], v[220:223], v[22:25]
	v_mfma_f32_16x16x32_bf16 v[18:21], v[196:199], v[220:223], v[18:21]
	v_mfma_f32_16x16x32_bf16 v[6:9], v[188:191], v[228:231], v[6:9]
	v_mfma_f32_16x16x32_bf16 v[2:5], v[196:199], v[228:231], v[2:5]
	s_cmp_lg_u32 s43, 12
	s_cbranch_scc1 .Ltail_bar_6
	s_cmp_eq_u64 s[12:13], 0
	s_cbranch_scc1 .Ltail_skip_6

; #define PG8_BAR __builtin_amdgcn_s_barrier()
; template <class Epi, bool ALIGN_EPI>
; __device__ __forceinline__ void gemm_phase(LAS unsigned char* lds, const Gemm g, const StaticOrder& S, const Epi& E) {
;     ...
;         }
;         if constexpr (ALIGN_EPI) { if (wr == 0) PG8_BAR; }
.Ltail_skip_6:
	s_add_i32 s43, s43, 2
	s_add_u32 s41, s41, 0x100
	s_addc_u32 s42, s42, 0
	s_cmp_gt_u32 s43, 13
	s_mov_b64 s[0:1], s[2:3]
	s_cbranch_scc0 .LBB0_414

; #define PG8_STAGE(bufoff, gbase, voff) do { _Pragma("unroll") for (int _i = 0; _i < 2; ++_i) \
;         __builtin_amdgcn_global_load_lds((const unsigned*)((const char*)(gbase) + (voff)[_i]), (LAS unsigned*)(lds + (bufoff) + ldsw + _i * 8192), 16, 0, 0); } while (0)
; #define PG8_LDA(dst, b, h) do { _Pragma("unroll") for (int m = 0; m < 4; ++m) _Pragma("unroll") for (int k = 0; k < 2; ++k) dst[m][k] = *(const LAS bf16x8*)(lds + PG8_SA(b, h) + aoff + m * 2048 + k * 1024); } while (0)
; #define PG8_LDB(dst, b, h) do { _Pragma("unroll") for (int n = 0; n < 2; ++n) _Pragma("unroll") for (int k = 0; k < 2; ++k) dst[n][k] = *(const LAS bf16x8*)(lds + PG8_SB(b, h) + boff + n * 2048 + k * 1024); } while (0)
; #define PG8_MMA(ai, bj, At, Bt) do { __builtin_amdgcn_s_setprio(1); _Pragma("unroll") for (int m = 0; m < 4; ++m) _Pragma("unroll") for (int n = 0; n < 2; ++n) _Pragma("unroll") for (int k = 0; k < 2; ++k) \
;         acc[ai][bj][m][n] = __builtin_amdgcn_mfma_f32_16x16x32_bf16(Bt[n][k], At[m][k], acc[ai][bj][m][n], 0, 0, 0); __builtin_amdgcn_s_setprio(0); } while (0)
; #define PG8_WAIT_V(n) asm volatile("s_waitcnt vmcnt(" #n ")" ::: "memory")
; #define PG8_WAIT_L(n) asm volatile("s_waitcnt lgkmcnt(" #n ")" ::: "memory")
; #define PG8_BAR __builtin_amdgcn_s_barrier()
; #define PG8_SCHED __builtin_amdgcn_sched_barrier(0)
; template <class Epi, bool ALIGN_EPI>
; __device__ __forceinline__ void gemm_phase(LAS unsigned char* lds, const Gemm g, const StaticOrder& S, const Epi& E) {
;     ...
;         for (int t = 0; t < nt; t += 2) {
;             const bool last = (t == nt - 2);
;             const char* a1 = cA + (size_t)(t + 1) * kstep;
;             const char* a2 = last ? nA : cA + (size_t)(t + 2) * kstep; const char* b2 = last ? nB : cB + (size_t)(t + 2) * kstep;
;             const char* a3 = a2 + kstep; const char* b3 = b2 + kstep;
;             PG8_LDB(B0, 0, 0); PG8_LDB(B1, 0, 1); PG8_SCHED; PG8_LDA(At, 0, 0); PG8_STAGE(PG8_SA(1, 1), a1 + hstepA, voffA);
;             PG8_WAIT_V(8); PG8_WAIT_L(0); PG8_BAR; PG8_MMA(0, 0, At, B0); PG8_MMA(0, 1, At, B1); PG8_BAR; PG8_SCHED;
;             PG8_LDA(At, 0, 1); PG8_STAGE(PG8_SB(0, 0), b2, voffB); PG8_STAGE(PG8_SB(0, 1), b2 + hstepB, voffB); PG8_STAGE(PG8_SA(0, 0), a2, voffA);
.LBB0_483:
	s_add_u32 s18, s6, 0xfffc0080
	s_addc_u32 s19, s7, -1
	s_add_i32 s41, 0, 0x10000
	s_cmp_eq_u32 s40, 12
	s_cselect_b32 s21, s1, s19
	s_cselect_b32 s20, s36, s18
	v_add_u32_e32 v152, s41, v140
	s_cselect_b32 s19, s11, s39
	s_cselect_b32 s18, s37, s38
	s_add_i32 s44, 0, 0x14000
	ds_read_b128 v[144:147], v152
	ds_read_b128 v[148:151], v152 offset:1024
	ds_read_b128 v[156:159], v152 offset:2048
	ds_read_b128 v[180:183], v152 offset:3072
	v_add_u32_e32 v152, s44, v140
	ds_read_b128 v[184:187], v152
	ds_read_b128 v[188:191], v152 offset:1024
	ds_read_b128 v[192:195], v152 offset:2048
	ds_read_b128 v[196:199], v152 offset:3072
	v_lshl_add_u64 v[152:153], s[6:7], 0, v[136:137]
	s_add_i32 m0, s25, 0xc000
	ds_read_b128 v[200:203], v142
	ds_read_b128 v[204:207], v142 offset:1024
	ds_read_b128 v[208:211], v142 offset:2048
	ds_read_b128 v[212:215], v142 offset:3072
	ds_read_b128 v[216:219], v142 offset:4096
	ds_read_b128 v[220:223], v142 offset:5120
	ds_read_b128 v[224:227], v142 offset:6144
	ds_read_b128 v[228:231], v142 offset:7168
	global_load_lds_dwordx4 v[152:153], off
	v_lshl_add_u64 v[152:153], s[6:7], 0, v[138:139]
	s_add_i32 m0, s25, 0xe000
	s_nop 0
	global_load_lds_dwordx4 v[152:153], off
	s_waitcnt vmcnt(8)
	s_waitcnt lgkmcnt(0)
	s_barrier
	s_waitcnt lgkmcnt(0)
	v_mfma_f32_16x16x32_bf16 v[126:129], v[144:147], v[200:203], v[126:129]
	v_mfma_f32_16x16x32_bf16 v[122:125], v[156:159], v[200:203], v[122:125]
	v_mfma_f32_16x16x32_bf16 v[110:113], v[144:147], v[208:211], v[110:113]
	v_mfma_f32_16x16x32_bf16 v[106:109], v[156:159], v[208:211], v[106:109]
	v_mfma_f32_16x16x32_bf16 v[94:97], v[144:147], v[216:219], v[94:97]
	v_mfma_f32_16x16x32_bf16 v[90:93], v[156:159], v[216:219], v[90:93]
	v_mfma_f32_16x16x32_bf16 v[78:81], v[144:147], v[224:227], v[78:81]
	v_mfma_f32_16x16x32_bf16 v[74:77], v[156:159], v[224:227], v[74:77]
	v_mfma_f32_16x16x32_bf16 v[126:129], v[148:151], v[204:207], v[126:129]
	v_mfma_f32_16x16x32_bf16 v[122:125], v[180:183], v[204:207], v[122:125]
	v_mfma_f32_16x16x32_bf16 v[110:113], v[148:151], v[212:215], v[110:113]
	v_mfma_f32_16x16x32_bf16 v[106:109], v[180:183], v[212:215], v[106:109]
	v_mfma_f32_16x16x32_bf16 v[94:97], v[148:151], v[220:223], v[94:97]
	v_mfma_f32_16x16x32_bf16 v[90:93], v[180:183], v[220:223], v[90:93]
	v_mfma_f32_16x16x32_bf16 v[78:81], v[148:151], v[228:231], v[78:81]
	v_mfma_f32_16x16x32_bf16 v[74:77], v[180:183], v[228:231], v[74:77]
	v_mfma_f32_16x16x32_bf16 v[118:121], v[184:187], v[200:203], v[118:121]
	v_mfma_f32_16x16x32_bf16 v[114:117], v[192:195], v[200:203], v[114:117]
	v_mfma_f32_16x16x32_bf16 v[102:105], v[184:187], v[208:211], v[102:105]
	v_mfma_f32_16x16x32_bf16 v[98:101], v[192:195], v[208:211], v[98:101]
	v_mfma_f32_16x16x32_bf16 v[86:89], v[184:187], v[216:219], v[86:89]
	v_mfma_f32_16x16x32_bf16 v[82:85], v[192:195], v[216:219], v[82:85]
	v_mfma_f32_16x16x32_bf16 v[70:73], v[184:187], v[224:227], v[70:73]
	v_mfma_f32_16x16x32_bf16 v[66:69], v[192:195], v[224:227], v[66:69]
	v_mfma_f32_16x16x32_bf16 v[118:121], v[188:191], v[204:207], v[118:121]
	v_mfma_f32_16x16x32_bf16 v[114:117], v[196:199], v[204:207], v[114:117]
	v_mfma_f32_16x16x32_bf16 v[102:105], v[188:191], v[212:215], v[102:105]
	v_mfma_f32_16x16x32_bf16 v[98:101], v[196:199], v[212:215], v[98:101]
	v_mfma_f32_16x16x32_bf16 v[86:89], v[188:191], v[220:223], v[86:89]
	v_mfma_f32_16x16x32_bf16 v[82:85], v[196:199], v[220:223], v[82:85]
	v_mfma_f32_16x16x32_bf16 v[70:73], v[188:191], v[228:231], v[70:73]
	v_mfma_f32_16x16x32_bf16 v[66:69], v[196:199], v[228:231], v[66:69]
	s_barrier
	s_add_i32 s41, s41, s24
	v_lshl_add_u64 v[152:153], s[18:19], 0, v[0:1]
	s_mov_b32 m0, s41
	ds_read_b128 v[200:203], v142 offset:16384
	ds_read_b128 v[204:207], v142 offset:17408
	ds_read_b128 v[208:211], v142 offset:18432
	ds_read_b128 v[212:215], v142 offset:19456
	ds_read_b128 v[216:219], v142 offset:20480
	ds_read_b128 v[220:223], v142 offset:21504
	ds_read_b128 v[224:227], v142 offset:22528
	ds_read_b128 v[228:231], v142 offset:23552
	global_load_lds_dwordx4 v[152:153], off
	s_add_i32 m0, s41, 0x2000
	s_add_u32 s42, s18, 0x40000
	v_lshl_add_u64 v[160:161], s[18:19], 0, v[134:135]
	s_addc_u32 s43, s19, 0
	s_add_i32 s41, s44, s24
	global_load_lds_dwordx4 v[160:161], off
	v_lshl_add_u64 v[162:163], s[42:43], 0, v[0:1]
	s_mov_b32 m0, s41
	v_lshl_add_u64 v[170:171], s[20:21], 0, v[132:133]
	global_load_lds_dwordx4 v[162:163], off
	v_lshl_add_u64 v[162:163], s[42:43], 0, v[134:135]
	s_add_i32 m0, s41, 0x2000
	s_nop 0
	global_load_lds_dwordx4 v[162:163], off
	v_lshl_add_u64 v[162:163], s[20:21], 0, v[130:131]
	s_mov_b32 m0, s25
	s_nop 0
	global_load_lds_dwordx4 v[162:163], off
	s_mov_b32 m0, s26
	s_nop 0
	global_load_lds_dwordx4 v[170:171], off
	s_waitcnt vmcnt(8)
	s_waitcnt lgkmcnt(0)
	s_barrier
; #define PG8_STAGE(bufoff, gbase, voff) do { _Pragma("unroll") for (int _i = 0; _i < 2; ++_i) \
;         __builtin_amdgcn_global_load_lds((const unsigned*)((const char*)(gbase) + (voff)[_i]), (LAS unsigned*)(lds + (bufoff) + ldsw + _i * 8192), 16, 0, 0); } while (0)
; #define PG8_LDA(dst, b, h) do { _Pragma("unroll") for (int m = 0; m < 4; ++m) _Pragma("unroll") for (int k = 0; k < 2; ++k) dst[m][k] = *(const LAS bf16x8*)(lds + PG8_SA(b, h) + aoff + m * 2048 + k * 1024); } while (0)
; #define PG8_LDB(dst, b, h) do { _Pragma("unroll") for (int n = 0; n < 2; ++n) _Pragma("unroll") for (int k = 0; k < 2; ++k) dst[n][k] = *(const LAS bf16x8*)(lds + PG8_SB(b, h) + boff + n * 2048 + k * 1024); } while (0)
; #define PG8_MMA(ai, bj, At, Bt) do { __builtin_amdgcn_s_setprio(1); _Pragma("unroll") for (int m = 0; m < 4; ++m) _Pragma("unroll") for (int n = 0; n < 2; ++n) _Pragma("unroll") for (int k = 0; k < 2; ++k) \
;         acc[ai][bj][m][n] = __builtin_amdgcn_mfma_f32_16x16x32_bf16(Bt[n][k], At[m][k], acc[ai][bj][m][n], 0, 0, 0); __builtin_amdgcn_s_setprio(0); } while (0)
; #define PG8_WAIT_V(n) asm volatile("s_waitcnt vmcnt(" #n ")" ::: "memory")
; #define PG8_WAIT_L(n) asm volatile("s_waitcnt lgkmcnt(" #n ")" ::: "memory")
; #define PG8_BAR __builtin_amdgcn_s_barrier()
; #define PG8_SCHED __builtin_amdgcn_sched_barrier(0)
; template <class Epi, bool ALIGN_EPI>
; __device__ __forceinline__ void gemm_phase(LAS unsigned char* lds, const Gemm g, const StaticOrder& S, const Epi& E) {
;     ...
;             PG8_WAIT_V(8); PG8_WAIT_L(0); PG8_BAR; PG8_MMA(1, 0, At, B0); PG8_MMA(1, 1, At, B1); PG8_BAR; PG8_SCHED;
;             PG8_LDB(B0, 1, 0); PG8_LDB(B1, 1, 1); PG8_SCHED; PG8_LDA(At, 1, 0); PG8_STAGE(PG8_SA(0, 1), a2 + hstepA, voffA);
;             PG8_WAIT_V(8); PG8_WAIT_L(0); PG8_BAR; PG8_MMA(0, 0, At, B0); PG8_MMA(0, 1, At, B1); PG8_BAR; PG8_SCHED;
	s_waitcnt lgkmcnt(0)
	v_mfma_f32_16x16x32_bf16 v[62:65], v[144:147], v[200:203], v[62:65]
	v_mfma_f32_16x16x32_bf16 v[58:61], v[156:159], v[200:203], v[58:61]
	v_mfma_f32_16x16x32_bf16 v[46:49], v[144:147], v[208:211], v[46:49]
	v_mfma_f32_16x16x32_bf16 v[42:45], v[156:159], v[208:211], v[42:45]
	v_mfma_f32_16x16x32_bf16 v[30:33], v[144:147], v[216:219], v[30:33]
	v_mfma_f32_16x16x32_bf16 v[26:29], v[156:159], v[216:219], v[26:29]
	v_mfma_f32_16x16x32_bf16 v[14:17], v[144:147], v[224:227], v[14:17]
	v_mfma_f32_16x16x32_bf16 v[10:13], v[156:159], v[224:227], v[10:13]
	v_mfma_f32_16x16x32_bf16 v[62:65], v[148:151], v[204:207], v[62:65]
	v_mfma_f32_16x16x32_bf16 v[58:61], v[180:183], v[204:207], v[58:61]
	v_mfma_f32_16x16x32_bf16 v[46:49], v[148:151], v[212:215], v[46:49]
	v_mfma_f32_16x16x32_bf16 v[42:45], v[180:183], v[212:215], v[42:45]
	v_mfma_f32_16x16x32_bf16 v[30:33], v[148:151], v[220:223], v[30:33]
	v_mfma_f32_16x16x32_bf16 v[26:29], v[180:183], v[220:223], v[26:29]
	v_mfma_f32_16x16x32_bf16 v[14:17], v[148:151], v[228:231], v[14:17]
	v_mfma_f32_16x16x32_bf16 v[10:13], v[180:183], v[228:231], v[10:13]
	v_mfma_f32_16x16x32_bf16 v[54:57], v[184:187], v[200:203], v[54:57]
	v_mfma_f32_16x16x32_bf16 v[50:53], v[192:195], v[200:203], v[50:53]
	v_mfma_f32_16x16x32_bf16 v[38:41], v[184:187], v[208:211], v[38:41]
	v_mfma_f32_16x16x32_bf16 v[34:37], v[192:195], v[208:211], v[34:37]
	v_mfma_f32_16x16x32_bf16 v[22:25], v[184:187], v[216:219], v[22:25]
	v_mfma_f32_16x16x32_bf16 v[18:21], v[192:195], v[216:219], v[18:21]
	v_mfma_f32_16x16x32_bf16 v[6:9], v[184:187], v[224:227], v[6:9]
	v_mfma_f32_16x16x32_bf16 v[2:5], v[192:195], v[224:227], v[2:5]
	v_mfma_f32_16x16x32_bf16 v[54:57], v[188:191], v[204:207], v[54:57]
	v_mfma_f32_16x16x32_bf16 v[50:53], v[196:199], v[204:207], v[50:53]
	v_mfma_f32_16x16x32_bf16 v[38:41], v[188:191], v[212:215], v[38:41]
	v_mfma_f32_16x16x32_bf16 v[34:37], v[196:199], v[212:215], v[34:37]
	v_mfma_f32_16x16x32_bf16 v[22:25], v[188:191], v[220:223], v[22:25]
	v_mfma_f32_16x16x32_bf16 v[18:21], v[196:199], v[220:223], v[18:21]
	v_mfma_f32_16x16x32_bf16 v[6:9], v[188:191], v[228:231], v[6:9]
	v_mfma_f32_16x16x32_bf16 v[2:5], v[196:199], v[228:231], v[2:5]
	s_barrier
	s_add_i32 s41, 0, 0x18000
	v_add_u32_e32 v164, s41, v140
	s_add_i32 s42, 0, 0x1c000
	ds_read_b128 v[144:147], v164
	ds_read_b128 v[148:151], v164 offset:1024
	ds_read_b128 v[156:159], v164 offset:2048
	ds_read_b128 v[180:183], v164 offset:3072
	v_add_u32_e32 v164, s42, v140
	ds_read_b128 v[184:187], v164
	ds_read_b128 v[188:191], v164 offset:1024
	ds_read_b128 v[192:195], v164 offset:2048
	ds_read_b128 v[196:199], v164 offset:3072
	s_add_u32 s20, s20, 0x40000
	s_addc_u32 s21, s21, 0
	s_mov_b32 m0, s27
	v_lshl_add_u64 v[172:173], s[20:21], 0, v[130:131]
	ds_read_b128 v[200:203], v142 offset:32768
	ds_read_b128 v[204:207], v142 offset:33792
	ds_read_b128 v[208:211], v142 offset:34816
	ds_read_b128 v[212:215], v142 offset:35840
	ds_read_b128 v[216:219], v142 offset:36864
	ds_read_b128 v[220:223], v142 offset:37888
	ds_read_b128 v[224:227], v142 offset:38912
	ds_read_b128 v[228:231], v142 offset:39936
	global_load_lds_dwordx4 v[172:173], off
	v_lshl_add_u64 v[172:173], s[20:21], 0, v[132:133]
	s_mov_b32 m0, s28
	s_nop 0
	global_load_lds_dwordx4 v[172:173], off
	s_waitcnt vmcnt(8)
	s_waitcnt lgkmcnt(0)
	s_barrier
	s_waitcnt lgkmcnt(0)
	v_mfma_f32_16x16x32_bf16 v[126:129], v[144:147], v[200:203], v[126:129]
	v_mfma_f32_16x16x32_bf16 v[122:125], v[156:159], v[200:203], v[122:125]
	v_mfma_f32_16x16x32_bf16 v[110:113], v[144:147], v[208:211], v[110:113]
	v_mfma_f32_16x16x32_bf16 v[106:109], v[156:159], v[208:211], v[106:109]
	v_mfma_f32_16x16x32_bf16 v[94:97], v[144:147], v[216:219], v[94:97]
	v_mfma_f32_16x16x32_bf16 v[90:93], v[156:159], v[216:219], v[90:93]
	v_mfma_f32_16x16x32_bf16 v[78:81], v[144:147], v[224:227], v[78:81]
	v_mfma_f32_16x16x32_bf16 v[74:77], v[156:159], v[224:227], v[74:77]
	v_mfma_f32_16x16x32_bf16 v[126:129], v[148:151], v[204:207], v[126:129]
	v_mfma_f32_16x16x32_bf16 v[122:125], v[180:183], v[204:207], v[122:125]
	v_mfma_f32_16x16x32_bf16 v[110:113], v[148:151], v[212:215], v[110:113]
	v_mfma_f32_16x16x32_bf16 v[106:109], v[180:183], v[212:215], v[106:109]
	v_mfma_f32_16x16x32_bf16 v[94:97], v[148:151], v[220:223], v[94:97]
	v_mfma_f32_16x16x32_bf16 v[90:93], v[180:183], v[220:223], v[90:93]
	v_mfma_f32_16x16x32_bf16 v[78:81], v[148:151], v[228:231], v[78:81]
	v_mfma_f32_16x16x32_bf16 v[74:77], v[180:183], v[228:231], v[74:77]
	v_mfma_f32_16x16x32_bf16 v[118:121], v[184:187], v[200:203], v[118:121]
	v_mfma_f32_16x16x32_bf16 v[114:117], v[192:195], v[200:203], v[114:117]
	v_mfma_f32_16x16x32_bf16 v[102:105], v[184:187], v[208:211], v[102:105]
	v_mfma_f32_16x16x32_bf16 v[98:101], v[192:195], v[208:211], v[98:101]
	v_mfma_f32_16x16x32_bf16 v[86:89], v[184:187], v[216:219], v[86:89]
	v_mfma_f32_16x16x32_bf16 v[82:85], v[192:195], v[216:219], v[82:85]
	v_mfma_f32_16x16x32_bf16 v[70:73], v[184:187], v[224:227], v[70:73]
	v_mfma_f32_16x16x32_bf16 v[66:69], v[192:195], v[224:227], v[66:69]
	v_mfma_f32_16x16x32_bf16 v[118:121], v[188:191], v[204:207], v[118:121]
	v_mfma_f32_16x16x32_bf16 v[114:117], v[196:199], v[204:207], v[114:117]
	v_mfma_f32_16x16x32_bf16 v[102:105], v[188:191], v[212:215], v[102:105]
	v_mfma_f32_16x16x32_bf16 v[98:101], v[196:199], v[212:215], v[98:101]
	v_mfma_f32_16x16x32_bf16 v[86:89], v[188:191], v[220:223], v[86:89]
	v_mfma_f32_16x16x32_bf16 v[82:85], v[196:199], v[220:223], v[82:85]
	v_mfma_f32_16x16x32_bf16 v[70:73], v[188:191], v[228:231], v[70:73]
	v_mfma_f32_16x16x32_bf16 v[66:69], v[196:199], v[228:231], v[66:69]
	s_barrier
; #define PG8_STAGE(bufoff, gbase, voff) do { _Pragma("unroll") for (int _i = 0; _i < 2; ++_i) \
;         __builtin_amdgcn_global_load_lds((const unsigned*)((const char*)(gbase) + (voff)[_i]), (LAS unsigned*)(lds + (bufoff) + ldsw + _i * 8192), 16, 0, 0); } while (0)
; #define PG8_LDA(dst, b, h) do { _Pragma("unroll") for (int m = 0; m < 4; ++m) _Pragma("unroll") for (int k = 0; k < 2; ++k) dst[m][k] = *(const LAS bf16x8*)(lds + PG8_SA(b, h) + aoff + m * 2048 + k * 1024); } while (0)
; #define PG8_MMA(ai, bj, At, Bt) do { __builtin_amdgcn_s_setprio(1); _Pragma("unroll") for (int m = 0; m < 4; ++m) _Pragma("unroll") for (int n = 0; n < 2; ++n) _Pragma("unroll") for (int k = 0; k < 2; ++k) \
;         acc[ai][bj][m][n] = __builtin_amdgcn_mfma_f32_16x16x32_bf16(Bt[n][k], At[m][k], acc[ai][bj][m][n], 0, 0, 0); __builtin_amdgcn_s_setprio(0); } while (0)
; #define PG8_WAIT_V(n) asm volatile("s_waitcnt vmcnt(" #n ")" ::: "memory")
; #define PG8_WAIT_L(n) asm volatile("s_waitcnt lgkmcnt(" #n ")" ::: "memory")
; #define PG8_BAR __builtin_amdgcn_s_barrier()
; #define PG8_SCHED __builtin_amdgcn_sched_barrier(0)
; template <class Epi, bool ALIGN_EPI>
; __device__ __forceinline__ void gemm_phase(LAS unsigned char* lds, const Gemm g, const StaticOrder& S, const Epi& E) {
;     ...
;             PG8_LDA(At, 1, 1); PG8_STAGE(PG8_SB(1, 0), b3, voffB); PG8_STAGE(PG8_SB(1, 1), b3 + hstepB, voffB); PG8_STAGE(PG8_SA(1, 0), a3, voffA);
;             PG8_WAIT_V(8); PG8_WAIT_L(0); PG8_BAR; PG8_MMA(1, 0, At, B0); PG8_MMA(1, 1, At, B1); PG8_BAR; PG8_SCHED;
	s_add_i32 s20, s41, s24
	v_lshl_add_u64 v[152:153], v[152:153], 0, s[94:95]
	s_mov_b32 m0, s20
	ds_read_b128 v[200:203], v142 offset:49152
	ds_read_b128 v[204:207], v142 offset:50176
	ds_read_b128 v[208:211], v142 offset:51200
	ds_read_b128 v[212:215], v142 offset:52224
	ds_read_b128 v[216:219], v142 offset:53248
	ds_read_b128 v[220:223], v142 offset:54272
	ds_read_b128 v[224:227], v142 offset:55296
	ds_read_b128 v[228:231], v142 offset:56320
	global_load_lds_dwordx4 v[152:153], off
	s_add_i32 m0, s20, 0x2000
	s_add_u32 s18, s18, 0x40080
	v_lshl_add_u64 v[152:153], v[160:161], 0, s[94:95]
	s_addc_u32 s19, s19, 0
	s_add_i32 s20, s42, s24
	global_load_lds_dwordx4 v[152:153], off
	v_lshl_add_u64 v[152:153], s[18:19], 0, v[0:1]
	s_mov_b32 m0, s20
	s_nop 0
	global_load_lds_dwordx4 v[152:153], off
	v_lshl_add_u64 v[152:153], s[18:19], 0, v[134:135]
	s_add_i32 m0, s20, 0x2000
	s_nop 0
	global_load_lds_dwordx4 v[152:153], off
	v_lshl_add_u64 v[152:153], v[162:163], 0, s[94:95]
	s_mov_b32 m0, s4
	s_nop 0
	global_load_lds_dwordx4 v[152:153], off
	v_lshl_add_u64 v[152:153], v[170:171], 0, s[94:95]
	s_mov_b32 m0, s29
	s_nop 0
	global_load_lds_dwordx4 v[152:153], off
	s_waitcnt vmcnt(8)
	s_waitcnt lgkmcnt(0)
	s_barrier
	s_waitcnt lgkmcnt(0)
	v_mfma_f32_16x16x32_bf16 v[62:65], v[144:147], v[200:203], v[62:65]
	v_mfma_f32_16x16x32_bf16 v[58:61], v[156:159], v[200:203], v[58:61]
	v_mfma_f32_16x16x32_bf16 v[46:49], v[144:147], v[208:211], v[46:49]
	v_mfma_f32_16x16x32_bf16 v[42:45], v[156:159], v[208:211], v[42:45]
	v_mfma_f32_16x16x32_bf16 v[30:33], v[144:147], v[216:219], v[30:33]
	v_mfma_f32_16x16x32_bf16 v[26:29], v[156:159], v[216:219], v[26:29]
	v_mfma_f32_16x16x32_bf16 v[14:17], v[144:147], v[224:227], v[14:17]
	v_mfma_f32_16x16x32_bf16 v[10:13], v[156:159], v[224:227], v[10:13]
	v_mfma_f32_16x16x32_bf16 v[62:65], v[148:151], v[204:207], v[62:65]
	v_mfma_f32_16x16x32_bf16 v[58:61], v[180:183], v[204:207], v[58:61]
	v_mfma_f32_16x16x32_bf16 v[46:49], v[148:151], v[212:215], v[46:49]
	v_mfma_f32_16x16x32_bf16 v[42:45], v[180:183], v[212:215], v[42:45]
	v_mfma_f32_16x16x32_bf16 v[30:33], v[148:151], v[220:223], v[30:33]
	v_mfma_f32_16x16x32_bf16 v[26:29], v[180:183], v[220:223], v[26:29]
	v_mfma_f32_16x16x32_bf16 v[14:17], v[148:151], v[228:231], v[14:17]
	v_mfma_f32_16x16x32_bf16 v[10:13], v[180:183], v[228:231], v[10:13]
	v_mfma_f32_16x16x32_bf16 v[54:57], v[184:187], v[200:203], v[54:57]
	v_mfma_f32_16x16x32_bf16 v[50:53], v[192:195], v[200:203], v[50:53]
	v_mfma_f32_16x16x32_bf16 v[38:41], v[184:187], v[208:211], v[38:41]
	v_mfma_f32_16x16x32_bf16 v[34:37], v[192:195], v[208:211], v[34:37]
	v_mfma_f32_16x16x32_bf16 v[22:25], v[184:187], v[216:219], v[22:25]
	v_mfma_f32_16x16x32_bf16 v[18:21], v[192:195], v[216:219], v[18:21]
	v_mfma_f32_16x16x32_bf16 v[6:9], v[184:187], v[224:227], v[6:9]
	v_mfma_f32_16x16x32_bf16 v[2:5], v[192:195], v[224:227], v[2:5]
	v_mfma_f32_16x16x32_bf16 v[54:57], v[188:191], v[204:207], v[54:57]
	v_mfma_f32_16x16x32_bf16 v[50:53], v[196:199], v[204:207], v[50:53]
	v_mfma_f32_16x16x32_bf16 v[38:41], v[188:191], v[212:215], v[38:41]
	v_mfma_f32_16x16x32_bf16 v[34:37], v[196:199], v[212:215], v[34:37]
	v_mfma_f32_16x16x32_bf16 v[22:25], v[188:191], v[220:223], v[22:25]
	v_mfma_f32_16x16x32_bf16 v[18:21], v[196:199], v[220:223], v[18:21]
	v_mfma_f32_16x16x32_bf16 v[6:9], v[188:191], v[228:231], v[6:9]
	v_mfma_f32_16x16x32_bf16 v[2:5], v[196:199], v[228:231], v[2:5]
	s_cmp_lg_u32 s40, 12
	s_cbranch_scc1 .Ltail_bar_4
	s_cmp_eq_u64 s[8:9], 0
	s_cbranch_scc1 .Ltail_skip_4

; #define PG8_STAGE(bufoff, gbase, voff) do { _Pragma("unroll") for (int _i = 0; _i < 2; ++_i) \
;         __builtin_amdgcn_global_load_lds((const unsigned*)((const char*)(gbase) + (voff)[_i]), (LAS unsigned*)(lds + (bufoff) + ldsw + _i * 8192), 16, 0, 0); } while (0)
; #define PG8_LDA(dst, b, h) do { _Pragma("unroll") for (int m = 0; m < 4; ++m) _Pragma("unroll") for (int k = 0; k < 2; ++k) dst[m][k] = *(const LAS bf16x8*)(lds + PG8_SA(b, h) + aoff + m * 2048 + k * 1024); } while (0)
; #define PG8_LDB(dst, b, h) do { _Pragma("unroll") for (int n = 0; n < 2; ++n) _Pragma("unroll") for (int k = 0; k < 2; ++k) dst[n][k] = *(const LAS bf16x8*)(lds + PG8_SB(b, h) + boff + n * 2048 + k * 1024); } while (0)
; #define PG8_MMA(ai, bj, At, Bt) do { __builtin_amdgcn_s_setprio(1); _Pragma("unroll") for (int m = 0; m < 4; ++m) _Pragma("unroll") for (int n = 0; n < 2; ++n) _Pragma("unroll") for (int k = 0; k < 2; ++k) \
;         acc[ai][bj][m][n] = __builtin_amdgcn_mfma_f32_16x16x32_bf16(Bt[n][k], At[m][k], acc[ai][bj][m][n], 0, 0, 0); __builtin_amdgcn_s_setprio(0); } while (0)
; #define PG8_WAIT_V(n) asm volatile("s_waitcnt vmcnt(" #n ")" ::: "memory")
; #define PG8_WAIT_L(n) asm volatile("s_waitcnt lgkmcnt(" #n ")" ::: "memory")
; #define PG8_BAR __builtin_amdgcn_s_barrier()
; #define PG8_SCHED __builtin_amdgcn_sched_barrier(0)
; template <class Epi, bool ALIGN_EPI>
; __device__ __forceinline__ void gemm_phase(LAS unsigned char* lds, const Gemm g, const StaticOrder& S, const Epi& E) {
;     ...
;         for (int t = 0; t < nt; t += 2) {
;             const bool last = (t == nt - 2);
;             const char* a1 = cA + (size_t)(t + 1) * kstep;
;             const char* a2 = last ? nA : cA + (size_t)(t + 2) * kstep; const char* b2 = last ? nB : cB + (size_t)(t + 2) * kstep;
;             const char* a3 = a2 + kstep; const char* b3 = b2 + kstep;
;             PG8_LDB(B0, 0, 0); PG8_LDB(B1, 0, 1); PG8_SCHED; PG8_LDA(At, 0, 0); PG8_STAGE(PG8_SA(1, 1), a1 + hstepA, voffA);
;             PG8_WAIT_V(8); PG8_WAIT_L(0); PG8_BAR; PG8_MMA(0, 0, At, B0); PG8_MMA(0, 1, At, B1); PG8_BAR; PG8_SCHED;
;             PG8_LDA(At, 0, 1); PG8_STAGE(PG8_SB(0, 0), b2, voffB); PG8_STAGE(PG8_SB(0, 1), b2 + hstepB, voffB); PG8_STAGE(PG8_SA(0, 0), a2, voffA);
.LBB0_603:
	s_add_u32 s24, s6, 0xfffc0080
	s_addc_u32 s25, s7, -1
	s_add_i32 s45, 0, 0x10000
	s_cmp_eq_u32 s44, 12
	s_cselect_b32 s27, s9, s25
	s_cselect_b32 s26, s40, s24
	v_add_u32_e32 v0, s45, v158
	s_cselect_b32 s25, s15, s43
	s_cselect_b32 s24, s41, s42
	s_add_i32 s48, 0, 0x14000
	ds_read_b128 v[142:145], v0
	ds_read_b128 v[146:149], v0 offset:1024
	ds_read_b128 v[150:153], v0 offset:2048
	ds_read_b128 v[180:183], v0 offset:3072
	v_add_u32_e32 v0, s48, v158
	ds_read_b128 v[184:187], v0
	ds_read_b128 v[188:191], v0 offset:1024
	ds_read_b128 v[192:195], v0 offset:2048
	ds_read_b128 v[196:199], v0 offset:3072
	v_lshl_add_u64 v[156:157], s[6:7], 0, v[138:139]
	s_add_i32 m0, s30, 0xc000
	ds_read_b128 v[200:203], v160
	ds_read_b128 v[204:207], v160 offset:1024
	ds_read_b128 v[208:211], v160 offset:2048
	ds_read_b128 v[212:215], v160 offset:3072
	ds_read_b128 v[216:219], v160 offset:4096
	ds_read_b128 v[220:223], v160 offset:5120
	ds_read_b128 v[224:227], v160 offset:6144
	ds_read_b128 v[228:231], v160 offset:7168
	global_load_lds_dwordx4 v[156:157], off
	v_lshl_add_u64 v[156:157], s[6:7], 0, v[140:141]
	s_add_i32 m0, s30, 0xe000
	s_nop 0
	global_load_lds_dwordx4 v[156:157], off
	s_waitcnt vmcnt(8)
	s_waitcnt lgkmcnt(0)
	s_barrier
	s_waitcnt lgkmcnt(0)
	v_mfma_f32_16x16x32_bf16 v[66:69], v[142:145], v[200:203], v[66:69]
	v_mfma_f32_16x16x32_bf16 v[58:61], v[150:153], v[200:203], v[58:61]
	v_mfma_f32_16x16x32_bf16 v[54:57], v[142:145], v[208:211], v[54:57]
	v_mfma_f32_16x16x32_bf16 v[50:53], v[150:153], v[208:211], v[50:53]
	v_mfma_f32_16x16x32_bf16 v[46:49], v[142:145], v[216:219], v[46:49]
	v_mfma_f32_16x16x32_bf16 v[42:45], v[150:153], v[216:219], v[42:45]
	v_mfma_f32_16x16x32_bf16 v[38:41], v[142:145], v[224:227], v[38:41]
	v_mfma_f32_16x16x32_bf16 v[34:37], v[150:153], v[224:227], v[34:37]
	v_mfma_f32_16x16x32_bf16 v[66:69], v[146:149], v[204:207], v[66:69]
	v_mfma_f32_16x16x32_bf16 v[58:61], v[180:183], v[204:207], v[58:61]
	v_mfma_f32_16x16x32_bf16 v[54:57], v[146:149], v[212:215], v[54:57]
	v_mfma_f32_16x16x32_bf16 v[50:53], v[180:183], v[212:215], v[50:53]
	v_mfma_f32_16x16x32_bf16 v[46:49], v[146:149], v[220:223], v[46:49]
	v_mfma_f32_16x16x32_bf16 v[42:45], v[180:183], v[220:223], v[42:45]
	v_mfma_f32_16x16x32_bf16 v[38:41], v[146:149], v[228:231], v[38:41]
	v_mfma_f32_16x16x32_bf16 v[34:37], v[180:183], v[228:231], v[34:37]
	v_mfma_f32_16x16x32_bf16 v[126:129], v[184:187], v[200:203], v[126:129]
	v_mfma_f32_16x16x32_bf16 v[122:125], v[192:195], v[200:203], v[122:125]
	v_mfma_f32_16x16x32_bf16 v[118:121], v[184:187], v[208:211], v[118:121]
	v_mfma_f32_16x16x32_bf16 v[114:117], v[192:195], v[208:211], v[114:117]
	v_mfma_f32_16x16x32_bf16 v[110:113], v[184:187], v[216:219], v[110:113]
	v_mfma_f32_16x16x32_bf16 v[106:109], v[192:195], v[216:219], v[106:109]
	v_mfma_f32_16x16x32_bf16 v[102:105], v[184:187], v[224:227], v[102:105]
	v_mfma_f32_16x16x32_bf16 v[98:101], v[192:195], v[224:227], v[98:101]
	v_mfma_f32_16x16x32_bf16 v[126:129], v[188:191], v[204:207], v[126:129]
	v_mfma_f32_16x16x32_bf16 v[122:125], v[196:199], v[204:207], v[122:125]
	v_mfma_f32_16x16x32_bf16 v[118:121], v[188:191], v[212:215], v[118:121]
	v_mfma_f32_16x16x32_bf16 v[114:117], v[196:199], v[212:215], v[114:117]
	v_mfma_f32_16x16x32_bf16 v[110:113], v[188:191], v[220:223], v[110:113]
	v_mfma_f32_16x16x32_bf16 v[106:109], v[196:199], v[220:223], v[106:109]
	v_mfma_f32_16x16x32_bf16 v[102:105], v[188:191], v[228:231], v[102:105]
	v_mfma_f32_16x16x32_bf16 v[98:101], v[196:199], v[228:231], v[98:101]
	s_barrier
	s_add_i32 s45, s45, s29
	v_lshl_add_u64 v[156:157], s[24:25], 0, v[132:133]
	s_mov_b32 m0, s45
	ds_read_b128 v[200:203], v160 offset:16384
	ds_read_b128 v[204:207], v160 offset:17408
	ds_read_b128 v[208:211], v160 offset:18432
	ds_read_b128 v[212:215], v160 offset:19456
	ds_read_b128 v[216:219], v160 offset:20480
	ds_read_b128 v[220:223], v160 offset:21504
	ds_read_b128 v[224:227], v160 offset:22528
	ds_read_b128 v[228:231], v160 offset:23552
	global_load_lds_dwordx4 v[156:157], off
	s_add_i32 m0, s45, 0x2000
	s_add_u32 s46, s24, 0x40000
	v_lshl_add_u64 v[162:163], s[24:25], 0, v[136:137]
	s_addc_u32 s47, s25, 0
	s_add_i32 s45, s48, s29
	global_load_lds_dwordx4 v[162:163], off
	v_lshl_add_u64 v[170:171], s[46:47], 0, v[132:133]
	s_mov_b32 m0, s45
	v_lshl_add_u64 v[172:173], s[26:27], 0, v[134:135]
	global_load_lds_dwordx4 v[170:171], off
	v_lshl_add_u64 v[170:171], s[46:47], 0, v[136:137]
	s_add_i32 m0, s45, 0x2000
	s_nop 0
	global_load_lds_dwordx4 v[170:171], off
	v_lshl_add_u64 v[170:171], s[26:27], 0, v[130:131]
	s_mov_b32 m0, s30
	s_nop 0
	global_load_lds_dwordx4 v[170:171], off
	s_mov_b32 m0, s31
	s_nop 0
	global_load_lds_dwordx4 v[172:173], off
	s_waitcnt vmcnt(8)
	s_waitcnt lgkmcnt(0)
	s_barrier
; #define PG8_STAGE(bufoff, gbase, voff) do { _Pragma("unroll") for (int _i = 0; _i < 2; ++_i) \
;         __builtin_amdgcn_global_load_lds((const unsigned*)((const char*)(gbase) + (voff)[_i]), (LAS unsigned*)(lds + (bufoff) + ldsw + _i * 8192), 16, 0, 0); } while (0)
; #define PG8_LDA(dst, b, h) do { _Pragma("unroll") for (int m = 0; m < 4; ++m) _Pragma("unroll") for (int k = 0; k < 2; ++k) dst[m][k] = *(const LAS bf16x8*)(lds + PG8_SA(b, h) + aoff + m * 2048 + k * 1024); } while (0)
; #define PG8_LDB(dst, b, h) do { _Pragma("unroll") for (int n = 0; n < 2; ++n) _Pragma("unroll") for (int k = 0; k < 2; ++k) dst[n][k] = *(const LAS bf16x8*)(lds + PG8_SB(b, h) + boff + n * 2048 + k * 1024); } while (0)
; #define PG8_MMA(ai, bj, At, Bt) do { __builtin_amdgcn_s_setprio(1); _Pragma("unroll") for (int m = 0; m < 4; ++m) _Pragma("unroll") for (int n = 0; n < 2; ++n) _Pragma("unroll") for (int k = 0; k < 2; ++k) \
;         acc[ai][bj][m][n] = __builtin_amdgcn_mfma_f32_16x16x32_bf16(Bt[n][k], At[m][k], acc[ai][bj][m][n], 0, 0, 0); __builtin_amdgcn_s_setprio(0); } while (0)
; #define PG8_WAIT_V(n) asm volatile("s_waitcnt vmcnt(" #n ")" ::: "memory")
; #define PG8_WAIT_L(n) asm volatile("s_waitcnt lgkmcnt(" #n ")" ::: "memory")
; #define PG8_BAR __builtin_amdgcn_s_barrier()
; #define PG8_SCHED __builtin_amdgcn_sched_barrier(0)
; template <class Epi, bool ALIGN_EPI>
; __device__ __forceinline__ void gemm_phase(LAS unsigned char* lds, const Gemm g, const StaticOrder& S, const Epi& E) {
;     ...
;             PG8_WAIT_V(8); PG8_WAIT_L(0); PG8_BAR; PG8_MMA(1, 0, At, B0); PG8_MMA(1, 1, At, B1); PG8_BAR; PG8_SCHED;
;             PG8_LDB(B0, 1, 0); PG8_LDB(B1, 1, 1); PG8_SCHED; PG8_LDA(At, 1, 0); PG8_STAGE(PG8_SA(0, 1), a2 + hstepA, voffA);
;             PG8_WAIT_V(8); PG8_WAIT_L(0); PG8_BAR; PG8_MMA(0, 0, At, B0); PG8_MMA(0, 1, At, B1); PG8_BAR; PG8_SCHED;
	s_waitcnt lgkmcnt(0)
	v_mfma_f32_16x16x32_bf16 v[30:33], v[142:145], v[200:203], v[30:33]
	v_mfma_f32_16x16x32_bf16 v[26:29], v[150:153], v[200:203], v[26:29]
	v_mfma_f32_16x16x32_bf16 v[22:25], v[142:145], v[208:211], v[22:25]
	v_mfma_f32_16x16x32_bf16 v[18:21], v[150:153], v[208:211], v[18:21]
	v_mfma_f32_16x16x32_bf16 v[14:17], v[142:145], v[216:219], v[14:17]
	v_mfma_f32_16x16x32_bf16 v[10:13], v[150:153], v[216:219], v[10:13]
	v_mfma_f32_16x16x32_bf16 v[6:9], v[142:145], v[224:227], v[6:9]
	v_mfma_f32_16x16x32_bf16 v[2:5], v[150:153], v[224:227], v[2:5]
	v_mfma_f32_16x16x32_bf16 v[30:33], v[146:149], v[204:207], v[30:33]
	v_mfma_f32_16x16x32_bf16 v[26:29], v[180:183], v[204:207], v[26:29]
	v_mfma_f32_16x16x32_bf16 v[22:25], v[146:149], v[212:215], v[22:25]
	v_mfma_f32_16x16x32_bf16 v[18:21], v[180:183], v[212:215], v[18:21]
	v_mfma_f32_16x16x32_bf16 v[14:17], v[146:149], v[220:223], v[14:17]
	v_mfma_f32_16x16x32_bf16 v[10:13], v[180:183], v[220:223], v[10:13]
	v_mfma_f32_16x16x32_bf16 v[6:9], v[146:149], v[228:231], v[6:9]
	v_mfma_f32_16x16x32_bf16 v[2:5], v[180:183], v[228:231], v[2:5]
	v_mfma_f32_16x16x32_bf16 v[94:97], v[184:187], v[200:203], v[94:97]
	v_mfma_f32_16x16x32_bf16 v[90:93], v[192:195], v[200:203], v[90:93]
	v_mfma_f32_16x16x32_bf16 v[86:89], v[184:187], v[208:211], v[86:89]
	v_mfma_f32_16x16x32_bf16 v[82:85], v[192:195], v[208:211], v[82:85]
	v_mfma_f32_16x16x32_bf16 v[78:81], v[184:187], v[216:219], v[78:81]
	v_mfma_f32_16x16x32_bf16 v[74:77], v[192:195], v[216:219], v[74:77]
	v_mfma_f32_16x16x32_bf16 v[70:73], v[184:187], v[224:227], v[70:73]
	v_mfma_f32_16x16x32_bf16 v[62:65], v[192:195], v[224:227], v[62:65]
	v_mfma_f32_16x16x32_bf16 v[94:97], v[188:191], v[204:207], v[94:97]
	v_mfma_f32_16x16x32_bf16 v[90:93], v[196:199], v[204:207], v[90:93]
	v_mfma_f32_16x16x32_bf16 v[86:89], v[188:191], v[212:215], v[86:89]
	v_mfma_f32_16x16x32_bf16 v[82:85], v[196:199], v[212:215], v[82:85]
	v_mfma_f32_16x16x32_bf16 v[78:81], v[188:191], v[220:223], v[78:81]
	v_mfma_f32_16x16x32_bf16 v[74:77], v[196:199], v[220:223], v[74:77]
	v_mfma_f32_16x16x32_bf16 v[70:73], v[188:191], v[228:231], v[70:73]
	v_mfma_f32_16x16x32_bf16 v[62:65], v[196:199], v[228:231], v[62:65]
	s_barrier
	s_add_i32 s45, 0, 0x18000
	v_add_u32_e32 v0, s45, v158
	s_add_i32 s46, 0, 0x1c000
	ds_read_b128 v[142:145], v0
	ds_read_b128 v[146:149], v0 offset:1024
	ds_read_b128 v[150:153], v0 offset:2048
	ds_read_b128 v[180:183], v0 offset:3072
	v_add_u32_e32 v0, s46, v158
	ds_read_b128 v[184:187], v0
	ds_read_b128 v[188:191], v0 offset:1024
	ds_read_b128 v[192:195], v0 offset:2048
	ds_read_b128 v[196:199], v0 offset:3072
	s_add_u32 s26, s26, 0x40000
	s_addc_u32 s27, s27, 0
	s_mov_b32 m0, s34
	v_lshl_add_u64 v[232:233], s[26:27], 0, v[130:131]
	ds_read_b128 v[200:203], v160 offset:32768
	ds_read_b128 v[204:207], v160 offset:33792
	ds_read_b128 v[208:211], v160 offset:34816
	ds_read_b128 v[212:215], v160 offset:35840
	ds_read_b128 v[216:219], v160 offset:36864
	ds_read_b128 v[220:223], v160 offset:37888
	ds_read_b128 v[224:227], v160 offset:38912
	ds_read_b128 v[228:231], v160 offset:39936
	global_load_lds_dwordx4 v[232:233], off
	v_lshl_add_u64 v[232:233], s[26:27], 0, v[134:135]
	s_mov_b32 m0, s35
	s_nop 0
	global_load_lds_dwordx4 v[232:233], off
	s_waitcnt vmcnt(8)
	s_waitcnt lgkmcnt(0)
	s_barrier
	s_waitcnt lgkmcnt(0)
	v_mfma_f32_16x16x32_bf16 v[66:69], v[142:145], v[200:203], v[66:69]
	v_mfma_f32_16x16x32_bf16 v[58:61], v[150:153], v[200:203], v[58:61]
	v_mfma_f32_16x16x32_bf16 v[54:57], v[142:145], v[208:211], v[54:57]
	v_mfma_f32_16x16x32_bf16 v[50:53], v[150:153], v[208:211], v[50:53]
	v_mfma_f32_16x16x32_bf16 v[46:49], v[142:145], v[216:219], v[46:49]
	v_mfma_f32_16x16x32_bf16 v[42:45], v[150:153], v[216:219], v[42:45]
	v_mfma_f32_16x16x32_bf16 v[38:41], v[142:145], v[224:227], v[38:41]
	v_mfma_f32_16x16x32_bf16 v[34:37], v[150:153], v[224:227], v[34:37]
	v_mfma_f32_16x16x32_bf16 v[66:69], v[146:149], v[204:207], v[66:69]
	v_mfma_f32_16x16x32_bf16 v[58:61], v[180:183], v[204:207], v[58:61]
	v_mfma_f32_16x16x32_bf16 v[54:57], v[146:149], v[212:215], v[54:57]
	v_mfma_f32_16x16x32_bf16 v[50:53], v[180:183], v[212:215], v[50:53]
	v_mfma_f32_16x16x32_bf16 v[46:49], v[146:149], v[220:223], v[46:49]
	v_mfma_f32_16x16x32_bf16 v[42:45], v[180:183], v[220:223], v[42:45]
	v_mfma_f32_16x16x32_bf16 v[38:41], v[146:149], v[228:231], v[38:41]
	v_mfma_f32_16x16x32_bf16 v[34:37], v[180:183], v[228:231], v[34:37]
	v_mfma_f32_16x16x32_bf16 v[126:129], v[184:187], v[200:203], v[126:129]
	v_mfma_f32_16x16x32_bf16 v[122:125], v[192:195], v[200:203], v[122:125]
	v_mfma_f32_16x16x32_bf16 v[118:121], v[184:187], v[208:211], v[118:121]
	v_mfma_f32_16x16x32_bf16 v[114:117], v[192:195], v[208:211], v[114:117]
	v_mfma_f32_16x16x32_bf16 v[110:113], v[184:187], v[216:219], v[110:113]
	v_mfma_f32_16x16x32_bf16 v[106:109], v[192:195], v[216:219], v[106:109]
	v_mfma_f32_16x16x32_bf16 v[102:105], v[184:187], v[224:227], v[102:105]
	v_mfma_f32_16x16x32_bf16 v[98:101], v[192:195], v[224:227], v[98:101]
	v_mfma_f32_16x16x32_bf16 v[126:129], v[188:191], v[204:207], v[126:129]
	v_mfma_f32_16x16x32_bf16 v[122:125], v[196:199], v[204:207], v[122:125]
	v_mfma_f32_16x16x32_bf16 v[118:121], v[188:191], v[212:215], v[118:121]
	v_mfma_f32_16x16x32_bf16 v[114:117], v[196:199], v[212:215], v[114:117]
	v_mfma_f32_16x16x32_bf16 v[110:113], v[188:191], v[220:223], v[110:113]
	v_mfma_f32_16x16x32_bf16 v[106:109], v[196:199], v[220:223], v[106:109]
	v_mfma_f32_16x16x32_bf16 v[102:105], v[188:191], v[228:231], v[102:105]
	v_mfma_f32_16x16x32_bf16 v[98:101], v[196:199], v[228:231], v[98:101]
	s_barrier
; #define PG8_STAGE(bufoff, gbase, voff) do { _Pragma("unroll") for (int _i = 0; _i < 2; ++_i) \
;         __builtin_amdgcn_global_load_lds((const unsigned*)((const char*)(gbase) + (voff)[_i]), (LAS unsigned*)(lds + (bufoff) + ldsw + _i * 8192), 16, 0, 0); } while (0)
; #define PG8_LDA(dst, b, h) do { _Pragma("unroll") for (int m = 0; m < 4; ++m) _Pragma("unroll") for (int k = 0; k < 2; ++k) dst[m][k] = *(const LAS bf16x8*)(lds + PG8_SA(b, h) + aoff + m * 2048 + k * 1024); } while (0)
; #define PG8_MMA(ai, bj, At, Bt) do { __builtin_amdgcn_s_setprio(1); _Pragma("unroll") for (int m = 0; m < 4; ++m) _Pragma("unroll") for (int n = 0; n < 2; ++n) _Pragma("unroll") for (int k = 0; k < 2; ++k) \
;         acc[ai][bj][m][n] = __builtin_amdgcn_mfma_f32_16x16x32_bf16(Bt[n][k], At[m][k], acc[ai][bj][m][n], 0, 0, 0); __builtin_amdgcn_s_setprio(0); } while (0)
; #define PG8_WAIT_V(n) asm volatile("s_waitcnt vmcnt(" #n ")" ::: "memory")
; #define PG8_WAIT_L(n) asm volatile("s_waitcnt lgkmcnt(" #n ")" ::: "memory")
; #define PG8_BAR __builtin_amdgcn_s_barrier()
; #define PG8_SCHED __builtin_amdgcn_sched_barrier(0)
; template <class Epi, bool ALIGN_EPI>
; __device__ __forceinline__ void gemm_phase(LAS unsigned char* lds, const Gemm g, const StaticOrder& S, const Epi& E) {
;     ...
;             PG8_LDA(At, 1, 1); PG8_STAGE(PG8_SB(1, 0), b3, voffB); PG8_STAGE(PG8_SB(1, 1), b3 + hstepB, voffB); PG8_STAGE(PG8_SA(1, 0), a3, voffA);
;             PG8_WAIT_V(8); PG8_WAIT_L(0); PG8_BAR; PG8_MMA(1, 0, At, B0); PG8_MMA(1, 1, At, B1); PG8_BAR; PG8_SCHED;
	s_add_i32 s26, s45, s29
	v_lshl_add_u64 v[156:157], v[156:157], 0, s[94:95]
	s_mov_b32 m0, s26
	ds_read_b128 v[200:203], v160 offset:49152
	ds_read_b128 v[204:207], v160 offset:50176
	ds_read_b128 v[208:211], v160 offset:51200
	ds_read_b128 v[212:215], v160 offset:52224
	ds_read_b128 v[216:219], v160 offset:53248
	ds_read_b128 v[220:223], v160 offset:54272
	ds_read_b128 v[224:227], v160 offset:55296
	ds_read_b128 v[228:231], v160 offset:56320
	global_load_lds_dwordx4 v[156:157], off
	s_add_i32 m0, s26, 0x2000
	s_add_u32 s24, s24, 0x40080
	v_lshl_add_u64 v[156:157], v[162:163], 0, s[94:95]
	s_addc_u32 s25, s25, 0
	s_add_i32 s26, s46, s29
	global_load_lds_dwordx4 v[156:157], off
	v_lshl_add_u64 v[156:157], s[24:25], 0, v[132:133]
	s_mov_b32 m0, s26
	s_nop 0
	global_load_lds_dwordx4 v[156:157], off
	v_lshl_add_u64 v[156:157], s[24:25], 0, v[136:137]
	s_add_i32 m0, s26, 0x2000
	s_nop 0
	global_load_lds_dwordx4 v[156:157], off
	v_lshl_add_u64 v[156:157], v[170:171], 0, s[94:95]
	s_mov_b32 m0, s36
	s_nop 0
	global_load_lds_dwordx4 v[156:157], off
	v_lshl_add_u64 v[156:157], v[172:173], 0, s[94:95]
	s_mov_b32 m0, s37
	s_nop 0
	global_load_lds_dwordx4 v[156:157], off
	s_waitcnt vmcnt(8)
	s_waitcnt lgkmcnt(0)
	s_barrier
	s_waitcnt lgkmcnt(0)
	v_mfma_f32_16x16x32_bf16 v[30:33], v[142:145], v[200:203], v[30:33]
	v_mfma_f32_16x16x32_bf16 v[26:29], v[150:153], v[200:203], v[26:29]
	v_mfma_f32_16x16x32_bf16 v[22:25], v[142:145], v[208:211], v[22:25]
	v_mfma_f32_16x16x32_bf16 v[18:21], v[150:153], v[208:211], v[18:21]
	v_mfma_f32_16x16x32_bf16 v[14:17], v[142:145], v[216:219], v[14:17]
	v_mfma_f32_16x16x32_bf16 v[10:13], v[150:153], v[216:219], v[10:13]
	v_mfma_f32_16x16x32_bf16 v[6:9], v[142:145], v[224:227], v[6:9]
	v_mfma_f32_16x16x32_bf16 v[2:5], v[150:153], v[224:227], v[2:5]
	v_mfma_f32_16x16x32_bf16 v[30:33], v[146:149], v[204:207], v[30:33]
	v_mfma_f32_16x16x32_bf16 v[26:29], v[180:183], v[204:207], v[26:29]
	v_mfma_f32_16x16x32_bf16 v[22:25], v[146:149], v[212:215], v[22:25]
	v_mfma_f32_16x16x32_bf16 v[18:21], v[180:183], v[212:215], v[18:21]
	v_mfma_f32_16x16x32_bf16 v[14:17], v[146:149], v[220:223], v[14:17]
	v_mfma_f32_16x16x32_bf16 v[10:13], v[180:183], v[220:223], v[10:13]
	v_mfma_f32_16x16x32_bf16 v[6:9], v[146:149], v[228:231], v[6:9]
	v_mfma_f32_16x16x32_bf16 v[2:5], v[180:183], v[228:231], v[2:5]
	v_mfma_f32_16x16x32_bf16 v[94:97], v[184:187], v[200:203], v[94:97]
	v_mfma_f32_16x16x32_bf16 v[90:93], v[192:195], v[200:203], v[90:93]
	v_mfma_f32_16x16x32_bf16 v[86:89], v[184:187], v[208:211], v[86:89]
	v_mfma_f32_16x16x32_bf16 v[82:85], v[192:195], v[208:211], v[82:85]
	v_mfma_f32_16x16x32_bf16 v[78:81], v[184:187], v[216:219], v[78:81]
	v_mfma_f32_16x16x32_bf16 v[74:77], v[192:195], v[216:219], v[74:77]
	v_mfma_f32_16x16x32_bf16 v[70:73], v[184:187], v[224:227], v[70:73]
	v_mfma_f32_16x16x32_bf16 v[62:65], v[192:195], v[224:227], v[62:65]
	v_mfma_f32_16x16x32_bf16 v[94:97], v[188:191], v[204:207], v[94:97]
	v_mfma_f32_16x16x32_bf16 v[90:93], v[196:199], v[204:207], v[90:93]
	v_mfma_f32_16x16x32_bf16 v[86:89], v[188:191], v[212:215], v[86:89]
	v_mfma_f32_16x16x32_bf16 v[82:85], v[196:199], v[212:215], v[82:85]
	v_mfma_f32_16x16x32_bf16 v[78:81], v[188:191], v[220:223], v[78:81]
	v_mfma_f32_16x16x32_bf16 v[74:77], v[196:199], v[220:223], v[74:77]
	v_mfma_f32_16x16x32_bf16 v[70:73], v[188:191], v[228:231], v[70:73]
	v_mfma_f32_16x16x32_bf16 v[62:65], v[196:199], v[228:231], v[62:65]
	s_cmp_lg_u32 s44, 12
	s_cbranch_scc1 .Ltail_bar_3
	s_cmp_eq_u64 s[12:13], 0
	s_cbranch_scc1 .Ltail_skip_3

; #define PG8_BAR __builtin_amdgcn_s_barrier()
; template <class Epi, bool ALIGN_EPI>
; __device__ __forceinline__ void gemm_phase(LAS unsigned char* lds, const Gemm g, const StaticOrder& S, const Epi& E) {
;     ...
;         for (int t = 0; t < nt; t += 2) {
;     ...
;         if constexpr (ALIGN_EPI) { if (wr == 0) PG8_BAR; }
.Ltail_skip_3:
	s_add_i32 s44, s44, 2
	s_add_u32 s6, s6, 0x100
	s_addc_u32 s7, s7, 0
	s_add_u32 s42, s42, 0x100
	s_addc_u32 s43, s43, 0
	s_cmp_gt_u32 s44, 13
	s_cbranch_scc0 .LBB0_603

; #define PG8_STAGE(bufoff, gbase, voff) do { _Pragma("unroll") for (int _i = 0; _i < 2; ++_i) \
;         __builtin_amdgcn_global_load_lds((const unsigned*)((const char*)(gbase) + (voff)[_i]), (LAS unsigned*)(lds + (bufoff) + ldsw + _i * 8192), 16, 0, 0); } while (0)
; #define PG8_LDA(dst, b, h) do { _Pragma("unroll") for (int m = 0; m < 4; ++m) _Pragma("unroll") for (int k = 0; k < 2; ++k) dst[m][k] = *(const LAS bf16x8*)(lds + PG8_SA(b, h) + aoff + m * 2048 + k * 1024); } while (0)
; #define PG8_LDB(dst, b, h) do { _Pragma("unroll") for (int n = 0; n < 2; ++n) _Pragma("unroll") for (int k = 0; k < 2; ++k) dst[n][k] = *(const LAS bf16x8*)(lds + PG8_SB(b, h) + boff + n * 2048 + k * 1024); } while (0)
; #define PG8_MMA(ai, bj, At, Bt) do { __builtin_amdgcn_s_setprio(1); _Pragma("unroll") for (int m = 0; m < 4; ++m) _Pragma("unroll") for (int n = 0; n < 2; ++n) _Pragma("unroll") for (int k = 0; k < 2; ++k) \
;         acc[ai][bj][m][n] = __builtin_amdgcn_mfma_f32_16x16x32_bf16(Bt[n][k], At[m][k], acc[ai][bj][m][n], 0, 0, 0); __builtin_amdgcn_s_setprio(0); } while (0)
; #define PG8_WAIT_V(n) asm volatile("s_waitcnt vmcnt(" #n ")" ::: "memory")
; #define PG8_WAIT_L(n) asm volatile("s_waitcnt lgkmcnt(" #n ")" ::: "memory")
; #define PG8_BAR __builtin_amdgcn_s_barrier()
; #define PG8_SCHED __builtin_amdgcn_sched_barrier(0)
; template <class Epi, bool ALIGN_EPI>
; __device__ __forceinline__ void gemm_phase(LAS unsigned char* lds, const Gemm g, const StaticOrder& S, const Epi& E) {
;     ...
;         for (int t = 0; t < nt; t += 2) {
;             const bool last = (t == nt - 2);
;             const char* a1 = cA + (size_t)(t + 1) * kstep;
;             const char* a2 = last ? nA : cA + (size_t)(t + 2) * kstep; const char* b2 = last ? nB : cB + (size_t)(t + 2) * kstep;
;             const char* a3 = a2 + kstep; const char* b3 = b2 + kstep;
;             PG8_LDB(B0, 0, 0); PG8_LDB(B1, 0, 1); PG8_SCHED; PG8_LDA(At, 0, 0); PG8_STAGE(PG8_SA(1, 1), a1 + hstepA, voffA);
;             PG8_WAIT_V(8); PG8_WAIT_L(0); PG8_BAR; PG8_MMA(0, 0, At, B0); PG8_MMA(0, 1, At, B1); PG8_BAR; PG8_SCHED;
;             PG8_LDA(At, 0, 1); PG8_STAGE(PG8_SB(0, 0), b2, voffB); PG8_STAGE(PG8_SB(0, 1), b2 + hstepB, voffB); PG8_STAGE(PG8_SA(0, 0), a2, voffA);
.LBB0_719:
	s_add_u32 s10, s8, 0x100
	s_addc_u32 s11, s9, 0
	s_add_i32 s46, 0, 0x10000
	s_cmp_eq_u32 s45, 40
	s_cselect_b32 s27, s23, s11
	s_cselect_b32 s26, s22, s10
	v_add_u32_e32 v152, s46, v160
	s_cselect_b32 s13, s25, s44
	s_cselect_b32 s12, s24, s29
	s_add_i32 s47, 0, 0x14000
	ds_read_b128 v[130:133], v152
	ds_read_b128 v[134:137], v152 offset:1024
	ds_read_b128 v[148:151], v152 offset:2048
	ds_read_b128 v[156:159], v152 offset:3072
	v_add_u32_e32 v152, s47, v160
	ds_read_b128 v[180:183], v152
	ds_read_b128 v[184:187], v152 offset:1024
	ds_read_b128 v[188:191], v152 offset:2048
	ds_read_b128 v[192:195], v152 offset:3072
	v_lshl_add_u64 v[152:153], s[8:9], 0, v[144:145]
	s_add_i32 m0, s35, 0xc000
	ds_read_b128 v[196:199], v161
	ds_read_b128 v[200:203], v161 offset:1024
	ds_read_b128 v[204:207], v161 offset:2048
	ds_read_b128 v[208:211], v161 offset:3072
	ds_read_b128 v[212:215], v161 offset:4096
	ds_read_b128 v[216:219], v161 offset:5120
	ds_read_b128 v[220:223], v161 offset:6144
	ds_read_b128 v[224:227], v161 offset:7168
	global_load_lds_dwordx4 v[152:153], off
	v_lshl_add_u64 v[152:153], s[8:9], 0, v[146:147]
	s_add_i32 m0, s35, 0xe000
	s_nop 0
	global_load_lds_dwordx4 v[152:153], off
	s_waitcnt vmcnt(8)
	s_waitcnt lgkmcnt(0)
	s_barrier
	s_waitcnt lgkmcnt(0)
	v_mfma_f32_16x16x32_bf16 v[126:129], v[130:133], v[196:199], v[126:129]
	v_mfma_f32_16x16x32_bf16 v[122:125], v[148:151], v[196:199], v[122:125]
	v_mfma_f32_16x16x32_bf16 v[110:113], v[130:133], v[204:207], v[110:113]
	v_mfma_f32_16x16x32_bf16 v[106:109], v[148:151], v[204:207], v[106:109]
	v_mfma_f32_16x16x32_bf16 v[94:97], v[130:133], v[212:215], v[94:97]
	v_mfma_f32_16x16x32_bf16 v[90:93], v[148:151], v[212:215], v[90:93]
	v_mfma_f32_16x16x32_bf16 v[78:81], v[130:133], v[220:223], v[78:81]
	v_mfma_f32_16x16x32_bf16 v[74:77], v[148:151], v[220:223], v[74:77]
	v_mfma_f32_16x16x32_bf16 v[126:129], v[134:137], v[200:203], v[126:129]
	v_mfma_f32_16x16x32_bf16 v[122:125], v[156:159], v[200:203], v[122:125]
	v_mfma_f32_16x16x32_bf16 v[110:113], v[134:137], v[208:211], v[110:113]
	v_mfma_f32_16x16x32_bf16 v[106:109], v[156:159], v[208:211], v[106:109]
	v_mfma_f32_16x16x32_bf16 v[94:97], v[134:137], v[216:219], v[94:97]
	v_mfma_f32_16x16x32_bf16 v[90:93], v[156:159], v[216:219], v[90:93]
	v_mfma_f32_16x16x32_bf16 v[78:81], v[134:137], v[224:227], v[78:81]
	v_mfma_f32_16x16x32_bf16 v[74:77], v[156:159], v[224:227], v[74:77]
	v_mfma_f32_16x16x32_bf16 v[118:121], v[180:183], v[196:199], v[118:121]
	v_mfma_f32_16x16x32_bf16 v[114:117], v[188:191], v[196:199], v[114:117]
	v_mfma_f32_16x16x32_bf16 v[102:105], v[180:183], v[204:207], v[102:105]
	v_mfma_f32_16x16x32_bf16 v[98:101], v[188:191], v[204:207], v[98:101]
	v_mfma_f32_16x16x32_bf16 v[86:89], v[180:183], v[212:215], v[86:89]
	v_mfma_f32_16x16x32_bf16 v[82:85], v[188:191], v[212:215], v[82:85]
	v_mfma_f32_16x16x32_bf16 v[70:73], v[180:183], v[220:223], v[70:73]
	v_mfma_f32_16x16x32_bf16 v[66:69], v[188:191], v[220:223], v[66:69]
	v_mfma_f32_16x16x32_bf16 v[118:121], v[184:187], v[200:203], v[118:121]
	v_mfma_f32_16x16x32_bf16 v[114:117], v[192:195], v[200:203], v[114:117]
	v_mfma_f32_16x16x32_bf16 v[102:105], v[184:187], v[208:211], v[102:105]
	v_mfma_f32_16x16x32_bf16 v[98:101], v[192:195], v[208:211], v[98:101]
	v_mfma_f32_16x16x32_bf16 v[86:89], v[184:187], v[216:219], v[86:89]
	v_mfma_f32_16x16x32_bf16 v[82:85], v[192:195], v[216:219], v[82:85]
	v_mfma_f32_16x16x32_bf16 v[70:73], v[184:187], v[224:227], v[70:73]
	v_mfma_f32_16x16x32_bf16 v[66:69], v[192:195], v[224:227], v[66:69]
	s_barrier
	s_add_i32 s8, s46, s30
	v_lshl_add_u64 v[152:153], s[12:13], 0, v[0:1]
	s_mov_b32 m0, s8
	ds_read_b128 v[196:199], v161 offset:16384
	ds_read_b128 v[200:203], v161 offset:17408
	ds_read_b128 v[204:207], v161 offset:18432
	ds_read_b128 v[208:211], v161 offset:19456
	ds_read_b128 v[212:215], v161 offset:20480
	ds_read_b128 v[216:219], v161 offset:21504
	ds_read_b128 v[220:223], v161 offset:22528
	ds_read_b128 v[224:227], v161 offset:23552
	global_load_lds_dwordx4 v[152:153], off
	s_add_i32 m0, s8, 0x2000
	s_add_u32 s8, s12, 0xb0000
	v_lshl_add_u64 v[162:163], s[12:13], 0, v[142:143]
	s_addc_u32 s9, s13, 0
	s_add_i32 s46, s47, s30
	global_load_lds_dwordx4 v[162:163], off
	v_lshl_add_u64 v[170:171], s[8:9], 0, v[0:1]
	s_mov_b32 m0, s46
	v_lshl_add_u64 v[172:173], s[26:27], 0, v[140:141]
	global_load_lds_dwordx4 v[170:171], off
	v_lshl_add_u64 v[170:171], s[8:9], 0, v[142:143]
	s_add_i32 m0, s46, 0x2000
	s_nop 0
	global_load_lds_dwordx4 v[170:171], off
	v_lshl_add_u64 v[170:171], s[26:27], 0, v[138:139]
	s_mov_b32 m0, s35
	s_nop 0
	global_load_lds_dwordx4 v[170:171], off
	s_mov_b32 m0, s36
	s_nop 0
	global_load_lds_dwordx4 v[172:173], off
	s_waitcnt vmcnt(8)
	s_waitcnt lgkmcnt(0)
	s_barrier
; #define PG8_STAGE(bufoff, gbase, voff) do { _Pragma("unroll") for (int _i = 0; _i < 2; ++_i) \
;         __builtin_amdgcn_global_load_lds((const unsigned*)((const char*)(gbase) + (voff)[_i]), (LAS unsigned*)(lds + (bufoff) + ldsw + _i * 8192), 16, 0, 0); } while (0)
; #define PG8_LDA(dst, b, h) do { _Pragma("unroll") for (int m = 0; m < 4; ++m) _Pragma("unroll") for (int k = 0; k < 2; ++k) dst[m][k] = *(const LAS bf16x8*)(lds + PG8_SA(b, h) + aoff + m * 2048 + k * 1024); } while (0)
; #define PG8_LDB(dst, b, h) do { _Pragma("unroll") for (int n = 0; n < 2; ++n) _Pragma("unroll") for (int k = 0; k < 2; ++k) dst[n][k] = *(const LAS bf16x8*)(lds + PG8_SB(b, h) + boff + n * 2048 + k * 1024); } while (0)
; #define PG8_MMA(ai, bj, At, Bt) do { __builtin_amdgcn_s_setprio(1); _Pragma("unroll") for (int m = 0; m < 4; ++m) _Pragma("unroll") for (int n = 0; n < 2; ++n) _Pragma("unroll") for (int k = 0; k < 2; ++k) \
;         acc[ai][bj][m][n] = __builtin_amdgcn_mfma_f32_16x16x32_bf16(Bt[n][k], At[m][k], acc[ai][bj][m][n], 0, 0, 0); __builtin_amdgcn_s_setprio(0); } while (0)
; #define PG8_WAIT_V(n) asm volatile("s_waitcnt vmcnt(" #n ")" ::: "memory")
; #define PG8_WAIT_L(n) asm volatile("s_waitcnt lgkmcnt(" #n ")" ::: "memory")
; #define PG8_BAR __builtin_amdgcn_s_barrier()
; #define PG8_SCHED __builtin_amdgcn_sched_barrier(0)
; template <class Epi, bool ALIGN_EPI>
; __device__ __forceinline__ void gemm_phase(LAS unsigned char* lds, const Gemm g, const StaticOrder& S, const Epi& E) {
;     ...
;             PG8_WAIT_V(8); PG8_WAIT_L(0); PG8_BAR; PG8_MMA(1, 0, At, B0); PG8_MMA(1, 1, At, B1); PG8_BAR; PG8_SCHED;
;             PG8_LDB(B0, 1, 0); PG8_LDB(B1, 1, 1); PG8_SCHED; PG8_LDA(At, 1, 0); PG8_STAGE(PG8_SA(0, 1), a2 + hstepA, voffA);
;             PG8_WAIT_V(8); PG8_WAIT_L(0); PG8_BAR; PG8_MMA(0, 0, At, B0); PG8_MMA(0, 1, At, B1); PG8_BAR; PG8_SCHED;
	s_waitcnt lgkmcnt(0)
	v_mfma_f32_16x16x32_bf16 v[62:65], v[130:133], v[196:199], v[62:65]
	v_mfma_f32_16x16x32_bf16 v[58:61], v[148:151], v[196:199], v[58:61]
	v_mfma_f32_16x16x32_bf16 v[46:49], v[130:133], v[204:207], v[46:49]
	v_mfma_f32_16x16x32_bf16 v[42:45], v[148:151], v[204:207], v[42:45]
	v_mfma_f32_16x16x32_bf16 v[30:33], v[130:133], v[212:215], v[30:33]
	v_mfma_f32_16x16x32_bf16 v[26:29], v[148:151], v[212:215], v[26:29]
	v_mfma_f32_16x16x32_bf16 v[14:17], v[130:133], v[220:223], v[14:17]
	v_mfma_f32_16x16x32_bf16 v[10:13], v[148:151], v[220:223], v[10:13]
	v_mfma_f32_16x16x32_bf16 v[62:65], v[134:137], v[200:203], v[62:65]
	v_mfma_f32_16x16x32_bf16 v[58:61], v[156:159], v[200:203], v[58:61]
	v_mfma_f32_16x16x32_bf16 v[46:49], v[134:137], v[208:211], v[46:49]
	v_mfma_f32_16x16x32_bf16 v[42:45], v[156:159], v[208:211], v[42:45]
	v_mfma_f32_16x16x32_bf16 v[30:33], v[134:137], v[216:219], v[30:33]
	v_mfma_f32_16x16x32_bf16 v[26:29], v[156:159], v[216:219], v[26:29]
	v_mfma_f32_16x16x32_bf16 v[14:17], v[134:137], v[224:227], v[14:17]
	v_mfma_f32_16x16x32_bf16 v[10:13], v[156:159], v[224:227], v[10:13]
	v_mfma_f32_16x16x32_bf16 v[54:57], v[180:183], v[196:199], v[54:57]
	v_mfma_f32_16x16x32_bf16 v[50:53], v[188:191], v[196:199], v[50:53]
	v_mfma_f32_16x16x32_bf16 v[38:41], v[180:183], v[204:207], v[38:41]
	v_mfma_f32_16x16x32_bf16 v[34:37], v[188:191], v[204:207], v[34:37]
	v_mfma_f32_16x16x32_bf16 v[22:25], v[180:183], v[212:215], v[22:25]
	v_mfma_f32_16x16x32_bf16 v[18:21], v[188:191], v[212:215], v[18:21]
	v_mfma_f32_16x16x32_bf16 v[6:9], v[180:183], v[220:223], v[6:9]
	v_mfma_f32_16x16x32_bf16 v[2:5], v[188:191], v[220:223], v[2:5]
	v_mfma_f32_16x16x32_bf16 v[54:57], v[184:187], v[200:203], v[54:57]
	v_mfma_f32_16x16x32_bf16 v[50:53], v[192:195], v[200:203], v[50:53]
	v_mfma_f32_16x16x32_bf16 v[38:41], v[184:187], v[208:211], v[38:41]
	v_mfma_f32_16x16x32_bf16 v[34:37], v[192:195], v[208:211], v[34:37]
	v_mfma_f32_16x16x32_bf16 v[22:25], v[184:187], v[216:219], v[22:25]
	v_mfma_f32_16x16x32_bf16 v[18:21], v[192:195], v[216:219], v[18:21]
	v_mfma_f32_16x16x32_bf16 v[6:9], v[184:187], v[224:227], v[6:9]
	v_mfma_f32_16x16x32_bf16 v[2:5], v[192:195], v[224:227], v[2:5]
	s_barrier
	s_add_i32 s46, 0, 0x18000
	s_add_i32 s47, 0, 0x1c000
	v_add_u32_e32 v156, s46, v160
	v_add_u32_e32 v164, s47, v160
	ds_read_b128 v[130:133], v156
	ds_read_b128 v[134:137], v156 offset:1024
	ds_read_b128 v[148:151], v156 offset:2048
	ds_read_b128 v[156:159], v156 offset:3072
	ds_read_b128 v[180:183], v164
	ds_read_b128 v[184:187], v164 offset:1024
	ds_read_b128 v[188:191], v164 offset:2048
	ds_read_b128 v[192:195], v164 offset:3072
	s_add_u32 s8, s26, 0xb0000
	s_addc_u32 s9, s27, 0
	s_mov_b32 m0, s37
	v_lshl_add_u64 v[228:229], s[8:9], 0, v[138:139]
	ds_read_b128 v[196:199], v161 offset:32768
	ds_read_b128 v[200:203], v161 offset:33792
	ds_read_b128 v[204:207], v161 offset:34816
	ds_read_b128 v[208:211], v161 offset:35840
	ds_read_b128 v[212:215], v161 offset:36864
	ds_read_b128 v[216:219], v161 offset:37888
	ds_read_b128 v[220:223], v161 offset:38912
	ds_read_b128 v[224:227], v161 offset:39936
	global_load_lds_dwordx4 v[228:229], off
	v_lshl_add_u64 v[228:229], s[8:9], 0, v[140:141]
	s_mov_b32 m0, s38
	s_nop 0
	global_load_lds_dwordx4 v[228:229], off
	s_waitcnt vmcnt(8)
	s_waitcnt lgkmcnt(0)
	s_barrier
	s_waitcnt lgkmcnt(0)
	v_mfma_f32_16x16x32_bf16 v[126:129], v[130:133], v[196:199], v[126:129]
	v_mfma_f32_16x16x32_bf16 v[122:125], v[148:151], v[196:199], v[122:125]
	v_mfma_f32_16x16x32_bf16 v[110:113], v[130:133], v[204:207], v[110:113]
	v_mfma_f32_16x16x32_bf16 v[106:109], v[148:151], v[204:207], v[106:109]
	v_mfma_f32_16x16x32_bf16 v[94:97], v[130:133], v[212:215], v[94:97]
	v_mfma_f32_16x16x32_bf16 v[90:93], v[148:151], v[212:215], v[90:93]
	v_mfma_f32_16x16x32_bf16 v[78:81], v[130:133], v[220:223], v[78:81]
	v_mfma_f32_16x16x32_bf16 v[74:77], v[148:151], v[220:223], v[74:77]
	v_mfma_f32_16x16x32_bf16 v[126:129], v[134:137], v[200:203], v[126:129]
	v_mfma_f32_16x16x32_bf16 v[122:125], v[156:159], v[200:203], v[122:125]
	v_mfma_f32_16x16x32_bf16 v[110:113], v[134:137], v[208:211], v[110:113]
	v_mfma_f32_16x16x32_bf16 v[106:109], v[156:159], v[208:211], v[106:109]
	v_mfma_f32_16x16x32_bf16 v[94:97], v[134:137], v[216:219], v[94:97]
	v_mfma_f32_16x16x32_bf16 v[90:93], v[156:159], v[216:219], v[90:93]
	v_mfma_f32_16x16x32_bf16 v[78:81], v[134:137], v[224:227], v[78:81]
	v_mfma_f32_16x16x32_bf16 v[74:77], v[156:159], v[224:227], v[74:77]
	v_mfma_f32_16x16x32_bf16 v[118:121], v[180:183], v[196:199], v[118:121]
	v_mfma_f32_16x16x32_bf16 v[114:117], v[188:191], v[196:199], v[114:117]
	v_mfma_f32_16x16x32_bf16 v[102:105], v[180:183], v[204:207], v[102:105]
	v_mfma_f32_16x16x32_bf16 v[98:101], v[188:191], v[204:207], v[98:101]
	v_mfma_f32_16x16x32_bf16 v[86:89], v[180:183], v[212:215], v[86:89]
	v_mfma_f32_16x16x32_bf16 v[82:85], v[188:191], v[212:215], v[82:85]
	v_mfma_f32_16x16x32_bf16 v[70:73], v[180:183], v[220:223], v[70:73]
	v_mfma_f32_16x16x32_bf16 v[66:69], v[188:191], v[220:223], v[66:69]
	v_mfma_f32_16x16x32_bf16 v[118:121], v[184:187], v[200:203], v[118:121]
	v_mfma_f32_16x16x32_bf16 v[114:117], v[192:195], v[200:203], v[114:117]
	v_mfma_f32_16x16x32_bf16 v[102:105], v[184:187], v[208:211], v[102:105]
	v_mfma_f32_16x16x32_bf16 v[98:101], v[192:195], v[208:211], v[98:101]
	v_mfma_f32_16x16x32_bf16 v[86:89], v[184:187], v[216:219], v[86:89]
	v_mfma_f32_16x16x32_bf16 v[82:85], v[192:195], v[216:219], v[82:85]
	v_mfma_f32_16x16x32_bf16 v[70:73], v[184:187], v[224:227], v[70:73]
	v_mfma_f32_16x16x32_bf16 v[66:69], v[192:195], v[224:227], v[66:69]
	s_barrier
; #define PG8_STAGE(bufoff, gbase, voff) do { _Pragma("unroll") for (int _i = 0; _i < 2; ++_i) \
;         __builtin_amdgcn_global_load_lds((const unsigned*)((const char*)(gbase) + (voff)[_i]), (LAS unsigned*)(lds + (bufoff) + ldsw + _i * 8192), 16, 0, 0); } while (0)
; #define PG8_LDA(dst, b, h) do { _Pragma("unroll") for (int m = 0; m < 4; ++m) _Pragma("unroll") for (int k = 0; k < 2; ++k) dst[m][k] = *(const LAS bf16x8*)(lds + PG8_SA(b, h) + aoff + m * 2048 + k * 1024); } while (0)
; #define PG8_MMA(ai, bj, At, Bt) do { __builtin_amdgcn_s_setprio(1); _Pragma("unroll") for (int m = 0; m < 4; ++m) _Pragma("unroll") for (int n = 0; n < 2; ++n) _Pragma("unroll") for (int k = 0; k < 2; ++k) \
;         acc[ai][bj][m][n] = __builtin_amdgcn_mfma_f32_16x16x32_bf16(Bt[n][k], At[m][k], acc[ai][bj][m][n], 0, 0, 0); __builtin_amdgcn_s_setprio(0); } while (0)
; #define PG8_WAIT_V(n) asm volatile("s_waitcnt vmcnt(" #n ")" ::: "memory")
; #define PG8_WAIT_L(n) asm volatile("s_waitcnt lgkmcnt(" #n ")" ::: "memory")
; #define PG8_BAR __builtin_amdgcn_s_barrier()
; #define PG8_SCHED __builtin_amdgcn_sched_barrier(0)
; template <class Epi, bool ALIGN_EPI>
; __device__ __forceinline__ void gemm_phase(LAS unsigned char* lds, const Gemm g, const StaticOrder& S, const Epi& E) {
;     ...
;             PG8_LDA(At, 1, 1); PG8_STAGE(PG8_SB(1, 0), b3, voffB); PG8_STAGE(PG8_SB(1, 1), b3 + hstepB, voffB); PG8_STAGE(PG8_SA(1, 0), a3, voffA);
;             PG8_WAIT_V(8); PG8_WAIT_L(0); PG8_BAR; PG8_MMA(1, 0, At, B0); PG8_MMA(1, 1, At, B1); PG8_BAR; PG8_SCHED;
	s_add_i32 s8, s46, s30
	v_lshl_add_u64 v[152:153], v[152:153], 0, s[94:95]
	s_mov_b32 m0, s8
	ds_read_b128 v[196:199], v161 offset:49152
	ds_read_b128 v[200:203], v161 offset:50176
	ds_read_b128 v[204:207], v161 offset:51200
	ds_read_b128 v[208:211], v161 offset:52224
	ds_read_b128 v[212:215], v161 offset:53248
	ds_read_b128 v[216:219], v161 offset:54272
	ds_read_b128 v[220:223], v161 offset:55296
	ds_read_b128 v[224:227], v161 offset:56320
	global_load_lds_dwordx4 v[152:153], off
	s_add_i32 m0, s8, 0x2000
	s_add_u32 s8, s12, 0xb0080
	v_lshl_add_u64 v[152:153], v[162:163], 0, s[94:95]
	s_addc_u32 s9, s13, 0
	s_add_i32 s12, s47, s30
	global_load_lds_dwordx4 v[152:153], off
	v_lshl_add_u64 v[152:153], s[8:9], 0, v[0:1]
	s_mov_b32 m0, s12
	s_nop 0
	global_load_lds_dwordx4 v[152:153], off
	v_lshl_add_u64 v[152:153], s[8:9], 0, v[142:143]
	s_add_i32 m0, s12, 0x2000
	s_nop 0
	global_load_lds_dwordx4 v[152:153], off
	v_lshl_add_u64 v[152:153], v[170:171], 0, s[94:95]
	s_mov_b32 m0, s39
	s_nop 0
	global_load_lds_dwordx4 v[152:153], off
	v_lshl_add_u64 v[152:153], v[172:173], 0, s[94:95]
	s_mov_b32 m0, s40
	s_nop 0
	global_load_lds_dwordx4 v[152:153], off
	s_waitcnt vmcnt(8)
	s_waitcnt lgkmcnt(0)
	s_barrier
	s_waitcnt lgkmcnt(0)
	v_mfma_f32_16x16x32_bf16 v[62:65], v[130:133], v[196:199], v[62:65]
	v_mfma_f32_16x16x32_bf16 v[58:61], v[148:151], v[196:199], v[58:61]
	v_mfma_f32_16x16x32_bf16 v[46:49], v[130:133], v[204:207], v[46:49]
	v_mfma_f32_16x16x32_bf16 v[42:45], v[148:151], v[204:207], v[42:45]
	v_mfma_f32_16x16x32_bf16 v[30:33], v[130:133], v[212:215], v[30:33]
	v_mfma_f32_16x16x32_bf16 v[26:29], v[148:151], v[212:215], v[26:29]
	v_mfma_f32_16x16x32_bf16 v[14:17], v[130:133], v[220:223], v[14:17]
	v_mfma_f32_16x16x32_bf16 v[10:13], v[148:151], v[220:223], v[10:13]
	v_mfma_f32_16x16x32_bf16 v[62:65], v[134:137], v[200:203], v[62:65]
	v_mfma_f32_16x16x32_bf16 v[58:61], v[156:159], v[200:203], v[58:61]
	v_mfma_f32_16x16x32_bf16 v[46:49], v[134:137], v[208:211], v[46:49]
	v_mfma_f32_16x16x32_bf16 v[42:45], v[156:159], v[208:211], v[42:45]
	v_mfma_f32_16x16x32_bf16 v[30:33], v[134:137], v[216:219], v[30:33]
	v_mfma_f32_16x16x32_bf16 v[26:29], v[156:159], v[216:219], v[26:29]
	v_mfma_f32_16x16x32_bf16 v[14:17], v[134:137], v[224:227], v[14:17]
	v_mfma_f32_16x16x32_bf16 v[10:13], v[156:159], v[224:227], v[10:13]
	v_mfma_f32_16x16x32_bf16 v[54:57], v[180:183], v[196:199], v[54:57]
	v_mfma_f32_16x16x32_bf16 v[50:53], v[188:191], v[196:199], v[50:53]
	v_mfma_f32_16x16x32_bf16 v[38:41], v[180:183], v[204:207], v[38:41]
	v_mfma_f32_16x16x32_bf16 v[34:37], v[188:191], v[204:207], v[34:37]
	v_mfma_f32_16x16x32_bf16 v[22:25], v[180:183], v[212:215], v[22:25]
	v_mfma_f32_16x16x32_bf16 v[18:21], v[188:191], v[212:215], v[18:21]
	v_mfma_f32_16x16x32_bf16 v[6:9], v[180:183], v[220:223], v[6:9]
	v_mfma_f32_16x16x32_bf16 v[2:5], v[188:191], v[220:223], v[2:5]
	v_mfma_f32_16x16x32_bf16 v[54:57], v[184:187], v[200:203], v[54:57]
	v_mfma_f32_16x16x32_bf16 v[50:53], v[192:195], v[200:203], v[50:53]
	v_mfma_f32_16x16x32_bf16 v[38:41], v[184:187], v[208:211], v[38:41]
	v_mfma_f32_16x16x32_bf16 v[34:37], v[192:195], v[208:211], v[34:37]
	v_mfma_f32_16x16x32_bf16 v[22:25], v[184:187], v[216:219], v[22:25]
	v_mfma_f32_16x16x32_bf16 v[18:21], v[192:195], v[216:219], v[18:21]
	v_mfma_f32_16x16x32_bf16 v[6:9], v[184:187], v[224:227], v[6:9]
	v_mfma_f32_16x16x32_bf16 v[2:5], v[192:195], v[224:227], v[2:5]
	s_cmp_lg_u32 s45, 40
	s_cbranch_scc1 .Ltail_bar_2
	s_cmp_eq_u64 s[16:17], 0
	s_cbranch_scc1 .Ltail_skip_2

; #define PG8_BAR __builtin_amdgcn_s_barrier()
; template <class Epi, bool ALIGN_EPI>
; __device__ __forceinline__ void gemm_phase(LAS unsigned char* lds, const Gemm g, const StaticOrder& S, const Epi& E) {
;     ...
;         for (int t = 0; t < nt; t += 2) {
;     ...
;         if constexpr (ALIGN_EPI) { if (wr == 0) PG8_BAR; }
.Ltail_skip_2:
	s_add_i32 s45, s45, 2
	s_add_u32 s29, s29, 0x100
	s_addc_u32 s44, s44, 0
	s_cmp_gt_u32 s45, 41
	s_mov_b64 s[8:9], s[10:11]
	s_cbranch_scc0 .LBB0_719

; #define PG8_STAGE(bufoff, gbase, voff) do { _Pragma("unroll") for (int _i = 0; _i < 2; ++_i) \
;         __builtin_amdgcn_global_load_lds((const unsigned*)((const char*)(gbase) + (voff)[_i]), (LAS unsigned*)(lds + (bufoff) + ldsw + _i * 8192), 16, 0, 0); } while (0)
; #define PG8_LDA(dst, b, h) do { _Pragma("unroll") for (int m = 0; m < 4; ++m) _Pragma("unroll") for (int k = 0; k < 2; ++k) dst[m][k] = *(const LAS bf16x8*)(lds + PG8_SA(b, h) + aoff + m * 2048 + k * 1024); } while (0)
; #define PG8_LDB(dst, b, h) do { _Pragma("unroll") for (int n = 0; n < 2; ++n) _Pragma("unroll") for (int k = 0; k < 2; ++k) dst[n][k] = *(const LAS bf16x8*)(lds + PG8_SB(b, h) + boff + n * 2048 + k * 1024); } while (0)
; #define PG8_MMA(ai, bj, At, Bt) do { __builtin_amdgcn_s_setprio(1); _Pragma("unroll") for (int m = 0; m < 4; ++m) _Pragma("unroll") for (int n = 0; n < 2; ++n) _Pragma("unroll") for (int k = 0; k < 2; ++k) \
;         acc[ai][bj][m][n] = __builtin_amdgcn_mfma_f32_16x16x32_bf16(Bt[n][k], At[m][k], acc[ai][bj][m][n], 0, 0, 0); __builtin_amdgcn_s_setprio(0); } while (0)
; #define PG8_WAIT_V(n) asm volatile("s_waitcnt vmcnt(" #n ")" ::: "memory")
; #define PG8_WAIT_L(n) asm volatile("s_waitcnt lgkmcnt(" #n ")" ::: "memory")
; #define PG8_BAR __builtin_amdgcn_s_barrier()
; #define PG8_SCHED __builtin_amdgcn_sched_barrier(0)
; template <class Epi, bool ALIGN_EPI>
; __device__ __forceinline__ void gemm_phase(LAS unsigned char* lds, const Gemm g, const StaticOrder& S, const Epi& E) {
;     ...
;         for (int t = 0; t < nt; t += 2) {
;             const bool last = (t == nt - 2);
;             const char* a1 = cA + (size_t)(t + 1) * kstep;
;             const char* a2 = last ? nA : cA + (size_t)(t + 2) * kstep; const char* b2 = last ? nB : cB + (size_t)(t + 2) * kstep;
;             const char* a3 = a2 + kstep; const char* b3 = b2 + kstep;
;             PG8_LDB(B0, 0, 0); PG8_LDB(B1, 0, 1); PG8_SCHED; PG8_LDA(At, 0, 0); PG8_STAGE(PG8_SA(1, 1), a1 + hstepA, voffA);
;             PG8_WAIT_V(8); PG8_WAIT_L(0); PG8_BAR; PG8_MMA(0, 0, At, B0); PG8_MMA(0, 1, At, B1); PG8_BAR; PG8_SCHED;
;             PG8_LDA(At, 0, 1); PG8_STAGE(PG8_SB(0, 0), b2, voffB); PG8_STAGE(PG8_SB(0, 1), b2 + hstepB, voffB); PG8_STAGE(PG8_SA(0, 0), a2, voffA);
.LBB0_849:
	s_add_u32 s18, s6, 0xfffc0080
	s_addc_u32 s19, s7, -1
	s_add_i32 s39, 0, 0x10000
	s_cmp_eq_u32 s38, 12
	s_cselect_b32 s21, s1, s19
	s_cselect_b32 s20, s34, s18
	v_add_u32_e32 v152, s39, v144
	s_cselect_b32 s19, s11, s37
	s_cselect_b32 s18, s35, s36
	s_add_i32 s42, 0, 0x14000
	ds_read_b128 v[140:143], v152
	ds_read_b128 v[148:151], v152 offset:1024
	ds_read_b128 v[156:159], v152 offset:2048
	ds_read_b128 v[180:183], v152 offset:3072
	v_add_u32_e32 v152, s42, v144
	ds_read_b128 v[184:187], v152
	ds_read_b128 v[188:191], v152 offset:1024
	ds_read_b128 v[192:195], v152 offset:2048
	ds_read_b128 v[196:199], v152 offset:3072
	v_lshl_add_u64 v[152:153], s[6:7], 0, v[136:137]
	s_add_i32 m0, s23, 0xc000
	ds_read_b128 v[200:203], v146
	ds_read_b128 v[204:207], v146 offset:1024
	ds_read_b128 v[208:211], v146 offset:2048
	ds_read_b128 v[212:215], v146 offset:3072
	ds_read_b128 v[216:219], v146 offset:4096
	ds_read_b128 v[220:223], v146 offset:5120
	ds_read_b128 v[224:227], v146 offset:6144
	ds_read_b128 v[228:231], v146 offset:7168
	global_load_lds_dwordx4 v[152:153], off
	v_lshl_add_u64 v[152:153], s[6:7], 0, v[138:139]
	s_add_i32 m0, s23, 0xe000
	s_nop 0
	global_load_lds_dwordx4 v[152:153], off
	s_waitcnt vmcnt(8)
	s_waitcnt lgkmcnt(0)
	s_barrier
	s_waitcnt lgkmcnt(0)
	v_mfma_f32_16x16x32_bf16 v[126:129], v[140:143], v[200:203], v[126:129]
	v_mfma_f32_16x16x32_bf16 v[118:121], v[156:159], v[200:203], v[118:121]
	v_mfma_f32_16x16x32_bf16 v[110:113], v[140:143], v[208:211], v[110:113]
	v_mfma_f32_16x16x32_bf16 v[102:105], v[156:159], v[208:211], v[102:105]
	v_mfma_f32_16x16x32_bf16 v[94:97], v[140:143], v[216:219], v[94:97]
	v_mfma_f32_16x16x32_bf16 v[86:89], v[156:159], v[216:219], v[86:89]
	v_mfma_f32_16x16x32_bf16 v[78:81], v[140:143], v[224:227], v[78:81]
	v_mfma_f32_16x16x32_bf16 v[70:73], v[156:159], v[224:227], v[70:73]
	v_mfma_f32_16x16x32_bf16 v[126:129], v[148:151], v[204:207], v[126:129]
	v_mfma_f32_16x16x32_bf16 v[118:121], v[180:183], v[204:207], v[118:121]
	v_mfma_f32_16x16x32_bf16 v[110:113], v[148:151], v[212:215], v[110:113]
	v_mfma_f32_16x16x32_bf16 v[102:105], v[180:183], v[212:215], v[102:105]
	v_mfma_f32_16x16x32_bf16 v[94:97], v[148:151], v[220:223], v[94:97]
	v_mfma_f32_16x16x32_bf16 v[86:89], v[180:183], v[220:223], v[86:89]
	v_mfma_f32_16x16x32_bf16 v[78:81], v[148:151], v[228:231], v[78:81]
	v_mfma_f32_16x16x32_bf16 v[70:73], v[180:183], v[228:231], v[70:73]
	v_mfma_f32_16x16x32_bf16 v[122:125], v[184:187], v[200:203], v[122:125]
	v_mfma_f32_16x16x32_bf16 v[114:117], v[192:195], v[200:203], v[114:117]
	v_mfma_f32_16x16x32_bf16 v[106:109], v[184:187], v[208:211], v[106:109]
	v_mfma_f32_16x16x32_bf16 v[98:101], v[192:195], v[208:211], v[98:101]
	v_mfma_f32_16x16x32_bf16 v[90:93], v[184:187], v[216:219], v[90:93]
	v_mfma_f32_16x16x32_bf16 v[82:85], v[192:195], v[216:219], v[82:85]
	v_mfma_f32_16x16x32_bf16 v[74:77], v[184:187], v[224:227], v[74:77]
	v_mfma_f32_16x16x32_bf16 v[66:69], v[192:195], v[224:227], v[66:69]
	v_mfma_f32_16x16x32_bf16 v[122:125], v[188:191], v[204:207], v[122:125]
	v_mfma_f32_16x16x32_bf16 v[114:117], v[196:199], v[204:207], v[114:117]
	v_mfma_f32_16x16x32_bf16 v[106:109], v[188:191], v[212:215], v[106:109]
	v_mfma_f32_16x16x32_bf16 v[98:101], v[196:199], v[212:215], v[98:101]
	v_mfma_f32_16x16x32_bf16 v[90:93], v[188:191], v[220:223], v[90:93]
	v_mfma_f32_16x16x32_bf16 v[82:85], v[196:199], v[220:223], v[82:85]
	v_mfma_f32_16x16x32_bf16 v[74:77], v[188:191], v[228:231], v[74:77]
	v_mfma_f32_16x16x32_bf16 v[66:69], v[196:199], v[228:231], v[66:69]
	s_barrier
	s_add_i32 s39, s39, s22
	v_lshl_add_u64 v[152:153], s[18:19], 0, v[0:1]
	s_mov_b32 m0, s39
	ds_read_b128 v[200:203], v146 offset:16384
	ds_read_b128 v[204:207], v146 offset:17408
	ds_read_b128 v[208:211], v146 offset:18432
	ds_read_b128 v[212:215], v146 offset:19456
	ds_read_b128 v[216:219], v146 offset:20480
	ds_read_b128 v[220:223], v146 offset:21504
	ds_read_b128 v[224:227], v146 offset:22528
	ds_read_b128 v[228:231], v146 offset:23552
	global_load_lds_dwordx4 v[152:153], off
	s_add_i32 m0, s39, 0x2000
	s_add_u32 s40, s18, 0x40000
	v_lshl_add_u64 v[160:161], s[18:19], 0, v[130:131]
	s_addc_u32 s41, s19, 0
	s_add_i32 s39, s42, s22
	global_load_lds_dwordx4 v[160:161], off
	v_lshl_add_u64 v[162:163], s[40:41], 0, v[0:1]
	s_mov_b32 m0, s39
	v_lshl_add_u64 v[170:171], s[20:21], 0, v[132:133]
	global_load_lds_dwordx4 v[162:163], off
	v_lshl_add_u64 v[162:163], s[40:41], 0, v[130:131]
	s_add_i32 m0, s39, 0x2000
	s_nop 0
	global_load_lds_dwordx4 v[162:163], off
	v_lshl_add_u64 v[162:163], s[20:21], 0, v[134:135]
	s_mov_b32 m0, s23
	s_nop 0
	global_load_lds_dwordx4 v[162:163], off
	s_mov_b32 m0, s24
	s_nop 0
	global_load_lds_dwordx4 v[170:171], off
	s_waitcnt vmcnt(8)
	s_waitcnt lgkmcnt(0)
	s_barrier
; #define PG8_STAGE(bufoff, gbase, voff) do { _Pragma("unroll") for (int _i = 0; _i < 2; ++_i) \
;         __builtin_amdgcn_global_load_lds((const unsigned*)((const char*)(gbase) + (voff)[_i]), (LAS unsigned*)(lds + (bufoff) + ldsw + _i * 8192), 16, 0, 0); } while (0)
; #define PG8_LDA(dst, b, h) do { _Pragma("unroll") for (int m = 0; m < 4; ++m) _Pragma("unroll") for (int k = 0; k < 2; ++k) dst[m][k] = *(const LAS bf16x8*)(lds + PG8_SA(b, h) + aoff + m * 2048 + k * 1024); } while (0)
; #define PG8_LDB(dst, b, h) do { _Pragma("unroll") for (int n = 0; n < 2; ++n) _Pragma("unroll") for (int k = 0; k < 2; ++k) dst[n][k] = *(const LAS bf16x8*)(lds + PG8_SB(b, h) + boff + n * 2048 + k * 1024); } while (0)
; #define PG8_MMA(ai, bj, At, Bt) do { __builtin_amdgcn_s_setprio(1); _Pragma("unroll") for (int m = 0; m < 4; ++m) _Pragma("unroll") for (int n = 0; n < 2; ++n) _Pragma("unroll") for (int k = 0; k < 2; ++k) \
;         acc[ai][bj][m][n] = __builtin_amdgcn_mfma_f32_16x16x32_bf16(Bt[n][k], At[m][k], acc[ai][bj][m][n], 0, 0, 0); __builtin_amdgcn_s_setprio(0); } while (0)
; #define PG8_WAIT_V(n) asm volatile("s_waitcnt vmcnt(" #n ")" ::: "memory")
; #define PG8_WAIT_L(n) asm volatile("s_waitcnt lgkmcnt(" #n ")" ::: "memory")
; #define PG8_BAR __builtin_amdgcn_s_barrier()
; #define PG8_SCHED __builtin_amdgcn_sched_barrier(0)
; template <class Epi, bool ALIGN_EPI>
; __device__ __forceinline__ void gemm_phase(LAS unsigned char* lds, const Gemm g, const StaticOrder& S, const Epi& E) {
;     ...
;             PG8_WAIT_V(8); PG8_WAIT_L(0); PG8_BAR; PG8_MMA(1, 0, At, B0); PG8_MMA(1, 1, At, B1); PG8_BAR; PG8_SCHED;
;             PG8_LDB(B0, 1, 0); PG8_LDB(B1, 1, 1); PG8_SCHED; PG8_LDA(At, 1, 0); PG8_STAGE(PG8_SA(0, 1), a2 + hstepA, voffA);
;             PG8_WAIT_V(8); PG8_WAIT_L(0); PG8_BAR; PG8_MMA(0, 0, At, B0); PG8_MMA(0, 1, At, B1); PG8_BAR; PG8_SCHED;
	s_waitcnt lgkmcnt(0)
	v_mfma_f32_16x16x32_bf16 v[62:65], v[140:143], v[200:203], v[62:65]
	v_mfma_f32_16x16x32_bf16 v[54:57], v[156:159], v[200:203], v[54:57]
	v_mfma_f32_16x16x32_bf16 v[46:49], v[140:143], v[208:211], v[46:49]
	v_mfma_f32_16x16x32_bf16 v[38:41], v[156:159], v[208:211], v[38:41]
	v_mfma_f32_16x16x32_bf16 v[30:33], v[140:143], v[216:219], v[30:33]
	v_mfma_f32_16x16x32_bf16 v[22:25], v[156:159], v[216:219], v[22:25]
	v_mfma_f32_16x16x32_bf16 v[14:17], v[140:143], v[224:227], v[14:17]
	v_mfma_f32_16x16x32_bf16 v[6:9], v[156:159], v[224:227], v[6:9]
	v_mfma_f32_16x16x32_bf16 v[62:65], v[148:151], v[204:207], v[62:65]
	v_mfma_f32_16x16x32_bf16 v[54:57], v[180:183], v[204:207], v[54:57]
	v_mfma_f32_16x16x32_bf16 v[46:49], v[148:151], v[212:215], v[46:49]
	v_mfma_f32_16x16x32_bf16 v[38:41], v[180:183], v[212:215], v[38:41]
	v_mfma_f32_16x16x32_bf16 v[30:33], v[148:151], v[220:223], v[30:33]
	v_mfma_f32_16x16x32_bf16 v[22:25], v[180:183], v[220:223], v[22:25]
	v_mfma_f32_16x16x32_bf16 v[14:17], v[148:151], v[228:231], v[14:17]
	v_mfma_f32_16x16x32_bf16 v[6:9], v[180:183], v[228:231], v[6:9]
	v_mfma_f32_16x16x32_bf16 v[58:61], v[184:187], v[200:203], v[58:61]
	v_mfma_f32_16x16x32_bf16 v[50:53], v[192:195], v[200:203], v[50:53]
	v_mfma_f32_16x16x32_bf16 v[42:45], v[184:187], v[208:211], v[42:45]
	v_mfma_f32_16x16x32_bf16 v[34:37], v[192:195], v[208:211], v[34:37]
	v_mfma_f32_16x16x32_bf16 v[26:29], v[184:187], v[216:219], v[26:29]
	v_mfma_f32_16x16x32_bf16 v[18:21], v[192:195], v[216:219], v[18:21]
	v_mfma_f32_16x16x32_bf16 v[10:13], v[184:187], v[224:227], v[10:13]
	v_mfma_f32_16x16x32_bf16 v[2:5], v[192:195], v[224:227], v[2:5]
	v_mfma_f32_16x16x32_bf16 v[58:61], v[188:191], v[204:207], v[58:61]
	v_mfma_f32_16x16x32_bf16 v[50:53], v[196:199], v[204:207], v[50:53]
	v_mfma_f32_16x16x32_bf16 v[42:45], v[188:191], v[212:215], v[42:45]
	v_mfma_f32_16x16x32_bf16 v[34:37], v[196:199], v[212:215], v[34:37]
	v_mfma_f32_16x16x32_bf16 v[26:29], v[188:191], v[220:223], v[26:29]
	v_mfma_f32_16x16x32_bf16 v[18:21], v[196:199], v[220:223], v[18:21]
	v_mfma_f32_16x16x32_bf16 v[10:13], v[188:191], v[228:231], v[10:13]
	v_mfma_f32_16x16x32_bf16 v[2:5], v[196:199], v[228:231], v[2:5]
	s_barrier
	s_add_i32 s39, 0, 0x18000
	v_add_u32_e32 v164, s39, v144
	s_add_i32 s40, 0, 0x1c000
	ds_read_b128 v[140:143], v164
	ds_read_b128 v[148:151], v164 offset:1024
	ds_read_b128 v[156:159], v164 offset:2048
	ds_read_b128 v[180:183], v164 offset:3072
	v_add_u32_e32 v164, s40, v144
	ds_read_b128 v[184:187], v164
	ds_read_b128 v[188:191], v164 offset:1024
	ds_read_b128 v[192:195], v164 offset:2048
	ds_read_b128 v[196:199], v164 offset:3072
	s_add_u32 s20, s20, 0x40000
	s_addc_u32 s21, s21, 0
	s_mov_b32 m0, s25
	v_lshl_add_u64 v[172:173], s[20:21], 0, v[134:135]
	ds_read_b128 v[200:203], v146 offset:32768
	ds_read_b128 v[204:207], v146 offset:33792
	ds_read_b128 v[208:211], v146 offset:34816
	ds_read_b128 v[212:215], v146 offset:35840
	ds_read_b128 v[216:219], v146 offset:36864
	ds_read_b128 v[220:223], v146 offset:37888
	ds_read_b128 v[224:227], v146 offset:38912
	ds_read_b128 v[228:231], v146 offset:39936
	global_load_lds_dwordx4 v[172:173], off
	v_lshl_add_u64 v[172:173], s[20:21], 0, v[132:133]
	s_mov_b32 m0, s26
	s_nop 0
	global_load_lds_dwordx4 v[172:173], off
	s_waitcnt vmcnt(8)
	s_waitcnt lgkmcnt(0)
	s_barrier
	s_waitcnt lgkmcnt(0)
	v_mfma_f32_16x16x32_bf16 v[126:129], v[140:143], v[200:203], v[126:129]
	v_mfma_f32_16x16x32_bf16 v[118:121], v[156:159], v[200:203], v[118:121]
	v_mfma_f32_16x16x32_bf16 v[110:113], v[140:143], v[208:211], v[110:113]
	v_mfma_f32_16x16x32_bf16 v[102:105], v[156:159], v[208:211], v[102:105]
	v_mfma_f32_16x16x32_bf16 v[94:97], v[140:143], v[216:219], v[94:97]
	v_mfma_f32_16x16x32_bf16 v[86:89], v[156:159], v[216:219], v[86:89]
	v_mfma_f32_16x16x32_bf16 v[78:81], v[140:143], v[224:227], v[78:81]
	v_mfma_f32_16x16x32_bf16 v[70:73], v[156:159], v[224:227], v[70:73]
	v_mfma_f32_16x16x32_bf16 v[126:129], v[148:151], v[204:207], v[126:129]
	v_mfma_f32_16x16x32_bf16 v[118:121], v[180:183], v[204:207], v[118:121]
	v_mfma_f32_16x16x32_bf16 v[110:113], v[148:151], v[212:215], v[110:113]
	v_mfma_f32_16x16x32_bf16 v[102:105], v[180:183], v[212:215], v[102:105]
	v_mfma_f32_16x16x32_bf16 v[94:97], v[148:151], v[220:223], v[94:97]
	v_mfma_f32_16x16x32_bf16 v[86:89], v[180:183], v[220:223], v[86:89]
	v_mfma_f32_16x16x32_bf16 v[78:81], v[148:151], v[228:231], v[78:81]
	v_mfma_f32_16x16x32_bf16 v[70:73], v[180:183], v[228:231], v[70:73]
	v_mfma_f32_16x16x32_bf16 v[122:125], v[184:187], v[200:203], v[122:125]
	v_mfma_f32_16x16x32_bf16 v[114:117], v[192:195], v[200:203], v[114:117]
	v_mfma_f32_16x16x32_bf16 v[106:109], v[184:187], v[208:211], v[106:109]
	v_mfma_f32_16x16x32_bf16 v[98:101], v[192:195], v[208:211], v[98:101]
	v_mfma_f32_16x16x32_bf16 v[90:93], v[184:187], v[216:219], v[90:93]
	v_mfma_f32_16x16x32_bf16 v[82:85], v[192:195], v[216:219], v[82:85]
	v_mfma_f32_16x16x32_bf16 v[74:77], v[184:187], v[224:227], v[74:77]
	v_mfma_f32_16x16x32_bf16 v[66:69], v[192:195], v[224:227], v[66:69]
	v_mfma_f32_16x16x32_bf16 v[122:125], v[188:191], v[204:207], v[122:125]
	v_mfma_f32_16x16x32_bf16 v[114:117], v[196:199], v[204:207], v[114:117]
	v_mfma_f32_16x16x32_bf16 v[106:109], v[188:191], v[212:215], v[106:109]
	v_mfma_f32_16x16x32_bf16 v[98:101], v[196:199], v[212:215], v[98:101]
	v_mfma_f32_16x16x32_bf16 v[90:93], v[188:191], v[220:223], v[90:93]
	v_mfma_f32_16x16x32_bf16 v[82:85], v[196:199], v[220:223], v[82:85]
	v_mfma_f32_16x16x32_bf16 v[74:77], v[188:191], v[228:231], v[74:77]
	v_mfma_f32_16x16x32_bf16 v[66:69], v[196:199], v[228:231], v[66:69]
	s_barrier
; #define PG8_STAGE(bufoff, gbase, voff) do { _Pragma("unroll") for (int _i = 0; _i < 2; ++_i) \
;         __builtin_amdgcn_global_load_lds((const unsigned*)((const char*)(gbase) + (voff)[_i]), (LAS unsigned*)(lds + (bufoff) + ldsw + _i * 8192), 16, 0, 0); } while (0)
; #define PG8_LDA(dst, b, h) do { _Pragma("unroll") for (int m = 0; m < 4; ++m) _Pragma("unroll") for (int k = 0; k < 2; ++k) dst[m][k] = *(const LAS bf16x8*)(lds + PG8_SA(b, h) + aoff + m * 2048 + k * 1024); } while (0)
; #define PG8_MMA(ai, bj, At, Bt) do { __builtin_amdgcn_s_setprio(1); _Pragma("unroll") for (int m = 0; m < 4; ++m) _Pragma("unroll") for (int n = 0; n < 2; ++n) _Pragma("unroll") for (int k = 0; k < 2; ++k) \
;         acc[ai][bj][m][n] = __builtin_amdgcn_mfma_f32_16x16x32_bf16(Bt[n][k], At[m][k], acc[ai][bj][m][n], 0, 0, 0); __builtin_amdgcn_s_setprio(0); } while (0)
; #define PG8_WAIT_V(n) asm volatile("s_waitcnt vmcnt(" #n ")" ::: "memory")
; #define PG8_WAIT_L(n) asm volatile("s_waitcnt lgkmcnt(" #n ")" ::: "memory")
; #define PG8_BAR __builtin_amdgcn_s_barrier()
; #define PG8_SCHED __builtin_amdgcn_sched_barrier(0)
; template <class Epi, bool ALIGN_EPI>
; __device__ __forceinline__ void gemm_phase(LAS unsigned char* lds, const Gemm g, const StaticOrder& S, const Epi& E) {
;     ...
;             PG8_LDA(At, 1, 1); PG8_STAGE(PG8_SB(1, 0), b3, voffB); PG8_STAGE(PG8_SB(1, 1), b3 + hstepB, voffB); PG8_STAGE(PG8_SA(1, 0), a3, voffA);
;             PG8_WAIT_V(8); PG8_WAIT_L(0); PG8_BAR; PG8_MMA(1, 0, At, B0); PG8_MMA(1, 1, At, B1); PG8_BAR; PG8_SCHED;
	s_add_i32 s20, s39, s22
	v_lshl_add_u64 v[152:153], v[152:153], 0, s[94:95]
	s_mov_b32 m0, s20
	ds_read_b128 v[200:203], v146 offset:49152
	ds_read_b128 v[204:207], v146 offset:50176
	ds_read_b128 v[208:211], v146 offset:51200
	ds_read_b128 v[212:215], v146 offset:52224
	ds_read_b128 v[216:219], v146 offset:53248
	ds_read_b128 v[220:223], v146 offset:54272
	ds_read_b128 v[224:227], v146 offset:55296
	ds_read_b128 v[228:231], v146 offset:56320
	global_load_lds_dwordx4 v[152:153], off
	s_add_i32 m0, s20, 0x2000
	s_add_u32 s18, s18, 0x40080
	v_lshl_add_u64 v[152:153], v[160:161], 0, s[94:95]
	s_addc_u32 s19, s19, 0
	s_add_i32 s20, s40, s22
	global_load_lds_dwordx4 v[152:153], off
	v_lshl_add_u64 v[152:153], s[18:19], 0, v[0:1]
	s_mov_b32 m0, s20
	s_nop 0
	global_load_lds_dwordx4 v[152:153], off
	v_lshl_add_u64 v[152:153], s[18:19], 0, v[130:131]
	s_add_i32 m0, s20, 0x2000
	s_nop 0
	global_load_lds_dwordx4 v[152:153], off
	v_lshl_add_u64 v[152:153], v[162:163], 0, s[94:95]
	s_mov_b32 m0, s27
	s_nop 0
	global_load_lds_dwordx4 v[152:153], off
	v_lshl_add_u64 v[152:153], v[170:171], 0, s[94:95]
	s_mov_b32 m0, s28
	s_nop 0
	global_load_lds_dwordx4 v[152:153], off
	s_waitcnt vmcnt(8)
	s_waitcnt lgkmcnt(0)
	s_barrier
	s_waitcnt lgkmcnt(0)
	v_mfma_f32_16x16x32_bf16 v[62:65], v[140:143], v[200:203], v[62:65]
	v_mfma_f32_16x16x32_bf16 v[54:57], v[156:159], v[200:203], v[54:57]
	v_mfma_f32_16x16x32_bf16 v[46:49], v[140:143], v[208:211], v[46:49]
	v_mfma_f32_16x16x32_bf16 v[38:41], v[156:159], v[208:211], v[38:41]
	v_mfma_f32_16x16x32_bf16 v[30:33], v[140:143], v[216:219], v[30:33]
	v_mfma_f32_16x16x32_bf16 v[22:25], v[156:159], v[216:219], v[22:25]
	v_mfma_f32_16x16x32_bf16 v[14:17], v[140:143], v[224:227], v[14:17]
	v_mfma_f32_16x16x32_bf16 v[6:9], v[156:159], v[224:227], v[6:9]
	v_mfma_f32_16x16x32_bf16 v[62:65], v[148:151], v[204:207], v[62:65]
	v_mfma_f32_16x16x32_bf16 v[54:57], v[180:183], v[204:207], v[54:57]
	v_mfma_f32_16x16x32_bf16 v[46:49], v[148:151], v[212:215], v[46:49]
	v_mfma_f32_16x16x32_bf16 v[38:41], v[180:183], v[212:215], v[38:41]
	v_mfma_f32_16x16x32_bf16 v[30:33], v[148:151], v[220:223], v[30:33]
	v_mfma_f32_16x16x32_bf16 v[22:25], v[180:183], v[220:223], v[22:25]
	v_mfma_f32_16x16x32_bf16 v[14:17], v[148:151], v[228:231], v[14:17]
	v_mfma_f32_16x16x32_bf16 v[6:9], v[180:183], v[228:231], v[6:9]
	v_mfma_f32_16x16x32_bf16 v[58:61], v[184:187], v[200:203], v[58:61]
	v_mfma_f32_16x16x32_bf16 v[50:53], v[192:195], v[200:203], v[50:53]
	v_mfma_f32_16x16x32_bf16 v[42:45], v[184:187], v[208:211], v[42:45]
	v_mfma_f32_16x16x32_bf16 v[34:37], v[192:195], v[208:211], v[34:37]
	v_mfma_f32_16x16x32_bf16 v[26:29], v[184:187], v[216:219], v[26:29]
	v_mfma_f32_16x16x32_bf16 v[18:21], v[192:195], v[216:219], v[18:21]
	v_mfma_f32_16x16x32_bf16 v[10:13], v[184:187], v[224:227], v[10:13]
	v_mfma_f32_16x16x32_bf16 v[2:5], v[192:195], v[224:227], v[2:5]
	v_mfma_f32_16x16x32_bf16 v[58:61], v[188:191], v[204:207], v[58:61]
	v_mfma_f32_16x16x32_bf16 v[50:53], v[196:199], v[204:207], v[50:53]
	v_mfma_f32_16x16x32_bf16 v[42:45], v[188:191], v[212:215], v[42:45]
	v_mfma_f32_16x16x32_bf16 v[34:37], v[196:199], v[212:215], v[34:37]
	v_mfma_f32_16x16x32_bf16 v[26:29], v[188:191], v[220:223], v[26:29]
	v_mfma_f32_16x16x32_bf16 v[18:21], v[196:199], v[220:223], v[18:21]
	v_mfma_f32_16x16x32_bf16 v[10:13], v[188:191], v[228:231], v[10:13]
	v_mfma_f32_16x16x32_bf16 v[2:5], v[196:199], v[228:231], v[2:5]
	s_cmp_lg_u32 s38, 12
	s_cbranch_scc1 .Ltail_bar_1
	s_cmp_eq_u64 s[8:9], 0
	s_cbranch_scc1 .Ltail_skip_1

; #define PG8_BAR __builtin_amdgcn_s_barrier()
; template <class Epi, bool ALIGN_EPI>
; __device__ __forceinline__ void gemm_phase(LAS unsigned char* lds, const Gemm g, const StaticOrder& S, const Epi& E) {
;     ...
;         for (int t = 0; t < nt; t += 2) {
;     ...
;         if constexpr (ALIGN_EPI) { if (wr == 0) PG8_BAR; }
.Ltail_skip_1:
	s_add_i32 s38, s38, 2
	s_add_u32 s6, s6, 0x100
	s_addc_u32 s7, s7, 0
	s_add_u32 s36, s36, 0x100
	s_addc_u32 s37, s37, 0
	s_cmp_gt_u32 s38, 13
	s_cbranch_scc0 .LBB0_849
